# GEMM cores use v_mfma_f32_16x16x32_bf16 (accumulators swapped into the 32x32 layout before the epilogues)
# speedup vs baseline: 1.0160x; 1.0160x over previous
; DI int tidx() { int t = threadIdx.x; asm volatile("" : "+v"(t)); return t; }
; DI void gemm_wide(const bf16_t* __restrict__ W, int ldw, const bf16_t* __restrict__ X, int ldx, int nkt,
;                   f32x16 (&acc)[4][2], bf16_t* lds) {
;   const int tid = tidx(), lane = tid & 63, wv = tid >> 6, wn = wv & 1, wm = wv >> 1;
;   const int lr = lane & 31, lh = lane >> 5;
;   const int lrow = tid >> 3, lkc = (tid & 7) * 8;
;   const bf16_t* wp = W + (size_t)lrow * ldw + lkc;
;   const bf16_t* xp = X + (size_t)lrow * ldx + lkc;
;   const size_t wst = (size_t)64 * ldw, xst = (size_t)64 * ldx;
;   u32x4 rw0, rw1, rw2, rw3, rx0, rx1, rx2, rx3;
;     ...
;   u32x4 sw0, sw1, sw2, sw3, sx0, sx1, sx2, sx3;
;     ...
;   __syncthreads();
;   GW_GLOAD(0)
;   GW_LSTORE(0)
;   GW_GLOAD(1)
;   GW_GLOAD_B(nkt > 2 ? 2 : nkt - 1)
;   __syncthreads();
.LBB0_267:
	s_mul_i32 s0, s9, 0x88000
	s_mul_hi_i32 s1, s9, 0x88000
	s_add_u32 s0, s4, s0
	s_addc_u32 s1, s5, s1
	s_mul_i32 s28, s8, 0x88000
	s_mul_hi_i32 s29, s8, 0x88000
	s_add_u32 s28, s14, s28
	s_addc_u32 s29, s15, s29
	v_and_b32_e32 v128, 63, v195
	v_lshrrev_b32_e32 v129, 6, v195
	v_and_b32_e32 v130, 15, v128
	v_lshrrev_b32_e32 v131, 4, v128
	v_bfe_u32 v132, v130, 1, 3
	v_lshlrev_b32_e32 v133, 7, v130
	v_xor_b32_e32 v134, v131, v132
	v_lshl_add_u32 v135, v134, 4, v133
	v_and_b32_e32 v136, 1, v129
	v_lshlrev_b32_e32 v136, 14, v136
	v_lshrrev_b32_e32 v137, 1, v129
	v_lshlrev_b32_e32 v137, 13, v137
	v_add_u32_e32 v137, 0x10000, v137
	v_readfirstlane_b32 s98, v129
	v_add_u32_e32 v204, v136, v135
	v_xor_b32_e32 v205, 64, v204
	v_add_u32_e32 v206, v137, v135
	v_xor_b32_e32 v207, 64, v206
	s_lshl_b32 s98, s98, 12
	s_movk_i32 s100, 2176
	v_lshrrev_b32_e32 v138, 3, v128
	v_lshl_add_u32 v138, v129, 5, v138
	v_mul_lo_u32 v139, v138, s100
	v_and_b32_e32 v140, 7, v128
	v_lshrrev_b32_e32 v141, 4, v128
	v_xor_b32_e32 v142, v140, v141
	v_xor_b32_e32 v143, 4, v142
	v_lshl_add_u32 v208, v142, 4, v139
	v_lshl_add_u32 v209, v143, 4, v139
	v_add_u32_e32 v209, 0x4400, v209
	v_add_u32_e32 v210, 0x8800, v208
	v_add_u32_e32 v211, 0x8800, v209
	s_barrier
	s_mov_b32 m0, s98
	s_nop 0
	global_load_lds_dwordx4 v208, s[0:1]
	s_add_u32 m0, s98, 0x400
	s_nop 0
	global_load_lds_dwordx4 v209, s[0:1]
	s_add_u32 m0, s98, 0x800
	s_nop 0
	global_load_lds_dwordx4 v210, s[0:1]
	s_add_u32 m0, s98, 0xc00
	s_nop 0
	global_load_lds_dwordx4 v211, s[0:1]
	s_add_u32 s0, s0, 0x80
	s_addc_u32 s1, s1, 0
	s_add_u32 m0, s98, 0x10000
	s_nop 0
	global_load_lds_dwordx4 v208, s[28:29]
	s_add_u32 m0, s98, 0x10400
	s_nop 0
	global_load_lds_dwordx4 v209, s[28:29]
	s_add_u32 m0, s98, 0x10800
	s_nop 0
	global_load_lds_dwordx4 v210, s[28:29]
	s_add_u32 m0, s98, 0x10c00
	s_nop 0
	global_load_lds_dwordx4 v211, s[28:29]
	s_add_u32 s28, s28, 0x80
	s_addc_u32 s29, s29, 0
	s_add_u32 m0, s98, 0x8000
	s_nop 0
	global_load_lds_dwordx4 v208, s[0:1]
	s_add_u32 m0, s98, 0x8400
	s_nop 0
	global_load_lds_dwordx4 v209, s[0:1]
	s_add_u32 m0, s98, 0x8800
	s_nop 0
	global_load_lds_dwordx4 v210, s[0:1]
	s_add_u32 m0, s98, 0x8c00
	s_nop 0
	global_load_lds_dwordx4 v211, s[0:1]
	s_add_u32 s0, s0, 0x80
	s_addc_u32 s1, s1, 0
	v_mov_b64_e32 v[112:113], 0
	v_mov_b64_e32 v[114:115], 0
	v_mov_b64_e32 v[116:117], 0
	v_mov_b64_e32 v[118:119], 0
	v_mov_b64_e32 v[120:121], 0
	v_mov_b64_e32 v[122:123], 0
	v_mov_b64_e32 v[124:125], 0
	v_mov_b64_e32 v[126:127], 0
	v_mov_b64_e32 v[80:81], 0
	v_mov_b64_e32 v[82:83], 0
	v_mov_b64_e32 v[84:85], 0
	v_mov_b64_e32 v[86:87], 0
	v_mov_b64_e32 v[88:89], 0
	v_mov_b64_e32 v[90:91], 0
	v_mov_b64_e32 v[92:93], 0
	v_mov_b64_e32 v[94:95], 0
	v_mov_b64_e32 v[96:97], 0
	v_mov_b64_e32 v[98:99], 0
	v_mov_b64_e32 v[100:101], 0
	v_mov_b64_e32 v[102:103], 0
	v_mov_b64_e32 v[104:105], 0
	v_mov_b64_e32 v[106:107], 0
	v_mov_b64_e32 v[108:109], 0
	v_mov_b64_e32 v[110:111], 0
	v_mov_b64_e32 v[64:65], 0
	v_mov_b64_e32 v[66:67], 0
	v_mov_b64_e32 v[68:69], 0
	v_mov_b64_e32 v[70:71], 0
	v_mov_b64_e32 v[72:73], 0
	v_mov_b64_e32 v[74:75], 0
	v_mov_b64_e32 v[76:77], 0
	v_mov_b64_e32 v[78:79], 0
	v_mov_b64_e32 v[48:49], 0
	v_mov_b64_e32 v[50:51], 0
	v_mov_b64_e32 v[52:53], 0
	v_mov_b64_e32 v[54:55], 0
	v_mov_b64_e32 v[56:57], 0
	v_mov_b64_e32 v[58:59], 0
	v_mov_b64_e32 v[60:61], 0
	v_mov_b64_e32 v[62:63], 0
	v_mov_b64_e32 v[16:17], 0
	v_mov_b64_e32 v[18:19], 0
	v_mov_b64_e32 v[20:21], 0
	v_mov_b64_e32 v[22:23], 0
	v_mov_b64_e32 v[24:25], 0
	v_mov_b64_e32 v[26:27], 0
	v_mov_b64_e32 v[28:29], 0
	v_mov_b64_e32 v[30:31], 0
	v_mov_b64_e32 v[32:33], 0
	v_mov_b64_e32 v[34:35], 0
	v_mov_b64_e32 v[36:37], 0
	v_mov_b64_e32 v[38:39], 0
	v_mov_b64_e32 v[40:41], 0
	v_mov_b64_e32 v[42:43], 0
	v_mov_b64_e32 v[44:45], 0
	v_mov_b64_e32 v[46:47], 0
	v_mov_b64_e32 v[0:1], 0
	v_mov_b64_e32 v[2:3], 0
	v_mov_b64_e32 v[4:5], 0
	v_mov_b64_e32 v[6:7], 0
	v_mov_b64_e32 v[8:9], 0
	v_mov_b64_e32 v[10:11], 0
	v_mov_b64_e32 v[12:13], 0
	v_mov_b64_e32 v[14:15], 0
	s_waitcnt vmcnt(4)
	s_barrier
	ds_read_b128 v[160:163], v204 offset:0
	ds_read_b128 v[128:131], v206 offset:0
	ds_read_b128 v[164:167], v204 offset:2048
	ds_read_b128 v[132:135], v206 offset:2048
	ds_read_b128 v[168:171], v204 offset:4096
	ds_read_b128 v[136:139], v206 offset:4096
	ds_read_b128 v[172:175], v204 offset:6144
	ds_read_b128 v[140:143], v206 offset:6144
	s_movk_i32 s99, 7
; DI void gemm_wide(const bf16_t* __restrict__ W, int ldw, const bf16_t* __restrict__ X, int ldx, int nkt,
;                   f32x16 (&acc)[4][2], bf16_t* lds) {
;     ...
;   for (int kt = 0; kt < nkt; kt += 2) {
;     __builtin_amdgcn_sched_barrier(0);
;     GW_ST2(1, 0, rw0, rw1)                         GW_KS(kt, 0)
;     GW_ST2(1, 128 * LDT, rw2, rw3)                 GW_KS(kt, 1)
;     GW_ST2(1, WT_E, rx0, rx1)                      GW_KS(kt, 2)
;     GW_ST2(1, WT_E + 128 * LDT, rx2, rx3)          GW_KS(kt, 3)
;     __builtin_amdgcn_sched_barrier(0);
;     GW_GLOAD(kt + 3 < nkt ? kt + 3 : nkt - 1)
;     __syncthreads();
;     __builtin_amdgcn_sched_barrier(0);
;     GW_ST2(0, 0, sw0, sw1)                         GW_KS(kt + 1, 0)
;     GW_ST2(0, 128 * LDT, sw2, sw3)                 GW_KS(kt + 1, 1)
;     GW_ST2(0, WT_E, sx0, sx1)                      GW_KS(kt + 1, 2)
;     GW_ST2(0, WT_E + 128 * LDT, sx2, sx3)          GW_KS(kt + 1, 3)
;     __builtin_amdgcn_sched_barrier(0);
;     GW_GLOAD_B(kt + 4 < nkt ? kt + 4 : nkt - 1)
;     __syncthreads();
;   }
.Lgw_inproj_loop:
	ds_read_b128 v[176:179], v204 offset:8192
	s_waitcnt lgkmcnt(7)
	v_mfma_f32_16x16x32_bf16 v[112:115], v[160:163], v[128:131], v[112:115]
	s_add_u32 m0, s98, 0x18000
	s_waitcnt lgkmcnt(5)
	v_mfma_f32_16x16x32_bf16 v[116:119], v[160:163], v[132:135], v[116:119]
	s_waitcnt lgkmcnt(3)
	v_mfma_f32_16x16x32_bf16 v[80:83], v[160:163], v[136:139], v[80:83]
	global_load_lds_dwordx4 v208, s[28:29]
	s_waitcnt lgkmcnt(1)
	v_mfma_f32_16x16x32_bf16 v[84:87], v[160:163], v[140:143], v[84:87]
	ds_read_b128 v[180:183], v204 offset:10240
	v_mfma_f32_16x16x32_bf16 v[120:123], v[164:167], v[128:131], v[120:123]
	s_add_u32 m0, s98, 0x18400
	v_mfma_f32_16x16x32_bf16 v[124:127], v[164:167], v[132:135], v[124:127]
	v_mfma_f32_16x16x32_bf16 v[88:91], v[164:167], v[136:139], v[88:91]
	global_load_lds_dwordx4 v209, s[28:29]
	v_mfma_f32_16x16x32_bf16 v[92:95], v[164:167], v[140:143], v[92:95]
	ds_read_b128 v[184:187], v204 offset:12288
	v_mfma_f32_16x16x32_bf16 v[96:99], v[168:171], v[128:131], v[96:99]
	s_add_u32 m0, s98, 0x18800
	v_mfma_f32_16x16x32_bf16 v[100:103], v[168:171], v[132:135], v[100:103]
	v_mfma_f32_16x16x32_bf16 v[64:67], v[168:171], v[136:139], v[64:67]
	global_load_lds_dwordx4 v210, s[28:29]
	v_mfma_f32_16x16x32_bf16 v[68:71], v[168:171], v[140:143], v[68:71]
	ds_read_b128 v[188:191], v204 offset:14336
	v_mfma_f32_16x16x32_bf16 v[104:107], v[172:175], v[128:131], v[104:107]
	s_add_u32 m0, s98, 0x18c00
	v_mfma_f32_16x16x32_bf16 v[108:111], v[172:175], v[132:135], v[108:111]
	v_mfma_f32_16x16x32_bf16 v[72:75], v[172:175], v[136:139], v[72:75]
	global_load_lds_dwordx4 v211, s[28:29]
	v_mfma_f32_16x16x32_bf16 v[76:79], v[172:175], v[140:143], v[76:79]
	s_add_u32 s28, s28, 0x80
	s_addc_u32 s29, s29, 0
	s_waitcnt lgkmcnt(3)
	v_mfma_f32_16x16x32_bf16 v[48:51], v[176:179], v[128:131], v[48:51]
	v_mfma_f32_16x16x32_bf16 v[52:55], v[176:179], v[132:135], v[52:55]
	ds_read_b128 v[160:163], v205 offset:0
	v_mfma_f32_16x16x32_bf16 v[16:19], v[176:179], v[136:139], v[16:19]
	v_mfma_f32_16x16x32_bf16 v[20:23], v[176:179], v[140:143], v[20:23]
	ds_read_b128 v[144:147], v207 offset:0
	s_waitcnt lgkmcnt(4)
	v_mfma_f32_16x16x32_bf16 v[56:59], v[180:183], v[128:131], v[56:59]
	v_mfma_f32_16x16x32_bf16 v[60:63], v[180:183], v[132:135], v[60:63]
	ds_read_b128 v[164:167], v205 offset:2048
	v_mfma_f32_16x16x32_bf16 v[24:27], v[180:183], v[136:139], v[24:27]
	v_mfma_f32_16x16x32_bf16 v[28:31], v[180:183], v[140:143], v[28:31]
	ds_read_b128 v[148:151], v207 offset:2048
	s_waitcnt lgkmcnt(5)
	v_mfma_f32_16x16x32_bf16 v[32:35], v[184:187], v[128:131], v[32:35]
	v_mfma_f32_16x16x32_bf16 v[36:39], v[184:187], v[132:135], v[36:39]
	ds_read_b128 v[168:171], v205 offset:4096
	v_mfma_f32_16x16x32_bf16 v[0:3], v[184:187], v[136:139], v[0:3]
	v_mfma_f32_16x16x32_bf16 v[4:7], v[184:187], v[140:143], v[4:7]
	ds_read_b128 v[152:155], v207 offset:4096
	s_waitcnt lgkmcnt(6)
	v_mfma_f32_16x16x32_bf16 v[40:43], v[188:191], v[128:131], v[40:43]
	v_mfma_f32_16x16x32_bf16 v[44:47], v[188:191], v[132:135], v[44:47]
	ds_read_b128 v[172:175], v205 offset:6144
	v_mfma_f32_16x16x32_bf16 v[8:11], v[188:191], v[136:139], v[8:11]
	v_mfma_f32_16x16x32_bf16 v[12:15], v[188:191], v[140:143], v[12:15]
	ds_read_b128 v[156:159], v207 offset:6144
	ds_read_b128 v[176:179], v205 offset:8192
	ds_read_b128 v[180:183], v205 offset:10240
	ds_read_b128 v[184:187], v205 offset:12288
	ds_read_b128 v[188:191], v205 offset:14336
	s_waitcnt lgkmcnt(10)
	v_mfma_f32_16x16x32_bf16 v[112:115], v[160:163], v[144:147], v[112:115]
	s_waitcnt lgkmcnt(8)
	v_mfma_f32_16x16x32_bf16 v[116:119], v[160:163], v[148:151], v[116:119]
	s_waitcnt lgkmcnt(6)
	v_mfma_f32_16x16x32_bf16 v[80:83], v[160:163], v[152:155], v[80:83]
	s_waitcnt lgkmcnt(4)
	v_mfma_f32_16x16x32_bf16 v[84:87], v[160:163], v[156:159], v[84:87]
	v_mfma_f32_16x16x32_bf16 v[120:123], v[164:167], v[144:147], v[120:123]
	v_mfma_f32_16x16x32_bf16 v[124:127], v[164:167], v[148:151], v[124:127]
	v_mfma_f32_16x16x32_bf16 v[88:91], v[164:167], v[152:155], v[88:91]
	v_mfma_f32_16x16x32_bf16 v[92:95], v[164:167], v[156:159], v[92:95]
	v_mfma_f32_16x16x32_bf16 v[96:99], v[168:171], v[144:147], v[96:99]
	v_mfma_f32_16x16x32_bf16 v[100:103], v[168:171], v[148:151], v[100:103]
	v_mfma_f32_16x16x32_bf16 v[64:67], v[168:171], v[152:155], v[64:67]
	v_mfma_f32_16x16x32_bf16 v[68:71], v[168:171], v[156:159], v[68:71]
	v_mfma_f32_16x16x32_bf16 v[104:107], v[172:175], v[144:147], v[104:107]
	v_mfma_f32_16x16x32_bf16 v[108:111], v[172:175], v[148:151], v[108:111]
	v_mfma_f32_16x16x32_bf16 v[72:75], v[172:175], v[152:155], v[72:75]
	v_mfma_f32_16x16x32_bf16 v[76:79], v[172:175], v[156:159], v[76:79]
	s_waitcnt vmcnt(0) lgkmcnt(0)
	s_barrier
; DI void gemm_wide(const bf16_t* __restrict__ W, int ldw, const bf16_t* __restrict__ X, int ldx, int nkt,
;                   f32x16 (&acc)[4][2], bf16_t* lds) {
;     ...
;   for (int kt = 0; kt < nkt; kt += 2) {
;     __builtin_amdgcn_sched_barrier(0);
;     GW_ST2(1, 0, rw0, rw1)                         GW_KS(kt, 0)
;     GW_ST2(1, 128 * LDT, rw2, rw3)                 GW_KS(kt, 1)
;     GW_ST2(1, WT_E, rx0, rx1)                      GW_KS(kt, 2)
;     GW_ST2(1, WT_E + 128 * LDT, rx2, rx3)          GW_KS(kt, 3)
;     __builtin_amdgcn_sched_barrier(0);
;     GW_GLOAD(kt + 3 < nkt ? kt + 3 : nkt - 1)
;     __syncthreads();
;     __builtin_amdgcn_sched_barrier(0);
;     GW_ST2(0, 0, sw0, sw1)                         GW_KS(kt + 1, 0)
;     GW_ST2(0, 128 * LDT, sw2, sw3)                 GW_KS(kt + 1, 1)
;     GW_ST2(0, WT_E, sx0, sx1)                      GW_KS(kt + 1, 2)
;     GW_ST2(0, WT_E + 128 * LDT, sx2, sx3)          GW_KS(kt + 1, 3)
;     __builtin_amdgcn_sched_barrier(0);
;     GW_GLOAD_B(kt + 4 < nkt ? kt + 4 : nkt - 1)
;     __syncthreads();
;   }
	v_mfma_f32_16x16x32_bf16 v[48:51], v[176:179], v[144:147], v[48:51]
	s_mov_b32 m0, s98
	v_mfma_f32_16x16x32_bf16 v[52:55], v[176:179], v[148:151], v[52:55]
	ds_read_b128 v[160:163], v204 offset:32768
	v_mfma_f32_16x16x32_bf16 v[16:19], v[176:179], v[152:155], v[16:19]
	global_load_lds_dwordx4 v208, s[0:1]
	v_mfma_f32_16x16x32_bf16 v[20:23], v[176:179], v[156:159], v[20:23]
	ds_read_b128 v[128:131], v206 offset:32768
	v_mfma_f32_16x16x32_bf16 v[56:59], v[180:183], v[144:147], v[56:59]
	s_add_u32 m0, s98, 0x400
	v_mfma_f32_16x16x32_bf16 v[60:63], v[180:183], v[148:151], v[60:63]
	ds_read_b128 v[164:167], v204 offset:34816
	v_mfma_f32_16x16x32_bf16 v[24:27], v[180:183], v[152:155], v[24:27]
	global_load_lds_dwordx4 v209, s[0:1]
	v_mfma_f32_16x16x32_bf16 v[28:31], v[180:183], v[156:159], v[28:31]
	ds_read_b128 v[132:135], v206 offset:34816
	v_mfma_f32_16x16x32_bf16 v[32:35], v[184:187], v[144:147], v[32:35]
	s_add_u32 m0, s98, 0x800
	v_mfma_f32_16x16x32_bf16 v[36:39], v[184:187], v[148:151], v[36:39]
	ds_read_b128 v[168:171], v204 offset:36864
	v_mfma_f32_16x16x32_bf16 v[0:3], v[184:187], v[152:155], v[0:3]
	global_load_lds_dwordx4 v210, s[0:1]
	v_mfma_f32_16x16x32_bf16 v[4:7], v[184:187], v[156:159], v[4:7]
	ds_read_b128 v[136:139], v206 offset:36864
	v_mfma_f32_16x16x32_bf16 v[40:43], v[188:191], v[144:147], v[40:43]
	s_add_u32 m0, s98, 0xc00
	v_mfma_f32_16x16x32_bf16 v[44:47], v[188:191], v[148:151], v[44:47]
	ds_read_b128 v[172:175], v204 offset:38912
	v_mfma_f32_16x16x32_bf16 v[8:11], v[188:191], v[152:155], v[8:11]
	global_load_lds_dwordx4 v211, s[0:1]
	v_mfma_f32_16x16x32_bf16 v[12:15], v[188:191], v[156:159], v[12:15]
	ds_read_b128 v[140:143], v206 offset:38912
	s_add_u32 s0, s0, 0x80
	s_addc_u32 s1, s1, 0
	ds_read_b128 v[176:179], v204 offset:40960
	s_waitcnt lgkmcnt(7)
	v_mfma_f32_16x16x32_bf16 v[112:115], v[160:163], v[128:131], v[112:115]
	s_add_u32 m0, s98, 0x10000
	s_waitcnt lgkmcnt(5)
	v_mfma_f32_16x16x32_bf16 v[116:119], v[160:163], v[132:135], v[116:119]
	s_waitcnt lgkmcnt(3)
	v_mfma_f32_16x16x32_bf16 v[80:83], v[160:163], v[136:139], v[80:83]
	global_load_lds_dwordx4 v208, s[28:29]
	s_waitcnt lgkmcnt(1)
	v_mfma_f32_16x16x32_bf16 v[84:87], v[160:163], v[140:143], v[84:87]
	ds_read_b128 v[180:183], v204 offset:43008
	v_mfma_f32_16x16x32_bf16 v[120:123], v[164:167], v[128:131], v[120:123]
	s_add_u32 m0, s98, 0x10400
	v_mfma_f32_16x16x32_bf16 v[124:127], v[164:167], v[132:135], v[124:127]
	v_mfma_f32_16x16x32_bf16 v[88:91], v[164:167], v[136:139], v[88:91]
	global_load_lds_dwordx4 v209, s[28:29]
	v_mfma_f32_16x16x32_bf16 v[92:95], v[164:167], v[140:143], v[92:95]
	ds_read_b128 v[184:187], v204 offset:45056
	v_mfma_f32_16x16x32_bf16 v[96:99], v[168:171], v[128:131], v[96:99]
	s_add_u32 m0, s98, 0x10800
	v_mfma_f32_16x16x32_bf16 v[100:103], v[168:171], v[132:135], v[100:103]
	v_mfma_f32_16x16x32_bf16 v[64:67], v[168:171], v[136:139], v[64:67]
	global_load_lds_dwordx4 v210, s[28:29]
	v_mfma_f32_16x16x32_bf16 v[68:71], v[168:171], v[140:143], v[68:71]
	ds_read_b128 v[188:191], v204 offset:47104
	v_mfma_f32_16x16x32_bf16 v[104:107], v[172:175], v[128:131], v[104:107]
	s_add_u32 m0, s98, 0x10c00
	v_mfma_f32_16x16x32_bf16 v[108:111], v[172:175], v[132:135], v[108:111]
	v_mfma_f32_16x16x32_bf16 v[72:75], v[172:175], v[136:139], v[72:75]
	global_load_lds_dwordx4 v211, s[28:29]
	v_mfma_f32_16x16x32_bf16 v[76:79], v[172:175], v[140:143], v[76:79]
	s_add_u32 s28, s28, 0x80
	s_addc_u32 s29, s29, 0
	s_waitcnt lgkmcnt(3)
	v_mfma_f32_16x16x32_bf16 v[48:51], v[176:179], v[128:131], v[48:51]
	v_mfma_f32_16x16x32_bf16 v[52:55], v[176:179], v[132:135], v[52:55]
	ds_read_b128 v[160:163], v205 offset:32768
	v_mfma_f32_16x16x32_bf16 v[16:19], v[176:179], v[136:139], v[16:19]
	v_mfma_f32_16x16x32_bf16 v[20:23], v[176:179], v[140:143], v[20:23]
	ds_read_b128 v[144:147], v207 offset:32768
	s_waitcnt lgkmcnt(4)
	v_mfma_f32_16x16x32_bf16 v[56:59], v[180:183], v[128:131], v[56:59]
	v_mfma_f32_16x16x32_bf16 v[60:63], v[180:183], v[132:135], v[60:63]
	ds_read_b128 v[164:167], v205 offset:34816
	v_mfma_f32_16x16x32_bf16 v[24:27], v[180:183], v[136:139], v[24:27]
	v_mfma_f32_16x16x32_bf16 v[28:31], v[180:183], v[140:143], v[28:31]
	ds_read_b128 v[148:151], v207 offset:34816
	s_waitcnt lgkmcnt(5)
	v_mfma_f32_16x16x32_bf16 v[32:35], v[184:187], v[128:131], v[32:35]
	v_mfma_f32_16x16x32_bf16 v[36:39], v[184:187], v[132:135], v[36:39]
	ds_read_b128 v[168:171], v205 offset:36864
	v_mfma_f32_16x16x32_bf16 v[0:3], v[184:187], v[136:139], v[0:3]
	v_mfma_f32_16x16x32_bf16 v[4:7], v[184:187], v[140:143], v[4:7]
	ds_read_b128 v[152:155], v207 offset:36864
	s_waitcnt lgkmcnt(6)
	v_mfma_f32_16x16x32_bf16 v[40:43], v[188:191], v[128:131], v[40:43]
	v_mfma_f32_16x16x32_bf16 v[44:47], v[188:191], v[132:135], v[44:47]
	ds_read_b128 v[172:175], v205 offset:38912
	v_mfma_f32_16x16x32_bf16 v[8:11], v[188:191], v[136:139], v[8:11]
	v_mfma_f32_16x16x32_bf16 v[12:15], v[188:191], v[140:143], v[12:15]
	ds_read_b128 v[156:159], v207 offset:38912
	ds_read_b128 v[176:179], v205 offset:40960
	ds_read_b128 v[180:183], v205 offset:43008
	ds_read_b128 v[184:187], v205 offset:45056
	ds_read_b128 v[188:191], v205 offset:47104
	s_waitcnt lgkmcnt(10)
	v_mfma_f32_16x16x32_bf16 v[112:115], v[160:163], v[144:147], v[112:115]
	s_waitcnt lgkmcnt(8)
	v_mfma_f32_16x16x32_bf16 v[116:119], v[160:163], v[148:151], v[116:119]
	s_waitcnt lgkmcnt(6)
	v_mfma_f32_16x16x32_bf16 v[80:83], v[160:163], v[152:155], v[80:83]
	s_waitcnt lgkmcnt(4)
	v_mfma_f32_16x16x32_bf16 v[84:87], v[160:163], v[156:159], v[84:87]
	v_mfma_f32_16x16x32_bf16 v[120:123], v[164:167], v[144:147], v[120:123]
	v_mfma_f32_16x16x32_bf16 v[124:127], v[164:167], v[148:151], v[124:127]
	v_mfma_f32_16x16x32_bf16 v[88:91], v[164:167], v[152:155], v[88:91]
	v_mfma_f32_16x16x32_bf16 v[92:95], v[164:167], v[156:159], v[92:95]
	v_mfma_f32_16x16x32_bf16 v[96:99], v[168:171], v[144:147], v[96:99]
	v_mfma_f32_16x16x32_bf16 v[100:103], v[168:171], v[148:151], v[100:103]
	v_mfma_f32_16x16x32_bf16 v[64:67], v[168:171], v[152:155], v[64:67]
	v_mfma_f32_16x16x32_bf16 v[68:71], v[168:171], v[156:159], v[68:71]
	v_mfma_f32_16x16x32_bf16 v[104:107], v[172:175], v[144:147], v[104:107]
	v_mfma_f32_16x16x32_bf16 v[108:111], v[172:175], v[148:151], v[108:111]
	v_mfma_f32_16x16x32_bf16 v[72:75], v[172:175], v[152:155], v[72:75]
	v_mfma_f32_16x16x32_bf16 v[76:79], v[172:175], v[156:159], v[76:79]
	s_waitcnt vmcnt(0) lgkmcnt(0)
	s_barrier
; DI void gemm_wide(const bf16_t* __restrict__ W, int ldw, const bf16_t* __restrict__ X, int ldx, int nkt,
;                   f32x16 (&acc)[4][2], bf16_t* lds) {
;     ...
;   for (int kt = 0; kt < nkt; kt += 2) {
;     __builtin_amdgcn_sched_barrier(0);
;     GW_ST2(1, 0, rw0, rw1)                         GW_KS(kt, 0)
;     GW_ST2(1, 128 * LDT, rw2, rw3)                 GW_KS(kt, 1)
;     GW_ST2(1, WT_E, rx0, rx1)                      GW_KS(kt, 2)
;     GW_ST2(1, WT_E + 128 * LDT, rx2, rx3)          GW_KS(kt, 3)
;     __builtin_amdgcn_sched_barrier(0);
;     GW_GLOAD(kt + 3 < nkt ? kt + 3 : nkt - 1)
;     __syncthreads();
;     __builtin_amdgcn_sched_barrier(0);
;     GW_ST2(0, 0, sw0, sw1)                         GW_KS(kt + 1, 0)
;     GW_ST2(0, 128 * LDT, sw2, sw3)                 GW_KS(kt + 1, 1)
;     GW_ST2(0, WT_E, sx0, sx1)                      GW_KS(kt + 1, 2)
;     GW_ST2(0, WT_E + 128 * LDT, sx2, sx3)          GW_KS(kt + 1, 3)
;     __builtin_amdgcn_sched_barrier(0);
;     GW_GLOAD_B(kt + 4 < nkt ? kt + 4 : nkt - 1)
;     __syncthreads();
;   }
	v_mfma_f32_16x16x32_bf16 v[48:51], v[176:179], v[144:147], v[48:51]
	s_add_u32 m0, s98, 0x8000
	v_mfma_f32_16x16x32_bf16 v[52:55], v[176:179], v[148:151], v[52:55]
	ds_read_b128 v[160:163], v204 offset:0
	v_mfma_f32_16x16x32_bf16 v[16:19], v[176:179], v[152:155], v[16:19]
	global_load_lds_dwordx4 v208, s[0:1]
	v_mfma_f32_16x16x32_bf16 v[20:23], v[176:179], v[156:159], v[20:23]
	ds_read_b128 v[128:131], v206 offset:0
	v_mfma_f32_16x16x32_bf16 v[56:59], v[180:183], v[144:147], v[56:59]
	s_add_u32 m0, s98, 0x8400
	v_mfma_f32_16x16x32_bf16 v[60:63], v[180:183], v[148:151], v[60:63]
	ds_read_b128 v[164:167], v204 offset:2048
	v_mfma_f32_16x16x32_bf16 v[24:27], v[180:183], v[152:155], v[24:27]
	global_load_lds_dwordx4 v209, s[0:1]
	v_mfma_f32_16x16x32_bf16 v[28:31], v[180:183], v[156:159], v[28:31]
	ds_read_b128 v[132:135], v206 offset:2048
	v_mfma_f32_16x16x32_bf16 v[32:35], v[184:187], v[144:147], v[32:35]
	s_add_u32 m0, s98, 0x8800
	v_mfma_f32_16x16x32_bf16 v[36:39], v[184:187], v[148:151], v[36:39]
	ds_read_b128 v[168:171], v204 offset:4096
	v_mfma_f32_16x16x32_bf16 v[0:3], v[184:187], v[152:155], v[0:3]
	global_load_lds_dwordx4 v210, s[0:1]
	v_mfma_f32_16x16x32_bf16 v[4:7], v[184:187], v[156:159], v[4:7]
	ds_read_b128 v[136:139], v206 offset:4096
	v_mfma_f32_16x16x32_bf16 v[40:43], v[188:191], v[144:147], v[40:43]
	s_add_u32 m0, s98, 0x8c00
	v_mfma_f32_16x16x32_bf16 v[44:47], v[188:191], v[148:151], v[44:47]
	ds_read_b128 v[172:175], v204 offset:6144
	v_mfma_f32_16x16x32_bf16 v[8:11], v[188:191], v[152:155], v[8:11]
	global_load_lds_dwordx4 v211, s[0:1]
	v_mfma_f32_16x16x32_bf16 v[12:15], v[188:191], v[156:159], v[12:15]
	ds_read_b128 v[140:143], v206 offset:6144
	s_add_u32 s0, s0, 0x80
	s_addc_u32 s1, s1, 0
	s_sub_u32 s99, s99, 1
	s_cmp_lg_u32 s99, 0
	s_cbranch_scc1 .Lgw_inproj_loop
	ds_read_b128 v[176:179], v204 offset:8192
	s_waitcnt lgkmcnt(7)
	v_mfma_f32_16x16x32_bf16 v[112:115], v[160:163], v[128:131], v[112:115]
	s_add_u32 m0, s98, 0x18000
	s_waitcnt lgkmcnt(5)
	v_mfma_f32_16x16x32_bf16 v[116:119], v[160:163], v[132:135], v[116:119]
	s_waitcnt lgkmcnt(3)
	v_mfma_f32_16x16x32_bf16 v[80:83], v[160:163], v[136:139], v[80:83]
	global_load_lds_dwordx4 v208, s[28:29]
	s_waitcnt lgkmcnt(1)
	v_mfma_f32_16x16x32_bf16 v[84:87], v[160:163], v[140:143], v[84:87]
	ds_read_b128 v[180:183], v204 offset:10240
	v_mfma_f32_16x16x32_bf16 v[120:123], v[164:167], v[128:131], v[120:123]
	s_add_u32 m0, s98, 0x18400
	v_mfma_f32_16x16x32_bf16 v[124:127], v[164:167], v[132:135], v[124:127]
	v_mfma_f32_16x16x32_bf16 v[88:91], v[164:167], v[136:139], v[88:91]
	global_load_lds_dwordx4 v209, s[28:29]
	v_mfma_f32_16x16x32_bf16 v[92:95], v[164:167], v[140:143], v[92:95]
	ds_read_b128 v[184:187], v204 offset:12288
	v_mfma_f32_16x16x32_bf16 v[96:99], v[168:171], v[128:131], v[96:99]
	s_add_u32 m0, s98, 0x18800
	v_mfma_f32_16x16x32_bf16 v[100:103], v[168:171], v[132:135], v[100:103]
	v_mfma_f32_16x16x32_bf16 v[64:67], v[168:171], v[136:139], v[64:67]
	global_load_lds_dwordx4 v210, s[28:29]
	v_mfma_f32_16x16x32_bf16 v[68:71], v[168:171], v[140:143], v[68:71]
	ds_read_b128 v[188:191], v204 offset:14336
	v_mfma_f32_16x16x32_bf16 v[104:107], v[172:175], v[128:131], v[104:107]
	s_add_u32 m0, s98, 0x18c00
	v_mfma_f32_16x16x32_bf16 v[108:111], v[172:175], v[132:135], v[108:111]
	v_mfma_f32_16x16x32_bf16 v[72:75], v[172:175], v[136:139], v[72:75]
	global_load_lds_dwordx4 v211, s[28:29]
	v_mfma_f32_16x16x32_bf16 v[76:79], v[172:175], v[140:143], v[76:79]
	s_add_u32 s28, s28, 0x80
	s_addc_u32 s29, s29, 0
	s_waitcnt lgkmcnt(3)
	v_mfma_f32_16x16x32_bf16 v[48:51], v[176:179], v[128:131], v[48:51]
	v_mfma_f32_16x16x32_bf16 v[52:55], v[176:179], v[132:135], v[52:55]
	ds_read_b128 v[160:163], v205 offset:0
	v_mfma_f32_16x16x32_bf16 v[16:19], v[176:179], v[136:139], v[16:19]
	v_mfma_f32_16x16x32_bf16 v[20:23], v[176:179], v[140:143], v[20:23]
	ds_read_b128 v[144:147], v207 offset:0
	s_waitcnt lgkmcnt(4)
	v_mfma_f32_16x16x32_bf16 v[56:59], v[180:183], v[128:131], v[56:59]
	v_mfma_f32_16x16x32_bf16 v[60:63], v[180:183], v[132:135], v[60:63]
	ds_read_b128 v[164:167], v205 offset:2048
	v_mfma_f32_16x16x32_bf16 v[24:27], v[180:183], v[136:139], v[24:27]
	v_mfma_f32_16x16x32_bf16 v[28:31], v[180:183], v[140:143], v[28:31]
	ds_read_b128 v[148:151], v207 offset:2048
	s_waitcnt lgkmcnt(5)
	v_mfma_f32_16x16x32_bf16 v[32:35], v[184:187], v[128:131], v[32:35]
	v_mfma_f32_16x16x32_bf16 v[36:39], v[184:187], v[132:135], v[36:39]
	ds_read_b128 v[168:171], v205 offset:4096
	v_mfma_f32_16x16x32_bf16 v[0:3], v[184:187], v[136:139], v[0:3]
	v_mfma_f32_16x16x32_bf16 v[4:7], v[184:187], v[140:143], v[4:7]
	ds_read_b128 v[152:155], v207 offset:4096
	s_waitcnt lgkmcnt(6)
	v_mfma_f32_16x16x32_bf16 v[40:43], v[188:191], v[128:131], v[40:43]
	v_mfma_f32_16x16x32_bf16 v[44:47], v[188:191], v[132:135], v[44:47]
	ds_read_b128 v[172:175], v205 offset:6144
	v_mfma_f32_16x16x32_bf16 v[8:11], v[188:191], v[136:139], v[8:11]
	v_mfma_f32_16x16x32_bf16 v[12:15], v[188:191], v[140:143], v[12:15]
	ds_read_b128 v[156:159], v207 offset:6144
	ds_read_b128 v[176:179], v205 offset:8192
	ds_read_b128 v[180:183], v205 offset:10240
	ds_read_b128 v[184:187], v205 offset:12288
	ds_read_b128 v[188:191], v205 offset:14336
	s_waitcnt lgkmcnt(10)
	v_mfma_f32_16x16x32_bf16 v[112:115], v[160:163], v[144:147], v[112:115]
	s_waitcnt lgkmcnt(8)
	v_mfma_f32_16x16x32_bf16 v[116:119], v[160:163], v[148:151], v[116:119]
	s_waitcnt lgkmcnt(6)
	v_mfma_f32_16x16x32_bf16 v[80:83], v[160:163], v[152:155], v[80:83]
	s_waitcnt lgkmcnt(4)
	v_mfma_f32_16x16x32_bf16 v[84:87], v[160:163], v[156:159], v[84:87]
	v_mfma_f32_16x16x32_bf16 v[120:123], v[164:167], v[144:147], v[120:123]
	v_mfma_f32_16x16x32_bf16 v[124:127], v[164:167], v[148:151], v[124:127]
	v_mfma_f32_16x16x32_bf16 v[88:91], v[164:167], v[152:155], v[88:91]
	v_mfma_f32_16x16x32_bf16 v[92:95], v[164:167], v[156:159], v[92:95]
	v_mfma_f32_16x16x32_bf16 v[96:99], v[168:171], v[144:147], v[96:99]
	v_mfma_f32_16x16x32_bf16 v[100:103], v[168:171], v[148:151], v[100:103]
	v_mfma_f32_16x16x32_bf16 v[64:67], v[168:171], v[152:155], v[64:67]
	v_mfma_f32_16x16x32_bf16 v[68:71], v[168:171], v[156:159], v[68:71]
	v_mfma_f32_16x16x32_bf16 v[104:107], v[172:175], v[144:147], v[104:107]
	v_mfma_f32_16x16x32_bf16 v[108:111], v[172:175], v[148:151], v[108:111]
	v_mfma_f32_16x16x32_bf16 v[72:75], v[172:175], v[152:155], v[72:75]
	v_mfma_f32_16x16x32_bf16 v[76:79], v[172:175], v[156:159], v[76:79]
	s_waitcnt vmcnt(0) lgkmcnt(0)
	s_barrier
; DI void gemm_wide(const bf16_t* __restrict__ W, int ldw, const bf16_t* __restrict__ X, int ldx, int nkt,
;                   f32x16 (&acc)[4][2], bf16_t* lds) {
;     ...
;   for (int kt = 0; kt < nkt; kt += 2) {
;     __builtin_amdgcn_sched_barrier(0);
;     GW_ST2(1, 0, rw0, rw1)                         GW_KS(kt, 0)
;     GW_ST2(1, 128 * LDT, rw2, rw3)                 GW_KS(kt, 1)
;     GW_ST2(1, WT_E, rx0, rx1)                      GW_KS(kt, 2)
;     GW_ST2(1, WT_E + 128 * LDT, rx2, rx3)          GW_KS(kt, 3)
;     __builtin_amdgcn_sched_barrier(0);
;     GW_GLOAD(kt + 3 < nkt ? kt + 3 : nkt - 1)
;     __syncthreads();
;     __builtin_amdgcn_sched_barrier(0);
;     GW_ST2(0, 0, sw0, sw1)                         GW_KS(kt + 1, 0)
;     GW_ST2(0, 128 * LDT, sw2, sw3)                 GW_KS(kt + 1, 1)
;     GW_ST2(0, WT_E, sx0, sx1)                      GW_KS(kt + 1, 2)
;     GW_ST2(0, WT_E + 128 * LDT, sx2, sx3)          GW_KS(kt + 1, 3)
;     __builtin_amdgcn_sched_barrier(0);
;     GW_GLOAD_B(kt + 4 < nkt ? kt + 4 : nkt - 1)
;     __syncthreads();
	v_mfma_f32_16x16x32_bf16 v[48:51], v[176:179], v[144:147], v[48:51]
	v_mfma_f32_16x16x32_bf16 v[52:55], v[176:179], v[148:151], v[52:55]
	ds_read_b128 v[160:163], v204 offset:32768
	v_mfma_f32_16x16x32_bf16 v[16:19], v[176:179], v[152:155], v[16:19]
	v_mfma_f32_16x16x32_bf16 v[20:23], v[176:179], v[156:159], v[20:23]
	ds_read_b128 v[128:131], v206 offset:32768
	v_mfma_f32_16x16x32_bf16 v[56:59], v[180:183], v[144:147], v[56:59]
	v_mfma_f32_16x16x32_bf16 v[60:63], v[180:183], v[148:151], v[60:63]
	ds_read_b128 v[164:167], v204 offset:34816
	v_mfma_f32_16x16x32_bf16 v[24:27], v[180:183], v[152:155], v[24:27]
	v_mfma_f32_16x16x32_bf16 v[28:31], v[180:183], v[156:159], v[28:31]
	ds_read_b128 v[132:135], v206 offset:34816
	v_mfma_f32_16x16x32_bf16 v[32:35], v[184:187], v[144:147], v[32:35]
	v_mfma_f32_16x16x32_bf16 v[36:39], v[184:187], v[148:151], v[36:39]
	ds_read_b128 v[168:171], v204 offset:36864
	v_mfma_f32_16x16x32_bf16 v[0:3], v[184:187], v[152:155], v[0:3]
	v_mfma_f32_16x16x32_bf16 v[4:7], v[184:187], v[156:159], v[4:7]
	ds_read_b128 v[136:139], v206 offset:36864
	v_mfma_f32_16x16x32_bf16 v[40:43], v[188:191], v[144:147], v[40:43]
	v_mfma_f32_16x16x32_bf16 v[44:47], v[188:191], v[148:151], v[44:47]
	ds_read_b128 v[172:175], v204 offset:38912
	v_mfma_f32_16x16x32_bf16 v[8:11], v[188:191], v[152:155], v[8:11]
	v_mfma_f32_16x16x32_bf16 v[12:15], v[188:191], v[156:159], v[12:15]
	ds_read_b128 v[140:143], v206 offset:38912
	ds_read_b128 v[176:179], v204 offset:40960
	s_waitcnt lgkmcnt(7)
	v_mfma_f32_16x16x32_bf16 v[112:115], v[160:163], v[128:131], v[112:115]
	s_waitcnt lgkmcnt(5)
	v_mfma_f32_16x16x32_bf16 v[116:119], v[160:163], v[132:135], v[116:119]
	s_waitcnt lgkmcnt(3)
	v_mfma_f32_16x16x32_bf16 v[80:83], v[160:163], v[136:139], v[80:83]
	s_waitcnt lgkmcnt(1)
	v_mfma_f32_16x16x32_bf16 v[84:87], v[160:163], v[140:143], v[84:87]
	ds_read_b128 v[180:183], v204 offset:43008
	v_mfma_f32_16x16x32_bf16 v[120:123], v[164:167], v[128:131], v[120:123]
	v_mfma_f32_16x16x32_bf16 v[124:127], v[164:167], v[132:135], v[124:127]
	v_mfma_f32_16x16x32_bf16 v[88:91], v[164:167], v[136:139], v[88:91]
	v_mfma_f32_16x16x32_bf16 v[92:95], v[164:167], v[140:143], v[92:95]
	ds_read_b128 v[184:187], v204 offset:45056
	v_mfma_f32_16x16x32_bf16 v[96:99], v[168:171], v[128:131], v[96:99]
	v_mfma_f32_16x16x32_bf16 v[100:103], v[168:171], v[132:135], v[100:103]
	v_mfma_f32_16x16x32_bf16 v[64:67], v[168:171], v[136:139], v[64:67]
	v_mfma_f32_16x16x32_bf16 v[68:71], v[168:171], v[140:143], v[68:71]
	ds_read_b128 v[188:191], v204 offset:47104
	v_mfma_f32_16x16x32_bf16 v[104:107], v[172:175], v[128:131], v[104:107]
	v_mfma_f32_16x16x32_bf16 v[108:111], v[172:175], v[132:135], v[108:111]
	v_mfma_f32_16x16x32_bf16 v[72:75], v[172:175], v[136:139], v[72:75]
	v_mfma_f32_16x16x32_bf16 v[76:79], v[172:175], v[140:143], v[76:79]
	s_waitcnt lgkmcnt(3)
	v_mfma_f32_16x16x32_bf16 v[48:51], v[176:179], v[128:131], v[48:51]
	v_mfma_f32_16x16x32_bf16 v[52:55], v[176:179], v[132:135], v[52:55]
	ds_read_b128 v[160:163], v205 offset:32768
	v_mfma_f32_16x16x32_bf16 v[16:19], v[176:179], v[136:139], v[16:19]
	v_mfma_f32_16x16x32_bf16 v[20:23], v[176:179], v[140:143], v[20:23]
	ds_read_b128 v[144:147], v207 offset:32768
	s_waitcnt lgkmcnt(4)
	v_mfma_f32_16x16x32_bf16 v[56:59], v[180:183], v[128:131], v[56:59]
	v_mfma_f32_16x16x32_bf16 v[60:63], v[180:183], v[132:135], v[60:63]
	ds_read_b128 v[164:167], v205 offset:34816
	v_mfma_f32_16x16x32_bf16 v[24:27], v[180:183], v[136:139], v[24:27]
	v_mfma_f32_16x16x32_bf16 v[28:31], v[180:183], v[140:143], v[28:31]
	ds_read_b128 v[148:151], v207 offset:34816
	s_waitcnt lgkmcnt(5)
	v_mfma_f32_16x16x32_bf16 v[32:35], v[184:187], v[128:131], v[32:35]
	v_mfma_f32_16x16x32_bf16 v[36:39], v[184:187], v[132:135], v[36:39]
	ds_read_b128 v[168:171], v205 offset:36864
	v_mfma_f32_16x16x32_bf16 v[0:3], v[184:187], v[136:139], v[0:3]
	v_mfma_f32_16x16x32_bf16 v[4:7], v[184:187], v[140:143], v[4:7]
	ds_read_b128 v[152:155], v207 offset:36864
	s_waitcnt lgkmcnt(6)
	v_mfma_f32_16x16x32_bf16 v[40:43], v[188:191], v[128:131], v[40:43]
	v_mfma_f32_16x16x32_bf16 v[44:47], v[188:191], v[132:135], v[44:47]
	ds_read_b128 v[172:175], v205 offset:38912
	v_mfma_f32_16x16x32_bf16 v[8:11], v[188:191], v[136:139], v[8:11]
	v_mfma_f32_16x16x32_bf16 v[12:15], v[188:191], v[140:143], v[12:15]
	ds_read_b128 v[156:159], v207 offset:38912
	ds_read_b128 v[176:179], v205 offset:40960
	ds_read_b128 v[180:183], v205 offset:43008
	ds_read_b128 v[184:187], v205 offset:45056
	ds_read_b128 v[188:191], v205 offset:47104
	s_waitcnt lgkmcnt(10)
	v_mfma_f32_16x16x32_bf16 v[112:115], v[160:163], v[144:147], v[112:115]
	s_waitcnt lgkmcnt(8)
	v_mfma_f32_16x16x32_bf16 v[116:119], v[160:163], v[148:151], v[116:119]
	s_waitcnt lgkmcnt(6)
	v_mfma_f32_16x16x32_bf16 v[80:83], v[160:163], v[152:155], v[80:83]
	s_waitcnt lgkmcnt(4)
	v_mfma_f32_16x16x32_bf16 v[84:87], v[160:163], v[156:159], v[84:87]
	v_mfma_f32_16x16x32_bf16 v[120:123], v[164:167], v[144:147], v[120:123]
	v_mfma_f32_16x16x32_bf16 v[124:127], v[164:167], v[148:151], v[124:127]
	v_mfma_f32_16x16x32_bf16 v[88:91], v[164:167], v[152:155], v[88:91]
	v_mfma_f32_16x16x32_bf16 v[92:95], v[164:167], v[156:159], v[92:95]
	v_mfma_f32_16x16x32_bf16 v[96:99], v[168:171], v[144:147], v[96:99]
	v_mfma_f32_16x16x32_bf16 v[100:103], v[168:171], v[148:151], v[100:103]
	v_mfma_f32_16x16x32_bf16 v[64:67], v[168:171], v[152:155], v[64:67]
	v_mfma_f32_16x16x32_bf16 v[68:71], v[168:171], v[156:159], v[68:71]
	v_mfma_f32_16x16x32_bf16 v[104:107], v[172:175], v[144:147], v[104:107]
	v_mfma_f32_16x16x32_bf16 v[108:111], v[172:175], v[148:151], v[108:111]
	v_mfma_f32_16x16x32_bf16 v[72:75], v[172:175], v[152:155], v[72:75]
	v_mfma_f32_16x16x32_bf16 v[76:79], v[172:175], v[156:159], v[76:79]
	s_waitcnt vmcnt(0) lgkmcnt(0)
	s_barrier
; DI bool epi_inproj_chunk(const P& p, int layer, int ch, int m0w, f32x16 (&a0)[2], f32x16 (&a1)[2], bf16_t* stg, int cp,
;                          bf16_t*& rdst, int& rldd, int& rcoff, float rs0, float rs1) {
;     ...
;   int type = RAW, ldd = 512, coff = 0, nh = 2, dv = 64, hd = 0, doff = 0;
;   bf16_t* dst = nullptr; const float* gain = nullptr; float scl = 1.f;
;   const float* gains = p.qk_gain + layer * 512;
;   unsigned char* ws = p.ws;
;   if (ch < 8) { type = NORM; dst = (bf16_t*)(ws + O_AQ); coff = ch * 64; gain = gains; scl = QSCL; }
;   else if (ch < 16) { type = NORM; dst = (bf16_t*)(ws + O_AK); coff = (ch - 8) * 64; gain = gains + 64; }
;   else if (ch < 24) { type = TRANS; dst = (bf16_t*)(ws + O_AVT); nh = 4; dv = 128; hd = (ch - 16) >> 1; doff = ((ch - 16) & 1) * 64; }
;   else if (ch < 32) { type = NORM; dst = (bf16_t*)(ws + O_BQ); coff = (ch - 24) * 64; gain = gains + 128; scl = QSCL; }
;   else if (ch < 34) { type = NORM; dst = (bf16_t*)(ws + O_BK); ldd = 128; coff = (ch - 32) * 64; gain = gains + 192; }
;   else if (ch < 36) { type = TRANS; dst = (bf16_t*)(ws + O_BVT); hd = ch - 34; }
;   else if (ch < 44) { type = NORM; dst = (bf16_t*)(ws + O_CQ); coff = (ch - 36) * 64; gain = gains + 256; scl = QSCL; }
;   else if (ch < 46) { type = RAW; dst = (bf16_t*)(ws + O_CK); ldd = 128; coff = (ch - 44) * 64; }
;   else if (ch < 48) { type = RAW; dst = (bf16_t*)(ws + O_CV); ldd = 128; coff = (ch - 46) * 64; }
;   else if (ch < 50) { type = NORM; dst = (bf16_t*)(ws + O_KS); ldd = 128; coff = (ch - 48) * 64; gain = gains + 384; }
;   else if (ch < 52) { type = TRANS; dst = (bf16_t*)(ws + O_VST); hd = ch - 50; }
;   else if (ch < 54) { type = NORM; dst = (bf16_t*)(ws + O_KW); ldd = 128; coff = (ch - 52) * 64; gain = gains + 448; }
;   else if (ch < 56) { type = TRANS; dst = (bf16_t*)(ws + O_VWT); hd = ch - 54; }
;   else if (ch < 104) { type = SIG; dst = (bf16_t*)(ws + O_MGS); ldd = 3072; coff = (ch - 56) * 64; }
;   else if (ch == 104) { type = CG; }
;   else return false;
	v_mfma_f32_16x16x32_bf16 v[48:51], v[176:179], v[144:147], v[48:51]
	v_mfma_f32_16x16x32_bf16 v[52:55], v[176:179], v[148:151], v[52:55]
	v_mfma_f32_16x16x32_bf16 v[16:19], v[176:179], v[152:155], v[16:19]
	v_mfma_f32_16x16x32_bf16 v[20:23], v[176:179], v[156:159], v[20:23]
	v_mfma_f32_16x16x32_bf16 v[56:59], v[180:183], v[144:147], v[56:59]
	v_mfma_f32_16x16x32_bf16 v[60:63], v[180:183], v[148:151], v[60:63]
	v_mfma_f32_16x16x32_bf16 v[24:27], v[180:183], v[152:155], v[24:27]
	v_mfma_f32_16x16x32_bf16 v[28:31], v[180:183], v[156:159], v[28:31]
	v_mfma_f32_16x16x32_bf16 v[32:35], v[184:187], v[144:147], v[32:35]
	v_mfma_f32_16x16x32_bf16 v[36:39], v[184:187], v[148:151], v[36:39]
	v_mfma_f32_16x16x32_bf16 v[0:3], v[184:187], v[152:155], v[0:3]
	v_mfma_f32_16x16x32_bf16 v[4:7], v[184:187], v[156:159], v[4:7]
	v_mfma_f32_16x16x32_bf16 v[40:43], v[188:191], v[144:147], v[40:43]
	v_mfma_f32_16x16x32_bf16 v[44:47], v[188:191], v[148:151], v[44:47]
	v_mfma_f32_16x16x32_bf16 v[8:11], v[188:191], v[152:155], v[8:11]
	v_mfma_f32_16x16x32_bf16 v[12:15], v[188:191], v[156:159], v[12:15]
	s_nop 7
	v_permlane16_swap_b32_e32 v112, v116
	v_permlane16_swap_b32_e32 v113, v117
	v_permlane16_swap_b32_e32 v114, v118
	v_permlane16_swap_b32_e32 v115, v119
	v_permlane16_swap_b32_e32 v120, v124
	v_permlane16_swap_b32_e32 v121, v125
	v_permlane16_swap_b32_e32 v122, v126
	v_permlane16_swap_b32_e32 v123, v127
	v_permlane32_swap_b32_e32 v112, v116
	v_permlane32_swap_b32_e32 v113, v117
	v_permlane32_swap_b32_e32 v114, v118
	v_permlane32_swap_b32_e32 v115, v119
	v_permlane32_swap_b32_e32 v120, v124
	v_permlane32_swap_b32_e32 v121, v125
	v_permlane32_swap_b32_e32 v122, v126
	v_permlane32_swap_b32_e32 v123, v127
	v_permlane16_swap_b32_e32 v80, v84
	v_permlane16_swap_b32_e32 v81, v85
	v_permlane16_swap_b32_e32 v82, v86
	v_permlane16_swap_b32_e32 v83, v87
	v_permlane16_swap_b32_e32 v88, v92
	v_permlane16_swap_b32_e32 v89, v93
	v_permlane16_swap_b32_e32 v90, v94
	v_permlane16_swap_b32_e32 v91, v95
	v_permlane32_swap_b32_e32 v80, v84
	v_permlane32_swap_b32_e32 v81, v85
	v_permlane32_swap_b32_e32 v82, v86
	v_permlane32_swap_b32_e32 v83, v87
	v_permlane32_swap_b32_e32 v88, v92
	v_permlane32_swap_b32_e32 v89, v93
	v_permlane32_swap_b32_e32 v90, v94
	v_permlane32_swap_b32_e32 v91, v95
	v_permlane16_swap_b32_e32 v96, v100
	v_permlane16_swap_b32_e32 v97, v101
	v_permlane16_swap_b32_e32 v98, v102
	v_permlane16_swap_b32_e32 v99, v103
	v_permlane16_swap_b32_e32 v104, v108
	v_permlane16_swap_b32_e32 v105, v109
	v_permlane16_swap_b32_e32 v106, v110
	v_permlane16_swap_b32_e32 v107, v111
	v_permlane32_swap_b32_e32 v96, v100
	v_permlane32_swap_b32_e32 v97, v101
	v_permlane32_swap_b32_e32 v98, v102
	v_permlane32_swap_b32_e32 v99, v103
	v_permlane32_swap_b32_e32 v104, v108
	v_permlane32_swap_b32_e32 v105, v109
	v_permlane32_swap_b32_e32 v106, v110
	v_permlane32_swap_b32_e32 v107, v111
	v_permlane16_swap_b32_e32 v64, v68
	v_permlane16_swap_b32_e32 v65, v69
	v_permlane16_swap_b32_e32 v66, v70
	v_permlane16_swap_b32_e32 v67, v71
	v_permlane16_swap_b32_e32 v72, v76
	v_permlane16_swap_b32_e32 v73, v77
	v_permlane16_swap_b32_e32 v74, v78
	v_permlane16_swap_b32_e32 v75, v79
	v_permlane32_swap_b32_e32 v64, v68
	v_permlane32_swap_b32_e32 v65, v69
	v_permlane32_swap_b32_e32 v66, v70
	v_permlane32_swap_b32_e32 v67, v71
	v_permlane32_swap_b32_e32 v72, v76
	v_permlane32_swap_b32_e32 v73, v77
	v_permlane32_swap_b32_e32 v74, v78
	v_permlane32_swap_b32_e32 v75, v79
	v_permlane16_swap_b32_e32 v48, v52
	v_permlane16_swap_b32_e32 v49, v53
	v_permlane16_swap_b32_e32 v50, v54
	v_permlane16_swap_b32_e32 v51, v55
	v_permlane16_swap_b32_e32 v56, v60
	v_permlane16_swap_b32_e32 v57, v61
	v_permlane16_swap_b32_e32 v58, v62
	v_permlane16_swap_b32_e32 v59, v63
	v_permlane32_swap_b32_e32 v48, v52
	v_permlane32_swap_b32_e32 v49, v53
	v_permlane32_swap_b32_e32 v50, v54
	v_permlane32_swap_b32_e32 v51, v55
	v_permlane32_swap_b32_e32 v56, v60
	v_permlane32_swap_b32_e32 v57, v61
	v_permlane32_swap_b32_e32 v58, v62
	v_permlane32_swap_b32_e32 v59, v63
	v_permlane16_swap_b32_e32 v16, v20
	v_permlane16_swap_b32_e32 v17, v21
	v_permlane16_swap_b32_e32 v18, v22
	v_permlane16_swap_b32_e32 v19, v23
	v_permlane16_swap_b32_e32 v24, v28
	v_permlane16_swap_b32_e32 v25, v29
	v_permlane16_swap_b32_e32 v26, v30
	v_permlane16_swap_b32_e32 v27, v31
	v_permlane32_swap_b32_e32 v16, v20
	v_permlane32_swap_b32_e32 v17, v21
	v_permlane32_swap_b32_e32 v18, v22
	v_permlane32_swap_b32_e32 v19, v23
	v_permlane32_swap_b32_e32 v24, v28
	v_permlane32_swap_b32_e32 v25, v29
	v_permlane32_swap_b32_e32 v26, v30
	v_permlane32_swap_b32_e32 v27, v31
	v_permlane16_swap_b32_e32 v32, v36
	v_permlane16_swap_b32_e32 v33, v37
	v_permlane16_swap_b32_e32 v34, v38
	v_permlane16_swap_b32_e32 v35, v39
	v_permlane16_swap_b32_e32 v40, v44
	v_permlane16_swap_b32_e32 v41, v45
	v_permlane16_swap_b32_e32 v42, v46
	v_permlane16_swap_b32_e32 v43, v47
	v_permlane32_swap_b32_e32 v32, v36
	v_permlane32_swap_b32_e32 v33, v37
	v_permlane32_swap_b32_e32 v34, v38
	v_permlane32_swap_b32_e32 v35, v39
	v_permlane32_swap_b32_e32 v40, v44
	v_permlane32_swap_b32_e32 v41, v45
	v_permlane32_swap_b32_e32 v42, v46
	v_permlane32_swap_b32_e32 v43, v47
	v_permlane16_swap_b32_e32 v0, v4
	v_permlane16_swap_b32_e32 v1, v5
	v_permlane16_swap_b32_e32 v2, v6
	v_permlane16_swap_b32_e32 v3, v7
	v_permlane16_swap_b32_e32 v8, v12
	v_permlane16_swap_b32_e32 v9, v13
	v_permlane16_swap_b32_e32 v10, v14
	v_permlane16_swap_b32_e32 v11, v15
	v_permlane32_swap_b32_e32 v0, v4
	v_permlane32_swap_b32_e32 v1, v5
	v_permlane32_swap_b32_e32 v2, v6
	v_permlane32_swap_b32_e32 v3, v7
	v_permlane32_swap_b32_e32 v8, v12
	v_permlane32_swap_b32_e32 v9, v13
	v_permlane32_swap_b32_e32 v10, v14
	v_permlane32_swap_b32_e32 v11, v15
	s_waitcnt vmcnt(9)
	v_mov_b32_e32 v130, v195
	s_lshl_b32 s66, s9, 2
	v_ashrrev_i32_e32 v131, 6, v130
	v_lshlrev_b32_e32 v128, 1, v131
	v_and_or_b32 v154, v128, 2, s66
	s_waitcnt vmcnt(0)
	v_mov_b32_e32 v142, v195
	v_cmp_lt_i32_e32 vcc, 7, v154
	s_mov_b64 s[40:41], 0
	s_and_saveexec_b64 s[0:1], vcc
	s_xor_b64 s[0:1], exec, s[0:1]
	s_cbranch_execz .LBB0_325
; DI bool epi_inproj_chunk(const P& p, int layer, int ch, int m0w, f32x16 (&a0)[2], f32x16 (&a1)[2], bf16_t* stg, int cp,
;                          bf16_t*& rdst, int& rldd, int& rcoff, float rs0, float rs1) {
;     ...
;   if (ch < 8) { type = NORM; dst = (bf16_t*)(ws + O_AQ); coff = ch * 64; gain = gains; scl = QSCL; }
;   else if (ch < 16) { type = NORM; dst = (bf16_t*)(ws + O_AK); coff = (ch - 8) * 64; gain = gains + 64; }
;   else if (ch < 24) { type = TRANS; dst = (bf16_t*)(ws + O_AVT); nh = 4; dv = 128; hd = (ch - 16) >> 1; doff = ((ch - 16) & 1) * 64; }
;   else if (ch < 32) { type = NORM; dst = (bf16_t*)(ws + O_BQ); coff = (ch - 24) * 64; gain = gains + 128; scl = QSCL; }
;   else if (ch < 34) { type = NORM; dst = (bf16_t*)(ws + O_BK); ldd = 128; coff = (ch - 32) * 64; gain = gains + 192; }
;   else if (ch < 36) { type = TRANS; dst = (bf16_t*)(ws + O_BVT); hd = ch - 34; }
;   else if (ch < 44) { type = NORM; dst = (bf16_t*)(ws + O_CQ); coff = (ch - 36) * 64; gain = gains + 256; scl = QSCL; }
;   else if (ch < 46) { type = RAW; dst = (bf16_t*)(ws + O_CK); ldd = 128; coff = (ch - 44) * 64; }
;   else if (ch < 48) { type = RAW; dst = (bf16_t*)(ws + O_CV); ldd = 128; coff = (ch - 46) * 64; }
;   else if (ch < 50) { type = NORM; dst = (bf16_t*)(ws + O_KS); ldd = 128; coff = (ch - 48) * 64; gain = gains + 384; }
;   else if (ch < 52) { type = TRANS; dst = (bf16_t*)(ws + O_VST); hd = ch - 50; }
;   else if (ch < 54) { type = NORM; dst = (bf16_t*)(ws + O_KW); ldd = 128; coff = (ch - 52) * 64; gain = gains + 448; }
;   else if (ch < 56) { type = TRANS; dst = (bf16_t*)(ws + O_VWT); hd = ch - 54; }
;   else if (ch < 104) { type = SIG; dst = (bf16_t*)(ws + O_MGS); ldd = 3072; coff = (ch - 56) * 64; }
;   else if (ch == 104) { type = CG; }
;   else return false;
	s_cmp_gt_u32 s66, 15
	s_cbranch_scc0 .LBB0_286
	s_cmp_gt_u32 s66, 23
	s_cbranch_scc0 .LBB0_287
	s_cmp_gt_u32 s66, 31
	s_cbranch_scc0 .LBB0_289
	v_cmp_lt_u32_e32 vcc, 33, v154
	s_and_saveexec_b64 s[30:31], vcc
	s_xor_b64 s[30:31], exec, s[30:31]
	s_cbranch_execz .LBB0_316
	s_cmp_gt_u32 s66, 35
	s_cbranch_scc0 .LBB0_290
	s_cmp_gt_u32 s66, 43
	s_cbranch_scc0 .LBB0_291
	v_cmp_lt_u32_e32 vcc, 45, v154
	s_mov_b64 s[44:45], 0
	s_and_saveexec_b64 s[38:39], vcc
	s_xor_b64 s[40:41], exec, s[38:39]
	s_cbranch_execz .LBB0_309
	s_mov_b64 s[38:39], -1
	s_mov_b64 s[62:63], 0
	s_cmp_gt_u32 s66, 47
	s_mov_b64 s[46:47], 0
	s_cbranch_scc0 .LBB0_306
	v_cmp_lt_u32_e32 vcc, 49, v154
	s_and_saveexec_b64 s[38:39], vcc
	s_xor_b64 s[44:45], exec, s[38:39]
	s_cbranch_execz .LBB0_303
	s_cmp_gt_u32 s66, 51
	s_cbranch_scc0 .LBB0_292
	v_cmp_lt_u32_e32 vcc, 53, v154
	s_mov_b64 s[28:29], 0
	s_and_saveexec_b64 s[38:39], vcc
	s_xor_b64 s[50:51], exec, s[38:39]
	s_cbranch_execz .LBB0_298
	s_mov_b64 s[38:39], -1
	s_mov_b64 s[34:35], 0
	s_cmp_gt_u32 s66, 55
	s_cbranch_scc0 .LBB0_295
	s_mov_b64 s[48:49], 0
	s_cmpk_gt_u32 s66, 0x67
	s_cbranch_scc0 .LBB0_284
	s_movk_i32 s38, 0x68
	v_cmp_eq_u32_e32 vcc, s38, v154
	s_mov_b64 s[38:39], 0
	s_and_b64 s[46:47], vcc, exec

; DI int tidx() { int t = threadIdx.x; asm volatile("" : "+v"(t)); return t; }
; DI void gemm_wide(const bf16_t* __restrict__ W, int ldw, const bf16_t* __restrict__ X, int ldx, int nkt,
;                   f32x16 (&acc)[4][2], bf16_t* lds) {
;   const int tid = tidx(), lane = tid & 63, wv = tid >> 6, wn = wv & 1, wm = wv >> 1;
;   const int lr = lane & 31, lh = lane >> 5;
;   const int lrow = tid >> 3, lkc = (tid & 7) * 8;
;   const bf16_t* wp = W + (size_t)lrow * ldw + lkc;
;   const bf16_t* xp = X + (size_t)lrow * ldx + lkc;
;   const size_t wst = (size_t)64 * ldw, xst = (size_t)64 * ldx;
;   u32x4 rw0, rw1, rw2, rw3, rx0, rx1, rx2, rx3;
;     ...
;   u32x4 sw0, sw1, sw2, sw3, sx0, sx1, sx2, sx3;
;     ...
;   __syncthreads();
;   GW_GLOAD(0)
;   GW_LSTORE(0)
;   GW_GLOAD(1)
;   GW_GLOAD_B(nkt > 2 ? 2 : nkt - 1)
;   __syncthreads();
; DI void phase_resid(const P& p, const bf16_t* W, const bf16_t* X, int K, bf16_t* sm, const Geo& ge, bool last) {
;     ...
;   while (tw.next(mt_, nt_)) {
;     f32x16 acc[4][2]; zero_acc8(acc);
;     const int ldk = K + 64;
;     gemm_wide(W + (size_t)nt_ * 256 * ldk, ldk, X + (size_t)mt_ * 256 * ldk, ldk, K / 64, acc, sm);
.LBB0_1104:
	s_cmp_gt_i32 s8, 63
	s_cselect_b64 s[0:1], -1, 0
	s_cmp_lt_i32 s8, 64
	s_mov_b64 s[4:5], -1
	s_mov_b32 s9, s54
	s_cbranch_scc0 .LBB0_1126
	s_ashr_i32 s9, s8, 3
	s_cmp_lt_i32 s9, 4
	s_cbranch_scc0 .LBB0_1125
	s_and_b32 s5, s8, 7
	s_or_b32 s4, s5, s55
	s_mul_i32 s26, s9, 0x88000
	s_mul_hi_i32 s25, s9, 0x88000
	s_add_u32 s26, s6, s26
	s_addc_u32 s27, s7, s25
	s_mul_i32 s25, s4, 0x88000
	s_add_u32 s28, s56, s25
	s_addc_u32 s29, s57, 0
	v_and_b32_e32 v128, 63, v195
	v_lshrrev_b32_e32 v129, 6, v195
	v_and_b32_e32 v130, 15, v128
	v_lshrrev_b32_e32 v131, 4, v128
	v_bfe_u32 v132, v130, 1, 3
	v_lshlrev_b32_e32 v133, 7, v130
	v_xor_b32_e32 v134, v131, v132
	v_lshl_add_u32 v135, v134, 4, v133
	v_and_b32_e32 v136, 1, v129
	v_lshlrev_b32_e32 v136, 14, v136
	v_lshrrev_b32_e32 v137, 1, v129
	v_lshlrev_b32_e32 v137, 13, v137
	v_add_u32_e32 v137, 0x10000, v137
	v_readfirstlane_b32 s98, v129
	v_add_u32_e32 v204, v136, v135
	v_xor_b32_e32 v205, 64, v204
	v_add_u32_e32 v206, v137, v135
	v_xor_b32_e32 v207, 64, v206
	s_lshl_b32 s98, s98, 12
	s_movk_i32 s100, 2176
	v_lshrrev_b32_e32 v138, 3, v128
	v_lshl_add_u32 v138, v129, 5, v138
	v_mul_lo_u32 v139, v138, s100
	v_and_b32_e32 v140, 7, v128
	v_lshrrev_b32_e32 v141, 4, v128
	v_xor_b32_e32 v142, v140, v141
	v_xor_b32_e32 v143, 4, v142
	v_lshl_add_u32 v208, v142, 4, v139
	v_lshl_add_u32 v209, v143, 4, v139
	v_add_u32_e32 v209, 0x4400, v209
	v_add_u32_e32 v210, 0x8800, v208
	v_add_u32_e32 v211, 0x8800, v209
	s_barrier
	s_mov_b32 m0, s98
	s_nop 0
	global_load_lds_dwordx4 v208, s[26:27]
	s_add_u32 m0, s98, 0x400
	s_nop 0
	global_load_lds_dwordx4 v209, s[26:27]
	s_add_u32 m0, s98, 0x800
	s_nop 0
	global_load_lds_dwordx4 v210, s[26:27]
	s_add_u32 m0, s98, 0xc00
	s_nop 0
	global_load_lds_dwordx4 v211, s[26:27]
	s_add_u32 s26, s26, 0x80
	s_addc_u32 s27, s27, 0
	s_add_u32 m0, s98, 0x10000
	s_nop 0
	global_load_lds_dwordx4 v208, s[28:29]
	s_add_u32 m0, s98, 0x10400
	s_nop 0
	global_load_lds_dwordx4 v209, s[28:29]
	s_add_u32 m0, s98, 0x10800
	s_nop 0
	global_load_lds_dwordx4 v210, s[28:29]
	s_add_u32 m0, s98, 0x10c00
	s_nop 0
	global_load_lds_dwordx4 v211, s[28:29]
	s_add_u32 s28, s28, 0x80
	s_addc_u32 s29, s29, 0
	s_add_u32 m0, s98, 0x8000
	s_nop 0
	global_load_lds_dwordx4 v208, s[26:27]
	s_add_u32 m0, s98, 0x8400
	s_nop 0
	global_load_lds_dwordx4 v209, s[26:27]
	s_add_u32 m0, s98, 0x8800
	s_nop 0
	global_load_lds_dwordx4 v210, s[26:27]
	s_add_u32 m0, s98, 0x8c00
	s_nop 0
	global_load_lds_dwordx4 v211, s[26:27]
	s_add_u32 s26, s26, 0x80
	s_addc_u32 s27, s27, 0
	v_mov_b64_e32 v[112:113], 0
	v_mov_b64_e32 v[114:115], 0
	v_mov_b64_e32 v[116:117], 0
	v_mov_b64_e32 v[118:119], 0
	v_mov_b64_e32 v[120:121], 0
	v_mov_b64_e32 v[122:123], 0
	v_mov_b64_e32 v[124:125], 0
	v_mov_b64_e32 v[126:127], 0
	v_mov_b64_e32 v[80:81], 0
	v_mov_b64_e32 v[82:83], 0
	v_mov_b64_e32 v[84:85], 0
	v_mov_b64_e32 v[86:87], 0
	v_mov_b64_e32 v[88:89], 0
	v_mov_b64_e32 v[90:91], 0
	v_mov_b64_e32 v[92:93], 0
	v_mov_b64_e32 v[94:95], 0
	v_mov_b64_e32 v[96:97], 0
	v_mov_b64_e32 v[98:99], 0
	v_mov_b64_e32 v[100:101], 0
	v_mov_b64_e32 v[102:103], 0
	v_mov_b64_e32 v[104:105], 0
	v_mov_b64_e32 v[106:107], 0
	v_mov_b64_e32 v[108:109], 0
	v_mov_b64_e32 v[110:111], 0
	v_mov_b64_e32 v[64:65], 0
	v_mov_b64_e32 v[66:67], 0
	v_mov_b64_e32 v[68:69], 0
	v_mov_b64_e32 v[70:71], 0
	v_mov_b64_e32 v[72:73], 0
	v_mov_b64_e32 v[74:75], 0
	v_mov_b64_e32 v[76:77], 0
	v_mov_b64_e32 v[78:79], 0
	v_mov_b64_e32 v[48:49], 0
	v_mov_b64_e32 v[50:51], 0
	v_mov_b64_e32 v[52:53], 0
	v_mov_b64_e32 v[54:55], 0
	v_mov_b64_e32 v[56:57], 0
	v_mov_b64_e32 v[58:59], 0
	v_mov_b64_e32 v[60:61], 0
	v_mov_b64_e32 v[62:63], 0
	v_mov_b64_e32 v[16:17], 0
	v_mov_b64_e32 v[18:19], 0
	v_mov_b64_e32 v[20:21], 0
	v_mov_b64_e32 v[22:23], 0
	v_mov_b64_e32 v[24:25], 0
	v_mov_b64_e32 v[26:27], 0
	v_mov_b64_e32 v[28:29], 0
	v_mov_b64_e32 v[30:31], 0
	v_mov_b64_e32 v[32:33], 0
	v_mov_b64_e32 v[34:35], 0
	v_mov_b64_e32 v[36:37], 0
	v_mov_b64_e32 v[38:39], 0
	v_mov_b64_e32 v[40:41], 0
	v_mov_b64_e32 v[42:43], 0
	v_mov_b64_e32 v[44:45], 0
	v_mov_b64_e32 v[46:47], 0
	v_mov_b64_e32 v[0:1], 0
	v_mov_b64_e32 v[2:3], 0
	v_mov_b64_e32 v[4:5], 0
	v_mov_b64_e32 v[6:7], 0
	v_mov_b64_e32 v[8:9], 0
	v_mov_b64_e32 v[10:11], 0
	v_mov_b64_e32 v[12:13], 0
	v_mov_b64_e32 v[14:15], 0
	s_waitcnt vmcnt(4)
	s_barrier
	ds_read_b128 v[160:163], v204 offset:0
	ds_read_b128 v[128:131], v206 offset:0
	ds_read_b128 v[164:167], v204 offset:2048
	ds_read_b128 v[132:135], v206 offset:2048
	ds_read_b128 v[168:171], v204 offset:4096
	ds_read_b128 v[136:139], v206 offset:4096
	ds_read_b128 v[172:175], v204 offset:6144
	ds_read_b128 v[140:143], v206 offset:6144
	s_movk_i32 s99, 7
; DI void gemm_wide(const bf16_t* __restrict__ W, int ldw, const bf16_t* __restrict__ X, int ldx, int nkt,
;                   f32x16 (&acc)[4][2], bf16_t* lds) {
;     ...
;   for (int kt = 0; kt < nkt; kt += 2) {
;     __builtin_amdgcn_sched_barrier(0);
;     GW_ST2(1, 0, rw0, rw1)                         GW_KS(kt, 0)
;     GW_ST2(1, 128 * LDT, rw2, rw3)                 GW_KS(kt, 1)
;     GW_ST2(1, WT_E, rx0, rx1)                      GW_KS(kt, 2)
;     GW_ST2(1, WT_E + 128 * LDT, rx2, rx3)          GW_KS(kt, 3)
;     __builtin_amdgcn_sched_barrier(0);
;     GW_GLOAD(kt + 3 < nkt ? kt + 3 : nkt - 1)
;     __syncthreads();
;     __builtin_amdgcn_sched_barrier(0);
;     GW_ST2(0, 0, sw0, sw1)                         GW_KS(kt + 1, 0)
;     GW_ST2(0, 128 * LDT, sw2, sw3)                 GW_KS(kt + 1, 1)
;     GW_ST2(0, WT_E, sx0, sx1)                      GW_KS(kt + 1, 2)
;     GW_ST2(0, WT_E + 128 * LDT, sx2, sx3)          GW_KS(kt + 1, 3)
;     __builtin_amdgcn_sched_barrier(0);
;     GW_GLOAD_B(kt + 4 < nkt ? kt + 4 : nkt - 1)
;     __syncthreads();
;   }
.Lgw_out_loop:
	ds_read_b128 v[176:179], v204 offset:8192
	s_waitcnt lgkmcnt(7)
	v_mfma_f32_16x16x32_bf16 v[112:115], v[160:163], v[128:131], v[112:115]
	s_add_u32 m0, s98, 0x18000
	s_waitcnt lgkmcnt(5)
	v_mfma_f32_16x16x32_bf16 v[116:119], v[160:163], v[132:135], v[116:119]
	s_waitcnt lgkmcnt(3)
	v_mfma_f32_16x16x32_bf16 v[80:83], v[160:163], v[136:139], v[80:83]
	global_load_lds_dwordx4 v208, s[28:29]
	s_waitcnt lgkmcnt(1)
	v_mfma_f32_16x16x32_bf16 v[84:87], v[160:163], v[140:143], v[84:87]
	ds_read_b128 v[180:183], v204 offset:10240
	v_mfma_f32_16x16x32_bf16 v[120:123], v[164:167], v[128:131], v[120:123]
	s_add_u32 m0, s98, 0x18400
	v_mfma_f32_16x16x32_bf16 v[124:127], v[164:167], v[132:135], v[124:127]
	v_mfma_f32_16x16x32_bf16 v[88:91], v[164:167], v[136:139], v[88:91]
	global_load_lds_dwordx4 v209, s[28:29]
	v_mfma_f32_16x16x32_bf16 v[92:95], v[164:167], v[140:143], v[92:95]
	ds_read_b128 v[184:187], v204 offset:12288
	v_mfma_f32_16x16x32_bf16 v[96:99], v[168:171], v[128:131], v[96:99]
	s_add_u32 m0, s98, 0x18800
	v_mfma_f32_16x16x32_bf16 v[100:103], v[168:171], v[132:135], v[100:103]
	v_mfma_f32_16x16x32_bf16 v[64:67], v[168:171], v[136:139], v[64:67]
	global_load_lds_dwordx4 v210, s[28:29]
	v_mfma_f32_16x16x32_bf16 v[68:71], v[168:171], v[140:143], v[68:71]
	ds_read_b128 v[188:191], v204 offset:14336
	v_mfma_f32_16x16x32_bf16 v[104:107], v[172:175], v[128:131], v[104:107]
	s_add_u32 m0, s98, 0x18c00
	v_mfma_f32_16x16x32_bf16 v[108:111], v[172:175], v[132:135], v[108:111]
	v_mfma_f32_16x16x32_bf16 v[72:75], v[172:175], v[136:139], v[72:75]
	global_load_lds_dwordx4 v211, s[28:29]
	v_mfma_f32_16x16x32_bf16 v[76:79], v[172:175], v[140:143], v[76:79]
	s_add_u32 s28, s28, 0x80
	s_addc_u32 s29, s29, 0
	s_waitcnt lgkmcnt(3)
	v_mfma_f32_16x16x32_bf16 v[48:51], v[176:179], v[128:131], v[48:51]
	v_mfma_f32_16x16x32_bf16 v[52:55], v[176:179], v[132:135], v[52:55]
	ds_read_b128 v[160:163], v205 offset:0
	v_mfma_f32_16x16x32_bf16 v[16:19], v[176:179], v[136:139], v[16:19]
	v_mfma_f32_16x16x32_bf16 v[20:23], v[176:179], v[140:143], v[20:23]
	ds_read_b128 v[144:147], v207 offset:0
	s_waitcnt lgkmcnt(4)
	v_mfma_f32_16x16x32_bf16 v[56:59], v[180:183], v[128:131], v[56:59]
	v_mfma_f32_16x16x32_bf16 v[60:63], v[180:183], v[132:135], v[60:63]
	ds_read_b128 v[164:167], v205 offset:2048
	v_mfma_f32_16x16x32_bf16 v[24:27], v[180:183], v[136:139], v[24:27]
	v_mfma_f32_16x16x32_bf16 v[28:31], v[180:183], v[140:143], v[28:31]
	ds_read_b128 v[148:151], v207 offset:2048
	s_waitcnt lgkmcnt(5)
	v_mfma_f32_16x16x32_bf16 v[32:35], v[184:187], v[128:131], v[32:35]
	v_mfma_f32_16x16x32_bf16 v[36:39], v[184:187], v[132:135], v[36:39]
	ds_read_b128 v[168:171], v205 offset:4096
	v_mfma_f32_16x16x32_bf16 v[0:3], v[184:187], v[136:139], v[0:3]
	v_mfma_f32_16x16x32_bf16 v[4:7], v[184:187], v[140:143], v[4:7]
	ds_read_b128 v[152:155], v207 offset:4096
	s_waitcnt lgkmcnt(6)
	v_mfma_f32_16x16x32_bf16 v[40:43], v[188:191], v[128:131], v[40:43]
	v_mfma_f32_16x16x32_bf16 v[44:47], v[188:191], v[132:135], v[44:47]
	ds_read_b128 v[172:175], v205 offset:6144
	v_mfma_f32_16x16x32_bf16 v[8:11], v[188:191], v[136:139], v[8:11]
	v_mfma_f32_16x16x32_bf16 v[12:15], v[188:191], v[140:143], v[12:15]
	ds_read_b128 v[156:159], v207 offset:6144
	ds_read_b128 v[176:179], v205 offset:8192
	ds_read_b128 v[180:183], v205 offset:10240
	ds_read_b128 v[184:187], v205 offset:12288
	ds_read_b128 v[188:191], v205 offset:14336
	s_waitcnt lgkmcnt(10)
	v_mfma_f32_16x16x32_bf16 v[112:115], v[160:163], v[144:147], v[112:115]
	s_waitcnt lgkmcnt(8)
	v_mfma_f32_16x16x32_bf16 v[116:119], v[160:163], v[148:151], v[116:119]
	s_waitcnt lgkmcnt(6)
	v_mfma_f32_16x16x32_bf16 v[80:83], v[160:163], v[152:155], v[80:83]
	s_waitcnt lgkmcnt(4)
	v_mfma_f32_16x16x32_bf16 v[84:87], v[160:163], v[156:159], v[84:87]
	v_mfma_f32_16x16x32_bf16 v[120:123], v[164:167], v[144:147], v[120:123]
	v_mfma_f32_16x16x32_bf16 v[124:127], v[164:167], v[148:151], v[124:127]
	v_mfma_f32_16x16x32_bf16 v[88:91], v[164:167], v[152:155], v[88:91]
	v_mfma_f32_16x16x32_bf16 v[92:95], v[164:167], v[156:159], v[92:95]
	v_mfma_f32_16x16x32_bf16 v[96:99], v[168:171], v[144:147], v[96:99]
	v_mfma_f32_16x16x32_bf16 v[100:103], v[168:171], v[148:151], v[100:103]
	v_mfma_f32_16x16x32_bf16 v[64:67], v[168:171], v[152:155], v[64:67]
	v_mfma_f32_16x16x32_bf16 v[68:71], v[168:171], v[156:159], v[68:71]
	v_mfma_f32_16x16x32_bf16 v[104:107], v[172:175], v[144:147], v[104:107]
	v_mfma_f32_16x16x32_bf16 v[108:111], v[172:175], v[148:151], v[108:111]
	v_mfma_f32_16x16x32_bf16 v[72:75], v[172:175], v[152:155], v[72:75]
	v_mfma_f32_16x16x32_bf16 v[76:79], v[172:175], v[156:159], v[76:79]
	s_waitcnt vmcnt(0) lgkmcnt(0)
	s_barrier
; DI void gemm_wide(const bf16_t* __restrict__ W, int ldw, const bf16_t* __restrict__ X, int ldx, int nkt,
;                   f32x16 (&acc)[4][2], bf16_t* lds) {
;     ...
;   for (int kt = 0; kt < nkt; kt += 2) {
;     __builtin_amdgcn_sched_barrier(0);
;     GW_ST2(1, 0, rw0, rw1)                         GW_KS(kt, 0)
;     GW_ST2(1, 128 * LDT, rw2, rw3)                 GW_KS(kt, 1)
;     GW_ST2(1, WT_E, rx0, rx1)                      GW_KS(kt, 2)
;     GW_ST2(1, WT_E + 128 * LDT, rx2, rx3)          GW_KS(kt, 3)
;     __builtin_amdgcn_sched_barrier(0);
;     GW_GLOAD(kt + 3 < nkt ? kt + 3 : nkt - 1)
;     __syncthreads();
;     __builtin_amdgcn_sched_barrier(0);
;     GW_ST2(0, 0, sw0, sw1)                         GW_KS(kt + 1, 0)
;     GW_ST2(0, 128 * LDT, sw2, sw3)                 GW_KS(kt + 1, 1)
;     GW_ST2(0, WT_E, sx0, sx1)                      GW_KS(kt + 1, 2)
;     GW_ST2(0, WT_E + 128 * LDT, sx2, sx3)          GW_KS(kt + 1, 3)
;     __builtin_amdgcn_sched_barrier(0);
;     GW_GLOAD_B(kt + 4 < nkt ? kt + 4 : nkt - 1)
;     __syncthreads();
;   }
	v_mfma_f32_16x16x32_bf16 v[48:51], v[176:179], v[144:147], v[48:51]
	s_mov_b32 m0, s98
	v_mfma_f32_16x16x32_bf16 v[52:55], v[176:179], v[148:151], v[52:55]
	ds_read_b128 v[160:163], v204 offset:32768
	v_mfma_f32_16x16x32_bf16 v[16:19], v[176:179], v[152:155], v[16:19]
	global_load_lds_dwordx4 v208, s[26:27]
	v_mfma_f32_16x16x32_bf16 v[20:23], v[176:179], v[156:159], v[20:23]
	ds_read_b128 v[128:131], v206 offset:32768
	v_mfma_f32_16x16x32_bf16 v[56:59], v[180:183], v[144:147], v[56:59]
	s_add_u32 m0, s98, 0x400
	v_mfma_f32_16x16x32_bf16 v[60:63], v[180:183], v[148:151], v[60:63]
	ds_read_b128 v[164:167], v204 offset:34816
	v_mfma_f32_16x16x32_bf16 v[24:27], v[180:183], v[152:155], v[24:27]
	global_load_lds_dwordx4 v209, s[26:27]
	v_mfma_f32_16x16x32_bf16 v[28:31], v[180:183], v[156:159], v[28:31]
	ds_read_b128 v[132:135], v206 offset:34816
	v_mfma_f32_16x16x32_bf16 v[32:35], v[184:187], v[144:147], v[32:35]
	s_add_u32 m0, s98, 0x800
	v_mfma_f32_16x16x32_bf16 v[36:39], v[184:187], v[148:151], v[36:39]
	ds_read_b128 v[168:171], v204 offset:36864
	v_mfma_f32_16x16x32_bf16 v[0:3], v[184:187], v[152:155], v[0:3]
	global_load_lds_dwordx4 v210, s[26:27]
	v_mfma_f32_16x16x32_bf16 v[4:7], v[184:187], v[156:159], v[4:7]
	ds_read_b128 v[136:139], v206 offset:36864
	v_mfma_f32_16x16x32_bf16 v[40:43], v[188:191], v[144:147], v[40:43]
	s_add_u32 m0, s98, 0xc00
	v_mfma_f32_16x16x32_bf16 v[44:47], v[188:191], v[148:151], v[44:47]
	ds_read_b128 v[172:175], v204 offset:38912
	v_mfma_f32_16x16x32_bf16 v[8:11], v[188:191], v[152:155], v[8:11]
	global_load_lds_dwordx4 v211, s[26:27]
	v_mfma_f32_16x16x32_bf16 v[12:15], v[188:191], v[156:159], v[12:15]
	ds_read_b128 v[140:143], v206 offset:38912
	s_add_u32 s26, s26, 0x80
	s_addc_u32 s27, s27, 0
	ds_read_b128 v[176:179], v204 offset:40960
	s_waitcnt lgkmcnt(7)
	v_mfma_f32_16x16x32_bf16 v[112:115], v[160:163], v[128:131], v[112:115]
	s_add_u32 m0, s98, 0x10000
	s_waitcnt lgkmcnt(5)
	v_mfma_f32_16x16x32_bf16 v[116:119], v[160:163], v[132:135], v[116:119]
	s_waitcnt lgkmcnt(3)
	v_mfma_f32_16x16x32_bf16 v[80:83], v[160:163], v[136:139], v[80:83]
	global_load_lds_dwordx4 v208, s[28:29]
	s_waitcnt lgkmcnt(1)
	v_mfma_f32_16x16x32_bf16 v[84:87], v[160:163], v[140:143], v[84:87]
	ds_read_b128 v[180:183], v204 offset:43008
	v_mfma_f32_16x16x32_bf16 v[120:123], v[164:167], v[128:131], v[120:123]
	s_add_u32 m0, s98, 0x10400
	v_mfma_f32_16x16x32_bf16 v[124:127], v[164:167], v[132:135], v[124:127]
	v_mfma_f32_16x16x32_bf16 v[88:91], v[164:167], v[136:139], v[88:91]
	global_load_lds_dwordx4 v209, s[28:29]
	v_mfma_f32_16x16x32_bf16 v[92:95], v[164:167], v[140:143], v[92:95]
	ds_read_b128 v[184:187], v204 offset:45056
	v_mfma_f32_16x16x32_bf16 v[96:99], v[168:171], v[128:131], v[96:99]
	s_add_u32 m0, s98, 0x10800
	v_mfma_f32_16x16x32_bf16 v[100:103], v[168:171], v[132:135], v[100:103]
	v_mfma_f32_16x16x32_bf16 v[64:67], v[168:171], v[136:139], v[64:67]
	global_load_lds_dwordx4 v210, s[28:29]
	v_mfma_f32_16x16x32_bf16 v[68:71], v[168:171], v[140:143], v[68:71]
	ds_read_b128 v[188:191], v204 offset:47104
	v_mfma_f32_16x16x32_bf16 v[104:107], v[172:175], v[128:131], v[104:107]
	s_add_u32 m0, s98, 0x10c00
	v_mfma_f32_16x16x32_bf16 v[108:111], v[172:175], v[132:135], v[108:111]
	v_mfma_f32_16x16x32_bf16 v[72:75], v[172:175], v[136:139], v[72:75]
	global_load_lds_dwordx4 v211, s[28:29]
	v_mfma_f32_16x16x32_bf16 v[76:79], v[172:175], v[140:143], v[76:79]
	s_add_u32 s28, s28, 0x80
	s_addc_u32 s29, s29, 0
	s_waitcnt lgkmcnt(3)
	v_mfma_f32_16x16x32_bf16 v[48:51], v[176:179], v[128:131], v[48:51]
	v_mfma_f32_16x16x32_bf16 v[52:55], v[176:179], v[132:135], v[52:55]
	ds_read_b128 v[160:163], v205 offset:32768
	v_mfma_f32_16x16x32_bf16 v[16:19], v[176:179], v[136:139], v[16:19]
	v_mfma_f32_16x16x32_bf16 v[20:23], v[176:179], v[140:143], v[20:23]
	ds_read_b128 v[144:147], v207 offset:32768
	s_waitcnt lgkmcnt(4)
	v_mfma_f32_16x16x32_bf16 v[56:59], v[180:183], v[128:131], v[56:59]
	v_mfma_f32_16x16x32_bf16 v[60:63], v[180:183], v[132:135], v[60:63]
	ds_read_b128 v[164:167], v205 offset:34816
	v_mfma_f32_16x16x32_bf16 v[24:27], v[180:183], v[136:139], v[24:27]
	v_mfma_f32_16x16x32_bf16 v[28:31], v[180:183], v[140:143], v[28:31]
	ds_read_b128 v[148:151], v207 offset:34816
	s_waitcnt lgkmcnt(5)
	v_mfma_f32_16x16x32_bf16 v[32:35], v[184:187], v[128:131], v[32:35]
	v_mfma_f32_16x16x32_bf16 v[36:39], v[184:187], v[132:135], v[36:39]
	ds_read_b128 v[168:171], v205 offset:36864
	v_mfma_f32_16x16x32_bf16 v[0:3], v[184:187], v[136:139], v[0:3]
	v_mfma_f32_16x16x32_bf16 v[4:7], v[184:187], v[140:143], v[4:7]
	ds_read_b128 v[152:155], v207 offset:36864
	s_waitcnt lgkmcnt(6)
	v_mfma_f32_16x16x32_bf16 v[40:43], v[188:191], v[128:131], v[40:43]
	v_mfma_f32_16x16x32_bf16 v[44:47], v[188:191], v[132:135], v[44:47]
	ds_read_b128 v[172:175], v205 offset:38912
	v_mfma_f32_16x16x32_bf16 v[8:11], v[188:191], v[136:139], v[8:11]
	v_mfma_f32_16x16x32_bf16 v[12:15], v[188:191], v[140:143], v[12:15]
	ds_read_b128 v[156:159], v207 offset:38912
	ds_read_b128 v[176:179], v205 offset:40960
	ds_read_b128 v[180:183], v205 offset:43008
	ds_read_b128 v[184:187], v205 offset:45056
	ds_read_b128 v[188:191], v205 offset:47104
	s_waitcnt lgkmcnt(10)
	v_mfma_f32_16x16x32_bf16 v[112:115], v[160:163], v[144:147], v[112:115]
	s_waitcnt lgkmcnt(8)
	v_mfma_f32_16x16x32_bf16 v[116:119], v[160:163], v[148:151], v[116:119]
	s_waitcnt lgkmcnt(6)
	v_mfma_f32_16x16x32_bf16 v[80:83], v[160:163], v[152:155], v[80:83]
	s_waitcnt lgkmcnt(4)
	v_mfma_f32_16x16x32_bf16 v[84:87], v[160:163], v[156:159], v[84:87]
	v_mfma_f32_16x16x32_bf16 v[120:123], v[164:167], v[144:147], v[120:123]
	v_mfma_f32_16x16x32_bf16 v[124:127], v[164:167], v[148:151], v[124:127]
	v_mfma_f32_16x16x32_bf16 v[88:91], v[164:167], v[152:155], v[88:91]
	v_mfma_f32_16x16x32_bf16 v[92:95], v[164:167], v[156:159], v[92:95]
	v_mfma_f32_16x16x32_bf16 v[96:99], v[168:171], v[144:147], v[96:99]
	v_mfma_f32_16x16x32_bf16 v[100:103], v[168:171], v[148:151], v[100:103]
	v_mfma_f32_16x16x32_bf16 v[64:67], v[168:171], v[152:155], v[64:67]
	v_mfma_f32_16x16x32_bf16 v[68:71], v[168:171], v[156:159], v[68:71]
	v_mfma_f32_16x16x32_bf16 v[104:107], v[172:175], v[144:147], v[104:107]
	v_mfma_f32_16x16x32_bf16 v[108:111], v[172:175], v[148:151], v[108:111]
	v_mfma_f32_16x16x32_bf16 v[72:75], v[172:175], v[152:155], v[72:75]
	v_mfma_f32_16x16x32_bf16 v[76:79], v[172:175], v[156:159], v[76:79]
	s_waitcnt vmcnt(0) lgkmcnt(0)
	s_barrier
; DI void gemm_wide(const bf16_t* __restrict__ W, int ldw, const bf16_t* __restrict__ X, int ldx, int nkt,
;                   f32x16 (&acc)[4][2], bf16_t* lds) {
;     ...
;   for (int kt = 0; kt < nkt; kt += 2) {
;     __builtin_amdgcn_sched_barrier(0);
;     GW_ST2(1, 0, rw0, rw1)                         GW_KS(kt, 0)
;     GW_ST2(1, 128 * LDT, rw2, rw3)                 GW_KS(kt, 1)
;     GW_ST2(1, WT_E, rx0, rx1)                      GW_KS(kt, 2)
;     GW_ST2(1, WT_E + 128 * LDT, rx2, rx3)          GW_KS(kt, 3)
;     __builtin_amdgcn_sched_barrier(0);
;     GW_GLOAD(kt + 3 < nkt ? kt + 3 : nkt - 1)
;     __syncthreads();
;     __builtin_amdgcn_sched_barrier(0);
;     GW_ST2(0, 0, sw0, sw1)                         GW_KS(kt + 1, 0)
;     GW_ST2(0, 128 * LDT, sw2, sw3)                 GW_KS(kt + 1, 1)
;     GW_ST2(0, WT_E, sx0, sx1)                      GW_KS(kt + 1, 2)
;     GW_ST2(0, WT_E + 128 * LDT, sx2, sx3)          GW_KS(kt + 1, 3)
;     __builtin_amdgcn_sched_barrier(0);
;     GW_GLOAD_B(kt + 4 < nkt ? kt + 4 : nkt - 1)
;     __syncthreads();
;   }
	v_mfma_f32_16x16x32_bf16 v[48:51], v[176:179], v[144:147], v[48:51]
	s_add_u32 m0, s98, 0x8000
	v_mfma_f32_16x16x32_bf16 v[52:55], v[176:179], v[148:151], v[52:55]
	ds_read_b128 v[160:163], v204 offset:0
	v_mfma_f32_16x16x32_bf16 v[16:19], v[176:179], v[152:155], v[16:19]
	global_load_lds_dwordx4 v208, s[26:27]
	v_mfma_f32_16x16x32_bf16 v[20:23], v[176:179], v[156:159], v[20:23]
	ds_read_b128 v[128:131], v206 offset:0
	v_mfma_f32_16x16x32_bf16 v[56:59], v[180:183], v[144:147], v[56:59]
	s_add_u32 m0, s98, 0x8400
	v_mfma_f32_16x16x32_bf16 v[60:63], v[180:183], v[148:151], v[60:63]
	ds_read_b128 v[164:167], v204 offset:2048
	v_mfma_f32_16x16x32_bf16 v[24:27], v[180:183], v[152:155], v[24:27]
	global_load_lds_dwordx4 v209, s[26:27]
	v_mfma_f32_16x16x32_bf16 v[28:31], v[180:183], v[156:159], v[28:31]
	ds_read_b128 v[132:135], v206 offset:2048
	v_mfma_f32_16x16x32_bf16 v[32:35], v[184:187], v[144:147], v[32:35]
	s_add_u32 m0, s98, 0x8800
	v_mfma_f32_16x16x32_bf16 v[36:39], v[184:187], v[148:151], v[36:39]
	ds_read_b128 v[168:171], v204 offset:4096
	v_mfma_f32_16x16x32_bf16 v[0:3], v[184:187], v[152:155], v[0:3]
	global_load_lds_dwordx4 v210, s[26:27]
	v_mfma_f32_16x16x32_bf16 v[4:7], v[184:187], v[156:159], v[4:7]
	ds_read_b128 v[136:139], v206 offset:4096
	v_mfma_f32_16x16x32_bf16 v[40:43], v[188:191], v[144:147], v[40:43]
	s_add_u32 m0, s98, 0x8c00
	v_mfma_f32_16x16x32_bf16 v[44:47], v[188:191], v[148:151], v[44:47]
	ds_read_b128 v[172:175], v204 offset:6144
	v_mfma_f32_16x16x32_bf16 v[8:11], v[188:191], v[152:155], v[8:11]
	global_load_lds_dwordx4 v211, s[26:27]
	v_mfma_f32_16x16x32_bf16 v[12:15], v[188:191], v[156:159], v[12:15]
	ds_read_b128 v[140:143], v206 offset:6144
	s_add_u32 s26, s26, 0x80
	s_addc_u32 s27, s27, 0
	s_sub_u32 s99, s99, 1
	s_cmp_lg_u32 s99, 0
	s_cbranch_scc1 .Lgw_out_loop
	ds_read_b128 v[176:179], v204 offset:8192
	s_waitcnt lgkmcnt(7)
	v_mfma_f32_16x16x32_bf16 v[112:115], v[160:163], v[128:131], v[112:115]
	s_add_u32 m0, s98, 0x18000
	s_waitcnt lgkmcnt(5)
	v_mfma_f32_16x16x32_bf16 v[116:119], v[160:163], v[132:135], v[116:119]
	s_waitcnt lgkmcnt(3)
	v_mfma_f32_16x16x32_bf16 v[80:83], v[160:163], v[136:139], v[80:83]
	global_load_lds_dwordx4 v208, s[28:29]
	s_waitcnt lgkmcnt(1)
	v_mfma_f32_16x16x32_bf16 v[84:87], v[160:163], v[140:143], v[84:87]
	ds_read_b128 v[180:183], v204 offset:10240
	v_mfma_f32_16x16x32_bf16 v[120:123], v[164:167], v[128:131], v[120:123]
	s_add_u32 m0, s98, 0x18400
	v_mfma_f32_16x16x32_bf16 v[124:127], v[164:167], v[132:135], v[124:127]
	v_mfma_f32_16x16x32_bf16 v[88:91], v[164:167], v[136:139], v[88:91]
	global_load_lds_dwordx4 v209, s[28:29]
	v_mfma_f32_16x16x32_bf16 v[92:95], v[164:167], v[140:143], v[92:95]
	ds_read_b128 v[184:187], v204 offset:12288
	v_mfma_f32_16x16x32_bf16 v[96:99], v[168:171], v[128:131], v[96:99]
	s_add_u32 m0, s98, 0x18800
	v_mfma_f32_16x16x32_bf16 v[100:103], v[168:171], v[132:135], v[100:103]
	v_mfma_f32_16x16x32_bf16 v[64:67], v[168:171], v[136:139], v[64:67]
	global_load_lds_dwordx4 v210, s[28:29]
	v_mfma_f32_16x16x32_bf16 v[68:71], v[168:171], v[140:143], v[68:71]
	ds_read_b128 v[188:191], v204 offset:14336
	v_mfma_f32_16x16x32_bf16 v[104:107], v[172:175], v[128:131], v[104:107]
	s_add_u32 m0, s98, 0x18c00
	v_mfma_f32_16x16x32_bf16 v[108:111], v[172:175], v[132:135], v[108:111]
	v_mfma_f32_16x16x32_bf16 v[72:75], v[172:175], v[136:139], v[72:75]
	global_load_lds_dwordx4 v211, s[28:29]
	v_mfma_f32_16x16x32_bf16 v[76:79], v[172:175], v[140:143], v[76:79]
	s_add_u32 s28, s28, 0x80
	s_addc_u32 s29, s29, 0
	s_waitcnt lgkmcnt(3)
	v_mfma_f32_16x16x32_bf16 v[48:51], v[176:179], v[128:131], v[48:51]
	v_mfma_f32_16x16x32_bf16 v[52:55], v[176:179], v[132:135], v[52:55]
	ds_read_b128 v[160:163], v205 offset:0
	v_mfma_f32_16x16x32_bf16 v[16:19], v[176:179], v[136:139], v[16:19]
	v_mfma_f32_16x16x32_bf16 v[20:23], v[176:179], v[140:143], v[20:23]
	ds_read_b128 v[144:147], v207 offset:0
	s_waitcnt lgkmcnt(4)
	v_mfma_f32_16x16x32_bf16 v[56:59], v[180:183], v[128:131], v[56:59]
	v_mfma_f32_16x16x32_bf16 v[60:63], v[180:183], v[132:135], v[60:63]
	ds_read_b128 v[164:167], v205 offset:2048
	v_mfma_f32_16x16x32_bf16 v[24:27], v[180:183], v[136:139], v[24:27]
	v_mfma_f32_16x16x32_bf16 v[28:31], v[180:183], v[140:143], v[28:31]
	ds_read_b128 v[148:151], v207 offset:2048
	s_waitcnt lgkmcnt(5)
	v_mfma_f32_16x16x32_bf16 v[32:35], v[184:187], v[128:131], v[32:35]
	v_mfma_f32_16x16x32_bf16 v[36:39], v[184:187], v[132:135], v[36:39]
	ds_read_b128 v[168:171], v205 offset:4096
	v_mfma_f32_16x16x32_bf16 v[0:3], v[184:187], v[136:139], v[0:3]
	v_mfma_f32_16x16x32_bf16 v[4:7], v[184:187], v[140:143], v[4:7]
	ds_read_b128 v[152:155], v207 offset:4096
	s_waitcnt lgkmcnt(6)
	v_mfma_f32_16x16x32_bf16 v[40:43], v[188:191], v[128:131], v[40:43]
	v_mfma_f32_16x16x32_bf16 v[44:47], v[188:191], v[132:135], v[44:47]
	ds_read_b128 v[172:175], v205 offset:6144
	v_mfma_f32_16x16x32_bf16 v[8:11], v[188:191], v[136:139], v[8:11]
	v_mfma_f32_16x16x32_bf16 v[12:15], v[188:191], v[140:143], v[12:15]
	ds_read_b128 v[156:159], v207 offset:6144
	ds_read_b128 v[176:179], v205 offset:8192
	ds_read_b128 v[180:183], v205 offset:10240
	ds_read_b128 v[184:187], v205 offset:12288
	ds_read_b128 v[188:191], v205 offset:14336
	s_waitcnt lgkmcnt(10)
	v_mfma_f32_16x16x32_bf16 v[112:115], v[160:163], v[144:147], v[112:115]
	s_waitcnt lgkmcnt(8)
	v_mfma_f32_16x16x32_bf16 v[116:119], v[160:163], v[148:151], v[116:119]
	s_waitcnt lgkmcnt(6)
	v_mfma_f32_16x16x32_bf16 v[80:83], v[160:163], v[152:155], v[80:83]
	s_waitcnt lgkmcnt(4)
	v_mfma_f32_16x16x32_bf16 v[84:87], v[160:163], v[156:159], v[84:87]
	v_mfma_f32_16x16x32_bf16 v[120:123], v[164:167], v[144:147], v[120:123]
	v_mfma_f32_16x16x32_bf16 v[124:127], v[164:167], v[148:151], v[124:127]
	v_mfma_f32_16x16x32_bf16 v[88:91], v[164:167], v[152:155], v[88:91]
	v_mfma_f32_16x16x32_bf16 v[92:95], v[164:167], v[156:159], v[92:95]
	v_mfma_f32_16x16x32_bf16 v[96:99], v[168:171], v[144:147], v[96:99]
	v_mfma_f32_16x16x32_bf16 v[100:103], v[168:171], v[148:151], v[100:103]
	v_mfma_f32_16x16x32_bf16 v[64:67], v[168:171], v[152:155], v[64:67]
	v_mfma_f32_16x16x32_bf16 v[68:71], v[168:171], v[156:159], v[68:71]
	v_mfma_f32_16x16x32_bf16 v[104:107], v[172:175], v[144:147], v[104:107]
	v_mfma_f32_16x16x32_bf16 v[108:111], v[172:175], v[148:151], v[108:111]
	v_mfma_f32_16x16x32_bf16 v[72:75], v[172:175], v[152:155], v[72:75]
	v_mfma_f32_16x16x32_bf16 v[76:79], v[172:175], v[156:159], v[76:79]
	s_waitcnt vmcnt(0) lgkmcnt(0)
	s_barrier
; DI void gemm_wide(const bf16_t* __restrict__ W, int ldw, const bf16_t* __restrict__ X, int ldx, int nkt,
;                   f32x16 (&acc)[4][2], bf16_t* lds) {
;     ...
;   for (int kt = 0; kt < nkt; kt += 2) {
;     __builtin_amdgcn_sched_barrier(0);
;     GW_ST2(1, 0, rw0, rw1)                         GW_KS(kt, 0)
;     GW_ST2(1, 128 * LDT, rw2, rw3)                 GW_KS(kt, 1)
;     GW_ST2(1, WT_E, rx0, rx1)                      GW_KS(kt, 2)
;     GW_ST2(1, WT_E + 128 * LDT, rx2, rx3)          GW_KS(kt, 3)
;     __builtin_amdgcn_sched_barrier(0);
;     GW_GLOAD(kt + 3 < nkt ? kt + 3 : nkt - 1)
;     __syncthreads();
;     __builtin_amdgcn_sched_barrier(0);
;     GW_ST2(0, 0, sw0, sw1)                         GW_KS(kt + 1, 0)
;     GW_ST2(0, 128 * LDT, sw2, sw3)                 GW_KS(kt + 1, 1)
;     GW_ST2(0, WT_E, sx0, sx1)                      GW_KS(kt + 1, 2)
;     GW_ST2(0, WT_E + 128 * LDT, sx2, sx3)          GW_KS(kt + 1, 3)
;     __builtin_amdgcn_sched_barrier(0);
;     GW_GLOAD_B(kt + 4 < nkt ? kt + 4 : nkt - 1)
;     __syncthreads();
	v_mfma_f32_16x16x32_bf16 v[48:51], v[176:179], v[144:147], v[48:51]
	v_mfma_f32_16x16x32_bf16 v[52:55], v[176:179], v[148:151], v[52:55]
	ds_read_b128 v[160:163], v204 offset:32768
	v_mfma_f32_16x16x32_bf16 v[16:19], v[176:179], v[152:155], v[16:19]
	v_mfma_f32_16x16x32_bf16 v[20:23], v[176:179], v[156:159], v[20:23]
	ds_read_b128 v[128:131], v206 offset:32768
	v_mfma_f32_16x16x32_bf16 v[56:59], v[180:183], v[144:147], v[56:59]
	v_mfma_f32_16x16x32_bf16 v[60:63], v[180:183], v[148:151], v[60:63]
	ds_read_b128 v[164:167], v204 offset:34816
	v_mfma_f32_16x16x32_bf16 v[24:27], v[180:183], v[152:155], v[24:27]
	v_mfma_f32_16x16x32_bf16 v[28:31], v[180:183], v[156:159], v[28:31]
	ds_read_b128 v[132:135], v206 offset:34816
	v_mfma_f32_16x16x32_bf16 v[32:35], v[184:187], v[144:147], v[32:35]
	v_mfma_f32_16x16x32_bf16 v[36:39], v[184:187], v[148:151], v[36:39]
	ds_read_b128 v[168:171], v204 offset:36864
	v_mfma_f32_16x16x32_bf16 v[0:3], v[184:187], v[152:155], v[0:3]
	v_mfma_f32_16x16x32_bf16 v[4:7], v[184:187], v[156:159], v[4:7]
	ds_read_b128 v[136:139], v206 offset:36864
	v_mfma_f32_16x16x32_bf16 v[40:43], v[188:191], v[144:147], v[40:43]
	v_mfma_f32_16x16x32_bf16 v[44:47], v[188:191], v[148:151], v[44:47]
	ds_read_b128 v[172:175], v204 offset:38912
	v_mfma_f32_16x16x32_bf16 v[8:11], v[188:191], v[152:155], v[8:11]
	v_mfma_f32_16x16x32_bf16 v[12:15], v[188:191], v[156:159], v[12:15]
	ds_read_b128 v[140:143], v206 offset:38912
	ds_read_b128 v[176:179], v204 offset:40960
	s_waitcnt lgkmcnt(7)
	v_mfma_f32_16x16x32_bf16 v[112:115], v[160:163], v[128:131], v[112:115]
	s_waitcnt lgkmcnt(5)
	v_mfma_f32_16x16x32_bf16 v[116:119], v[160:163], v[132:135], v[116:119]
	s_waitcnt lgkmcnt(3)
	v_mfma_f32_16x16x32_bf16 v[80:83], v[160:163], v[136:139], v[80:83]
	s_waitcnt lgkmcnt(1)
	v_mfma_f32_16x16x32_bf16 v[84:87], v[160:163], v[140:143], v[84:87]
	ds_read_b128 v[180:183], v204 offset:43008
	v_mfma_f32_16x16x32_bf16 v[120:123], v[164:167], v[128:131], v[120:123]
	v_mfma_f32_16x16x32_bf16 v[124:127], v[164:167], v[132:135], v[124:127]
	v_mfma_f32_16x16x32_bf16 v[88:91], v[164:167], v[136:139], v[88:91]
	v_mfma_f32_16x16x32_bf16 v[92:95], v[164:167], v[140:143], v[92:95]
	ds_read_b128 v[184:187], v204 offset:45056
	v_mfma_f32_16x16x32_bf16 v[96:99], v[168:171], v[128:131], v[96:99]
	v_mfma_f32_16x16x32_bf16 v[100:103], v[168:171], v[132:135], v[100:103]
	v_mfma_f32_16x16x32_bf16 v[64:67], v[168:171], v[136:139], v[64:67]
	v_mfma_f32_16x16x32_bf16 v[68:71], v[168:171], v[140:143], v[68:71]
	ds_read_b128 v[188:191], v204 offset:47104
	v_mfma_f32_16x16x32_bf16 v[104:107], v[172:175], v[128:131], v[104:107]
	v_mfma_f32_16x16x32_bf16 v[108:111], v[172:175], v[132:135], v[108:111]
	v_mfma_f32_16x16x32_bf16 v[72:75], v[172:175], v[136:139], v[72:75]
	v_mfma_f32_16x16x32_bf16 v[76:79], v[172:175], v[140:143], v[76:79]
	s_waitcnt lgkmcnt(3)
	v_mfma_f32_16x16x32_bf16 v[48:51], v[176:179], v[128:131], v[48:51]
	v_mfma_f32_16x16x32_bf16 v[52:55], v[176:179], v[132:135], v[52:55]
	ds_read_b128 v[160:163], v205 offset:32768
	v_mfma_f32_16x16x32_bf16 v[16:19], v[176:179], v[136:139], v[16:19]
	v_mfma_f32_16x16x32_bf16 v[20:23], v[176:179], v[140:143], v[20:23]
	ds_read_b128 v[144:147], v207 offset:32768
	s_waitcnt lgkmcnt(4)
	v_mfma_f32_16x16x32_bf16 v[56:59], v[180:183], v[128:131], v[56:59]
	v_mfma_f32_16x16x32_bf16 v[60:63], v[180:183], v[132:135], v[60:63]
	ds_read_b128 v[164:167], v205 offset:34816
	v_mfma_f32_16x16x32_bf16 v[24:27], v[180:183], v[136:139], v[24:27]
	v_mfma_f32_16x16x32_bf16 v[28:31], v[180:183], v[140:143], v[28:31]
	ds_read_b128 v[148:151], v207 offset:34816
	s_waitcnt lgkmcnt(5)
	v_mfma_f32_16x16x32_bf16 v[32:35], v[184:187], v[128:131], v[32:35]
	v_mfma_f32_16x16x32_bf16 v[36:39], v[184:187], v[132:135], v[36:39]
	ds_read_b128 v[168:171], v205 offset:36864
	v_mfma_f32_16x16x32_bf16 v[0:3], v[184:187], v[136:139], v[0:3]
	v_mfma_f32_16x16x32_bf16 v[4:7], v[184:187], v[140:143], v[4:7]
	ds_read_b128 v[152:155], v207 offset:36864
	s_waitcnt lgkmcnt(6)
	v_mfma_f32_16x16x32_bf16 v[40:43], v[188:191], v[128:131], v[40:43]
	v_mfma_f32_16x16x32_bf16 v[44:47], v[188:191], v[132:135], v[44:47]
	ds_read_b128 v[172:175], v205 offset:38912
	v_mfma_f32_16x16x32_bf16 v[8:11], v[188:191], v[136:139], v[8:11]
	v_mfma_f32_16x16x32_bf16 v[12:15], v[188:191], v[140:143], v[12:15]
	ds_read_b128 v[156:159], v207 offset:38912
	ds_read_b128 v[176:179], v205 offset:40960
	ds_read_b128 v[180:183], v205 offset:43008
	ds_read_b128 v[184:187], v205 offset:45056
	ds_read_b128 v[188:191], v205 offset:47104
	s_waitcnt lgkmcnt(10)
	v_mfma_f32_16x16x32_bf16 v[112:115], v[160:163], v[144:147], v[112:115]
	s_waitcnt lgkmcnt(8)
	v_mfma_f32_16x16x32_bf16 v[116:119], v[160:163], v[148:151], v[116:119]
	s_waitcnt lgkmcnt(6)
	v_mfma_f32_16x16x32_bf16 v[80:83], v[160:163], v[152:155], v[80:83]
	s_waitcnt lgkmcnt(4)
	v_mfma_f32_16x16x32_bf16 v[84:87], v[160:163], v[156:159], v[84:87]
	v_mfma_f32_16x16x32_bf16 v[120:123], v[164:167], v[144:147], v[120:123]
	v_mfma_f32_16x16x32_bf16 v[124:127], v[164:167], v[148:151], v[124:127]
	v_mfma_f32_16x16x32_bf16 v[88:91], v[164:167], v[152:155], v[88:91]
	v_mfma_f32_16x16x32_bf16 v[92:95], v[164:167], v[156:159], v[92:95]
	v_mfma_f32_16x16x32_bf16 v[96:99], v[168:171], v[144:147], v[96:99]
	v_mfma_f32_16x16x32_bf16 v[100:103], v[168:171], v[148:151], v[100:103]
	v_mfma_f32_16x16x32_bf16 v[64:67], v[168:171], v[152:155], v[64:67]
	v_mfma_f32_16x16x32_bf16 v[68:71], v[168:171], v[156:159], v[68:71]
	v_mfma_f32_16x16x32_bf16 v[104:107], v[172:175], v[144:147], v[104:107]
	v_mfma_f32_16x16x32_bf16 v[108:111], v[172:175], v[148:151], v[108:111]
	v_mfma_f32_16x16x32_bf16 v[72:75], v[172:175], v[152:155], v[72:75]
	v_mfma_f32_16x16x32_bf16 v[76:79], v[172:175], v[156:159], v[76:79]
	s_waitcnt vmcnt(0) lgkmcnt(0)
	s_barrier
; DI void phase_resid(const P& p, const bf16_t* W, const bf16_t* X, int K, bf16_t* sm, const Geo& ge, bool last) {
;     ...
;     const int m0w = mt_ * 256 + wm * 64, n0w = nt_ * 256 + wn * 128;
; #pragma unroll
;     for (int cp = 0; cp < 2; ++cp) {
; #pragma unroll 4
;       for (int it = 0; it < 8; ++it) {
;         const int row = it * 8 + (lane >> 3), c8 = (lane & 7) * 8;
;         const u32x4 raw = *(const u32x4*)(xb + (size_t)(m0w + row) * LDK1 + n0w + cp * 64 + c8);
	v_mfma_f32_16x16x32_bf16 v[48:51], v[176:179], v[144:147], v[48:51]
	v_mfma_f32_16x16x32_bf16 v[52:55], v[176:179], v[148:151], v[52:55]
	v_mfma_f32_16x16x32_bf16 v[16:19], v[176:179], v[152:155], v[16:19]
	v_mfma_f32_16x16x32_bf16 v[20:23], v[176:179], v[156:159], v[20:23]
	v_mfma_f32_16x16x32_bf16 v[56:59], v[180:183], v[144:147], v[56:59]
	v_mfma_f32_16x16x32_bf16 v[60:63], v[180:183], v[148:151], v[60:63]
	v_mfma_f32_16x16x32_bf16 v[24:27], v[180:183], v[152:155], v[24:27]
	v_mfma_f32_16x16x32_bf16 v[28:31], v[180:183], v[156:159], v[28:31]
	v_mfma_f32_16x16x32_bf16 v[32:35], v[184:187], v[144:147], v[32:35]
	v_mfma_f32_16x16x32_bf16 v[36:39], v[184:187], v[148:151], v[36:39]
	v_mfma_f32_16x16x32_bf16 v[0:3], v[184:187], v[152:155], v[0:3]
	v_mfma_f32_16x16x32_bf16 v[4:7], v[184:187], v[156:159], v[4:7]
	v_mfma_f32_16x16x32_bf16 v[40:43], v[188:191], v[144:147], v[40:43]
	v_mfma_f32_16x16x32_bf16 v[44:47], v[188:191], v[148:151], v[44:47]
	v_mfma_f32_16x16x32_bf16 v[8:11], v[188:191], v[152:155], v[8:11]
	v_mfma_f32_16x16x32_bf16 v[12:15], v[188:191], v[156:159], v[12:15]
	s_nop 7
	v_permlane16_swap_b32_e32 v112, v116
	v_permlane16_swap_b32_e32 v113, v117
	v_permlane16_swap_b32_e32 v114, v118
	v_permlane16_swap_b32_e32 v115, v119
	v_permlane16_swap_b32_e32 v120, v124
	v_permlane16_swap_b32_e32 v121, v125
	v_permlane16_swap_b32_e32 v122, v126
	v_permlane16_swap_b32_e32 v123, v127
	v_permlane32_swap_b32_e32 v112, v116
	v_permlane32_swap_b32_e32 v113, v117
	v_permlane32_swap_b32_e32 v114, v118
	v_permlane32_swap_b32_e32 v115, v119
	v_permlane32_swap_b32_e32 v120, v124
	v_permlane32_swap_b32_e32 v121, v125
	v_permlane32_swap_b32_e32 v122, v126
	v_permlane32_swap_b32_e32 v123, v127
	v_permlane16_swap_b32_e32 v80, v84
	v_permlane16_swap_b32_e32 v81, v85
	v_permlane16_swap_b32_e32 v82, v86
	v_permlane16_swap_b32_e32 v83, v87
	v_permlane16_swap_b32_e32 v88, v92
	v_permlane16_swap_b32_e32 v89, v93
	v_permlane16_swap_b32_e32 v90, v94
	v_permlane16_swap_b32_e32 v91, v95
	v_permlane32_swap_b32_e32 v80, v84
	v_permlane32_swap_b32_e32 v81, v85
	v_permlane32_swap_b32_e32 v82, v86
	v_permlane32_swap_b32_e32 v83, v87
	v_permlane32_swap_b32_e32 v88, v92
	v_permlane32_swap_b32_e32 v89, v93
	v_permlane32_swap_b32_e32 v90, v94
	v_permlane32_swap_b32_e32 v91, v95
	v_permlane16_swap_b32_e32 v96, v100
	v_permlane16_swap_b32_e32 v97, v101
	v_permlane16_swap_b32_e32 v98, v102
	v_permlane16_swap_b32_e32 v99, v103
	v_permlane16_swap_b32_e32 v104, v108
	v_permlane16_swap_b32_e32 v105, v109
	v_permlane16_swap_b32_e32 v106, v110
	v_permlane16_swap_b32_e32 v107, v111
	v_permlane32_swap_b32_e32 v96, v100
	v_permlane32_swap_b32_e32 v97, v101
	v_permlane32_swap_b32_e32 v98, v102
	v_permlane32_swap_b32_e32 v99, v103
	v_permlane32_swap_b32_e32 v104, v108
	v_permlane32_swap_b32_e32 v105, v109
	v_permlane32_swap_b32_e32 v106, v110
	v_permlane32_swap_b32_e32 v107, v111
	v_permlane16_swap_b32_e32 v64, v68
	v_permlane16_swap_b32_e32 v65, v69
	v_permlane16_swap_b32_e32 v66, v70
	v_permlane16_swap_b32_e32 v67, v71
	v_permlane16_swap_b32_e32 v72, v76
	v_permlane16_swap_b32_e32 v73, v77
	v_permlane16_swap_b32_e32 v74, v78
	v_permlane16_swap_b32_e32 v75, v79
	v_permlane32_swap_b32_e32 v64, v68
	v_permlane32_swap_b32_e32 v65, v69
	v_permlane32_swap_b32_e32 v66, v70
	v_permlane32_swap_b32_e32 v67, v71
	v_permlane32_swap_b32_e32 v72, v76
	v_permlane32_swap_b32_e32 v73, v77
	v_permlane32_swap_b32_e32 v74, v78
	v_permlane32_swap_b32_e32 v75, v79
	v_permlane16_swap_b32_e32 v48, v52
	v_permlane16_swap_b32_e32 v49, v53
	v_permlane16_swap_b32_e32 v50, v54
	v_permlane16_swap_b32_e32 v51, v55
	v_permlane16_swap_b32_e32 v56, v60
	v_permlane16_swap_b32_e32 v57, v61
	v_permlane16_swap_b32_e32 v58, v62
	v_permlane16_swap_b32_e32 v59, v63
	v_permlane32_swap_b32_e32 v48, v52
	v_permlane32_swap_b32_e32 v49, v53
	v_permlane32_swap_b32_e32 v50, v54
	v_permlane32_swap_b32_e32 v51, v55
	v_permlane32_swap_b32_e32 v56, v60
	v_permlane32_swap_b32_e32 v57, v61
	v_permlane32_swap_b32_e32 v58, v62
	v_permlane32_swap_b32_e32 v59, v63
	v_permlane16_swap_b32_e32 v16, v20
	v_permlane16_swap_b32_e32 v17, v21
	v_permlane16_swap_b32_e32 v18, v22
	v_permlane16_swap_b32_e32 v19, v23
	v_permlane16_swap_b32_e32 v24, v28
	v_permlane16_swap_b32_e32 v25, v29
	v_permlane16_swap_b32_e32 v26, v30
	v_permlane16_swap_b32_e32 v27, v31
	v_permlane32_swap_b32_e32 v16, v20
	v_permlane32_swap_b32_e32 v17, v21
	v_permlane32_swap_b32_e32 v18, v22
	v_permlane32_swap_b32_e32 v19, v23
	v_permlane32_swap_b32_e32 v24, v28
	v_permlane32_swap_b32_e32 v25, v29
	v_permlane32_swap_b32_e32 v26, v30
	v_permlane32_swap_b32_e32 v27, v31
	v_permlane16_swap_b32_e32 v32, v36
	v_permlane16_swap_b32_e32 v33, v37
	v_permlane16_swap_b32_e32 v34, v38
	v_permlane16_swap_b32_e32 v35, v39
	v_permlane16_swap_b32_e32 v40, v44
	v_permlane16_swap_b32_e32 v41, v45
	v_permlane16_swap_b32_e32 v42, v46
	v_permlane16_swap_b32_e32 v43, v47
	v_permlane32_swap_b32_e32 v32, v36
	v_permlane32_swap_b32_e32 v33, v37
	v_permlane32_swap_b32_e32 v34, v38
	v_permlane32_swap_b32_e32 v35, v39
	v_permlane32_swap_b32_e32 v40, v44
	v_permlane32_swap_b32_e32 v41, v45
	v_permlane32_swap_b32_e32 v42, v46
	v_permlane32_swap_b32_e32 v43, v47
	v_permlane16_swap_b32_e32 v0, v4
	v_permlane16_swap_b32_e32 v1, v5
	v_permlane16_swap_b32_e32 v2, v6
	v_permlane16_swap_b32_e32 v3, v7
	v_permlane16_swap_b32_e32 v8, v12
	v_permlane16_swap_b32_e32 v9, v13
	v_permlane16_swap_b32_e32 v10, v14
	v_permlane16_swap_b32_e32 v11, v15
	v_permlane32_swap_b32_e32 v0, v4
	v_permlane32_swap_b32_e32 v1, v5
	v_permlane32_swap_b32_e32 v2, v6
	v_permlane32_swap_b32_e32 v3, v7
	v_permlane32_swap_b32_e32 v8, v12
	v_permlane32_swap_b32_e32 v9, v13
	v_permlane32_swap_b32_e32 v10, v14
	v_permlane32_swap_b32_e32 v11, v15
	s_waitcnt vmcnt(1)
	v_lshl_or_b32 v134, s9, 8, v235
	v_ashrrev_i32_e32 v135, 31, v134
	s_lshl_b32 s25, s5, 8
	v_lshl_add_u64 v[130:131], v[134:135], 1, v[196:197]
	v_add_u32_e32 v137, s25, v238
	s_mov_b32 s5, 0
	v_mov_b32_e32 v128, v237

; DI int tidx() { int t = threadIdx.x; asm volatile("" : "+v"(t)); return t; }
; DI void gemm_wide(const bf16_t* __restrict__ W, int ldw, const bf16_t* __restrict__ X, int ldx, int nkt,
;                   f32x16 (&acc)[4][2], bf16_t* lds) {
;   const int tid = tidx(), lane = tid & 63, wv = tid >> 6, wn = wv & 1, wm = wv >> 1;
;   const int lr = lane & 31, lh = lane >> 5;
;   const int lrow = tid >> 3, lkc = (tid & 7) * 8;
;   const bf16_t* wp = W + (size_t)lrow * ldw + lkc;
;   const bf16_t* xp = X + (size_t)lrow * ldx + lkc;
;   const size_t wst = (size_t)64 * ldw, xst = (size_t)64 * ldx;
;   u32x4 rw0, rw1, rw2, rw3, rx0, rx1, rx2, rx3;
;     ...
;   u32x4 sw0, sw1, sw2, sw3, sx0, sx1, sx2, sx3;
;     ...
;   __syncthreads();
;   GW_GLOAD(0)
;   GW_LSTORE(0)
;   GW_GLOAD(1)
;   GW_GLOAD_B(nkt > 2 ? 2 : nkt - 1)
;   __syncthreads();
; DI void phase_up(const P& p, int layer, bf16_t* sm, const Geo& ge) {
;     ...
;   while (tw.next(mt_, nt_)) {
;     if (mt_ != mt_have) {
;       rs0 = row_rstd(part, mt_ * 256 + wm * 64 + lr);
;       rs1 = row_rstd(part, mt_ * 256 + wm * 64 + 32 + lr);
;       mt_have = mt_;
;     }
;     f32x16 acc[4][2]; zero_acc8(acc);
;     gemm_wide(W + (size_t)nt_ * 256 * LDK1, LDK1, X + (size_t)mt_ * 256 * LDK1, LDK1, 16, acc, sm);
.LBB0_1145:
	s_lshl_b32 s0, s4, 3
	s_ashr_i32 s1, s5, 3
	s_add_i32 s0, s1, s0
	s_mul_i32 s8, s0, 0x88000
	s_mul_hi_i32 s1, s0, 0x88000
	s_add_u32 s8, s2, s8
	s_addc_u32 s9, s3, s1
	s_mul_i32 s1, s6, 0x88000
	s_add_u32 s26, s14, s1
	s_addc_u32 s27, s15, 0
	v_and_b32_e32 v128, 63, v195
	v_lshrrev_b32_e32 v129, 6, v195
	v_and_b32_e32 v130, 15, v128
	v_lshrrev_b32_e32 v131, 4, v128
	v_bfe_u32 v132, v130, 1, 3
	v_lshlrev_b32_e32 v133, 7, v130
	v_xor_b32_e32 v134, v131, v132
	v_lshl_add_u32 v135, v134, 4, v133
	v_and_b32_e32 v136, 1, v129
	v_lshlrev_b32_e32 v136, 14, v136
	v_lshrrev_b32_e32 v137, 1, v129
	v_lshlrev_b32_e32 v137, 13, v137
	v_add_u32_e32 v137, 0x10000, v137
	v_readfirstlane_b32 s98, v129
	v_add_u32_e32 v204, v136, v135
	v_xor_b32_e32 v205, 64, v204
	v_add_u32_e32 v206, v137, v135
	v_xor_b32_e32 v207, 64, v206
	s_lshl_b32 s98, s98, 12
	s_movk_i32 s100, 2176
	v_lshrrev_b32_e32 v138, 3, v128
	v_lshl_add_u32 v138, v129, 5, v138
	v_mul_lo_u32 v139, v138, s100
	v_and_b32_e32 v140, 7, v128
	v_lshrrev_b32_e32 v141, 4, v128
	v_xor_b32_e32 v142, v140, v141
	v_xor_b32_e32 v143, 4, v142
	v_lshl_add_u32 v208, v142, 4, v139
	v_lshl_add_u32 v209, v143, 4, v139
	v_add_u32_e32 v209, 0x4400, v209
	v_add_u32_e32 v210, 0x8800, v208
	v_add_u32_e32 v211, 0x8800, v209
	s_barrier
	s_mov_b32 m0, s98
	s_nop 0
	global_load_lds_dwordx4 v208, s[8:9]
	s_add_u32 m0, s98, 0x400
	s_nop 0
	global_load_lds_dwordx4 v209, s[8:9]
	s_add_u32 m0, s98, 0x800
	s_nop 0
	global_load_lds_dwordx4 v210, s[8:9]
	s_add_u32 m0, s98, 0xc00
	s_nop 0
	global_load_lds_dwordx4 v211, s[8:9]
	s_add_u32 s8, s8, 0x80
	s_addc_u32 s9, s9, 0
	s_add_u32 m0, s98, 0x10000
	s_nop 0
	global_load_lds_dwordx4 v208, s[26:27]
	s_add_u32 m0, s98, 0x10400
	s_nop 0
	global_load_lds_dwordx4 v209, s[26:27]
	s_add_u32 m0, s98, 0x10800
	s_nop 0
	global_load_lds_dwordx4 v210, s[26:27]
	s_add_u32 m0, s98, 0x10c00
	s_nop 0
	global_load_lds_dwordx4 v211, s[26:27]
	s_add_u32 s26, s26, 0x80
	s_addc_u32 s27, s27, 0
	s_add_u32 m0, s98, 0x8000
	s_nop 0
	global_load_lds_dwordx4 v208, s[8:9]
	s_add_u32 m0, s98, 0x8400
	s_nop 0
	global_load_lds_dwordx4 v209, s[8:9]
	s_add_u32 m0, s98, 0x8800
	s_nop 0
	global_load_lds_dwordx4 v210, s[8:9]
	s_add_u32 m0, s98, 0x8c00
	s_nop 0
	global_load_lds_dwordx4 v211, s[8:9]
	s_add_u32 s8, s8, 0x80
	s_addc_u32 s9, s9, 0
	v_mov_b64_e32 v[112:113], 0
	v_mov_b64_e32 v[114:115], 0
	v_mov_b64_e32 v[116:117], 0
	v_mov_b64_e32 v[118:119], 0
	v_mov_b64_e32 v[120:121], 0
	v_mov_b64_e32 v[122:123], 0
	v_mov_b64_e32 v[124:125], 0
	v_mov_b64_e32 v[126:127], 0
	v_mov_b64_e32 v[64:65], 0
	v_mov_b64_e32 v[66:67], 0
	v_mov_b64_e32 v[68:69], 0
	v_mov_b64_e32 v[70:71], 0
	v_mov_b64_e32 v[72:73], 0
	v_mov_b64_e32 v[74:75], 0
	v_mov_b64_e32 v[76:77], 0
	v_mov_b64_e32 v[78:79], 0
	v_mov_b64_e32 v[96:97], 0
	v_mov_b64_e32 v[98:99], 0
	v_mov_b64_e32 v[100:101], 0
	v_mov_b64_e32 v[102:103], 0
	v_mov_b64_e32 v[104:105], 0
	v_mov_b64_e32 v[106:107], 0
	v_mov_b64_e32 v[108:109], 0
	v_mov_b64_e32 v[110:111], 0
	v_mov_b64_e32 v[32:33], 0
	v_mov_b64_e32 v[34:35], 0
	v_mov_b64_e32 v[36:37], 0
	v_mov_b64_e32 v[38:39], 0
	v_mov_b64_e32 v[40:41], 0
	v_mov_b64_e32 v[42:43], 0
	v_mov_b64_e32 v[44:45], 0
	v_mov_b64_e32 v[46:47], 0
	v_mov_b64_e32 v[80:81], 0
	v_mov_b64_e32 v[82:83], 0
	v_mov_b64_e32 v[84:85], 0
	v_mov_b64_e32 v[86:87], 0
	v_mov_b64_e32 v[88:89], 0
	v_mov_b64_e32 v[90:91], 0
	v_mov_b64_e32 v[92:93], 0
	v_mov_b64_e32 v[94:95], 0
	v_mov_b64_e32 v[16:17], 0
	v_mov_b64_e32 v[18:19], 0
	v_mov_b64_e32 v[20:21], 0
	v_mov_b64_e32 v[22:23], 0
	v_mov_b64_e32 v[24:25], 0
	v_mov_b64_e32 v[26:27], 0
	v_mov_b64_e32 v[28:29], 0
	v_mov_b64_e32 v[30:31], 0
	v_mov_b64_e32 v[48:49], 0
	v_mov_b64_e32 v[50:51], 0
	v_mov_b64_e32 v[52:53], 0
	v_mov_b64_e32 v[54:55], 0
	v_mov_b64_e32 v[56:57], 0
	v_mov_b64_e32 v[58:59], 0
	v_mov_b64_e32 v[60:61], 0
	v_mov_b64_e32 v[62:63], 0
	v_mov_b64_e32 v[0:1], 0
	v_mov_b64_e32 v[2:3], 0
	v_mov_b64_e32 v[4:5], 0
	v_mov_b64_e32 v[6:7], 0
	v_mov_b64_e32 v[8:9], 0
	v_mov_b64_e32 v[10:11], 0
	v_mov_b64_e32 v[12:13], 0
	v_mov_b64_e32 v[14:15], 0
	s_waitcnt vmcnt(4)
	s_barrier
	ds_read_b128 v[160:163], v204 offset:0
	ds_read_b128 v[128:131], v206 offset:0
	ds_read_b128 v[164:167], v204 offset:2048
	ds_read_b128 v[132:135], v206 offset:2048
	ds_read_b128 v[168:171], v204 offset:4096
	ds_read_b128 v[136:139], v206 offset:4096
	ds_read_b128 v[172:175], v204 offset:6144
	ds_read_b128 v[140:143], v206 offset:6144
	s_movk_i32 s99, 7
; DI void gemm_wide(const bf16_t* __restrict__ W, int ldw, const bf16_t* __restrict__ X, int ldx, int nkt,
;                   f32x16 (&acc)[4][2], bf16_t* lds) {
;     ...
;   for (int kt = 0; kt < nkt; kt += 2) {
;     __builtin_amdgcn_sched_barrier(0);
;     GW_ST2(1, 0, rw0, rw1)                         GW_KS(kt, 0)
;     GW_ST2(1, 128 * LDT, rw2, rw3)                 GW_KS(kt, 1)
;     GW_ST2(1, WT_E, rx0, rx1)                      GW_KS(kt, 2)
;     GW_ST2(1, WT_E + 128 * LDT, rx2, rx3)          GW_KS(kt, 3)
;     __builtin_amdgcn_sched_barrier(0);
;     GW_GLOAD(kt + 3 < nkt ? kt + 3 : nkt - 1)
;     __syncthreads();
;     __builtin_amdgcn_sched_barrier(0);
;     GW_ST2(0, 0, sw0, sw1)                         GW_KS(kt + 1, 0)
;     GW_ST2(0, 128 * LDT, sw2, sw3)                 GW_KS(kt + 1, 1)
;     GW_ST2(0, WT_E, sx0, sx1)                      GW_KS(kt + 1, 2)
;     GW_ST2(0, WT_E + 128 * LDT, sx2, sx3)          GW_KS(kt + 1, 3)
;     __builtin_amdgcn_sched_barrier(0);
;     GW_GLOAD_B(kt + 4 < nkt ? kt + 4 : nkt - 1)
;     __syncthreads();
;   }
.Lgw_up_loop:
	ds_read_b128 v[176:179], v204 offset:8192
	s_waitcnt lgkmcnt(7)
	v_mfma_f32_16x16x32_bf16 v[112:115], v[160:163], v[128:131], v[112:115]
	s_add_u32 m0, s98, 0x18000
	s_waitcnt lgkmcnt(5)
	v_mfma_f32_16x16x32_bf16 v[116:119], v[160:163], v[132:135], v[116:119]
	s_waitcnt lgkmcnt(3)
	v_mfma_f32_16x16x32_bf16 v[64:67], v[160:163], v[136:139], v[64:67]
	global_load_lds_dwordx4 v208, s[26:27]
	s_waitcnt lgkmcnt(1)
	v_mfma_f32_16x16x32_bf16 v[68:71], v[160:163], v[140:143], v[68:71]
	ds_read_b128 v[180:183], v204 offset:10240
	v_mfma_f32_16x16x32_bf16 v[120:123], v[164:167], v[128:131], v[120:123]
	s_add_u32 m0, s98, 0x18400
	v_mfma_f32_16x16x32_bf16 v[124:127], v[164:167], v[132:135], v[124:127]
	v_mfma_f32_16x16x32_bf16 v[72:75], v[164:167], v[136:139], v[72:75]
	global_load_lds_dwordx4 v209, s[26:27]
	v_mfma_f32_16x16x32_bf16 v[76:79], v[164:167], v[140:143], v[76:79]
	ds_read_b128 v[184:187], v204 offset:12288
	v_mfma_f32_16x16x32_bf16 v[96:99], v[168:171], v[128:131], v[96:99]
	s_add_u32 m0, s98, 0x18800
	v_mfma_f32_16x16x32_bf16 v[100:103], v[168:171], v[132:135], v[100:103]
	v_mfma_f32_16x16x32_bf16 v[32:35], v[168:171], v[136:139], v[32:35]
	global_load_lds_dwordx4 v210, s[26:27]
	v_mfma_f32_16x16x32_bf16 v[36:39], v[168:171], v[140:143], v[36:39]
	ds_read_b128 v[188:191], v204 offset:14336
	v_mfma_f32_16x16x32_bf16 v[104:107], v[172:175], v[128:131], v[104:107]
	s_add_u32 m0, s98, 0x18c00
	v_mfma_f32_16x16x32_bf16 v[108:111], v[172:175], v[132:135], v[108:111]
	v_mfma_f32_16x16x32_bf16 v[40:43], v[172:175], v[136:139], v[40:43]
	global_load_lds_dwordx4 v211, s[26:27]
	v_mfma_f32_16x16x32_bf16 v[44:47], v[172:175], v[140:143], v[44:47]
	s_add_u32 s26, s26, 0x80
	s_addc_u32 s27, s27, 0
	s_waitcnt lgkmcnt(3)
	v_mfma_f32_16x16x32_bf16 v[80:83], v[176:179], v[128:131], v[80:83]
	v_mfma_f32_16x16x32_bf16 v[84:87], v[176:179], v[132:135], v[84:87]
	ds_read_b128 v[160:163], v205 offset:0
	v_mfma_f32_16x16x32_bf16 v[16:19], v[176:179], v[136:139], v[16:19]
	v_mfma_f32_16x16x32_bf16 v[20:23], v[176:179], v[140:143], v[20:23]
	ds_read_b128 v[144:147], v207 offset:0
	s_waitcnt lgkmcnt(4)
	v_mfma_f32_16x16x32_bf16 v[88:91], v[180:183], v[128:131], v[88:91]
	v_mfma_f32_16x16x32_bf16 v[92:95], v[180:183], v[132:135], v[92:95]
	ds_read_b128 v[164:167], v205 offset:2048
	v_mfma_f32_16x16x32_bf16 v[24:27], v[180:183], v[136:139], v[24:27]
	v_mfma_f32_16x16x32_bf16 v[28:31], v[180:183], v[140:143], v[28:31]
	ds_read_b128 v[148:151], v207 offset:2048
	s_waitcnt lgkmcnt(5)
	v_mfma_f32_16x16x32_bf16 v[48:51], v[184:187], v[128:131], v[48:51]
	v_mfma_f32_16x16x32_bf16 v[52:55], v[184:187], v[132:135], v[52:55]
	ds_read_b128 v[168:171], v205 offset:4096
	v_mfma_f32_16x16x32_bf16 v[0:3], v[184:187], v[136:139], v[0:3]
	v_mfma_f32_16x16x32_bf16 v[4:7], v[184:187], v[140:143], v[4:7]
	ds_read_b128 v[152:155], v207 offset:4096
	s_waitcnt lgkmcnt(6)
	v_mfma_f32_16x16x32_bf16 v[56:59], v[188:191], v[128:131], v[56:59]
	v_mfma_f32_16x16x32_bf16 v[60:63], v[188:191], v[132:135], v[60:63]
	ds_read_b128 v[172:175], v205 offset:6144
	v_mfma_f32_16x16x32_bf16 v[8:11], v[188:191], v[136:139], v[8:11]
	v_mfma_f32_16x16x32_bf16 v[12:15], v[188:191], v[140:143], v[12:15]
	ds_read_b128 v[156:159], v207 offset:6144
	ds_read_b128 v[176:179], v205 offset:8192
	ds_read_b128 v[180:183], v205 offset:10240
	ds_read_b128 v[184:187], v205 offset:12288
	ds_read_b128 v[188:191], v205 offset:14336
	s_waitcnt lgkmcnt(10)
	v_mfma_f32_16x16x32_bf16 v[112:115], v[160:163], v[144:147], v[112:115]
	s_waitcnt lgkmcnt(8)
	v_mfma_f32_16x16x32_bf16 v[116:119], v[160:163], v[148:151], v[116:119]
	s_waitcnt lgkmcnt(6)
	v_mfma_f32_16x16x32_bf16 v[64:67], v[160:163], v[152:155], v[64:67]
	s_waitcnt lgkmcnt(4)
	v_mfma_f32_16x16x32_bf16 v[68:71], v[160:163], v[156:159], v[68:71]
	v_mfma_f32_16x16x32_bf16 v[120:123], v[164:167], v[144:147], v[120:123]
	v_mfma_f32_16x16x32_bf16 v[124:127], v[164:167], v[148:151], v[124:127]
	v_mfma_f32_16x16x32_bf16 v[72:75], v[164:167], v[152:155], v[72:75]
	v_mfma_f32_16x16x32_bf16 v[76:79], v[164:167], v[156:159], v[76:79]
	v_mfma_f32_16x16x32_bf16 v[96:99], v[168:171], v[144:147], v[96:99]
	v_mfma_f32_16x16x32_bf16 v[100:103], v[168:171], v[148:151], v[100:103]
	v_mfma_f32_16x16x32_bf16 v[32:35], v[168:171], v[152:155], v[32:35]
	v_mfma_f32_16x16x32_bf16 v[36:39], v[168:171], v[156:159], v[36:39]
	v_mfma_f32_16x16x32_bf16 v[104:107], v[172:175], v[144:147], v[104:107]
	v_mfma_f32_16x16x32_bf16 v[108:111], v[172:175], v[148:151], v[108:111]
	v_mfma_f32_16x16x32_bf16 v[40:43], v[172:175], v[152:155], v[40:43]
	v_mfma_f32_16x16x32_bf16 v[44:47], v[172:175], v[156:159], v[44:47]
	s_waitcnt vmcnt(0) lgkmcnt(0)
	s_barrier
; DI void gemm_wide(const bf16_t* __restrict__ W, int ldw, const bf16_t* __restrict__ X, int ldx, int nkt,
;                   f32x16 (&acc)[4][2], bf16_t* lds) {
;     ...
;   for (int kt = 0; kt < nkt; kt += 2) {
;     __builtin_amdgcn_sched_barrier(0);
;     GW_ST2(1, 0, rw0, rw1)                         GW_KS(kt, 0)
;     GW_ST2(1, 128 * LDT, rw2, rw3)                 GW_KS(kt, 1)
;     GW_ST2(1, WT_E, rx0, rx1)                      GW_KS(kt, 2)
;     GW_ST2(1, WT_E + 128 * LDT, rx2, rx3)          GW_KS(kt, 3)
;     __builtin_amdgcn_sched_barrier(0);
;     GW_GLOAD(kt + 3 < nkt ? kt + 3 : nkt - 1)
;     __syncthreads();
;     __builtin_amdgcn_sched_barrier(0);
;     GW_ST2(0, 0, sw0, sw1)                         GW_KS(kt + 1, 0)
;     GW_ST2(0, 128 * LDT, sw2, sw3)                 GW_KS(kt + 1, 1)
;     GW_ST2(0, WT_E, sx0, sx1)                      GW_KS(kt + 1, 2)
;     GW_ST2(0, WT_E + 128 * LDT, sx2, sx3)          GW_KS(kt + 1, 3)
;     __builtin_amdgcn_sched_barrier(0);
;     GW_GLOAD_B(kt + 4 < nkt ? kt + 4 : nkt - 1)
;     __syncthreads();
;   }
	v_mfma_f32_16x16x32_bf16 v[80:83], v[176:179], v[144:147], v[80:83]
	s_mov_b32 m0, s98
	v_mfma_f32_16x16x32_bf16 v[84:87], v[176:179], v[148:151], v[84:87]
	ds_read_b128 v[160:163], v204 offset:32768
	v_mfma_f32_16x16x32_bf16 v[16:19], v[176:179], v[152:155], v[16:19]
	global_load_lds_dwordx4 v208, s[8:9]
	v_mfma_f32_16x16x32_bf16 v[20:23], v[176:179], v[156:159], v[20:23]
	ds_read_b128 v[128:131], v206 offset:32768
	v_mfma_f32_16x16x32_bf16 v[88:91], v[180:183], v[144:147], v[88:91]
	s_add_u32 m0, s98, 0x400
	v_mfma_f32_16x16x32_bf16 v[92:95], v[180:183], v[148:151], v[92:95]
	ds_read_b128 v[164:167], v204 offset:34816
	v_mfma_f32_16x16x32_bf16 v[24:27], v[180:183], v[152:155], v[24:27]
	global_load_lds_dwordx4 v209, s[8:9]
	v_mfma_f32_16x16x32_bf16 v[28:31], v[180:183], v[156:159], v[28:31]
	ds_read_b128 v[132:135], v206 offset:34816
	v_mfma_f32_16x16x32_bf16 v[48:51], v[184:187], v[144:147], v[48:51]
	s_add_u32 m0, s98, 0x800
	v_mfma_f32_16x16x32_bf16 v[52:55], v[184:187], v[148:151], v[52:55]
	ds_read_b128 v[168:171], v204 offset:36864
	v_mfma_f32_16x16x32_bf16 v[0:3], v[184:187], v[152:155], v[0:3]
	global_load_lds_dwordx4 v210, s[8:9]
	v_mfma_f32_16x16x32_bf16 v[4:7], v[184:187], v[156:159], v[4:7]
	ds_read_b128 v[136:139], v206 offset:36864
	v_mfma_f32_16x16x32_bf16 v[56:59], v[188:191], v[144:147], v[56:59]
	s_add_u32 m0, s98, 0xc00
	v_mfma_f32_16x16x32_bf16 v[60:63], v[188:191], v[148:151], v[60:63]
	ds_read_b128 v[172:175], v204 offset:38912
	v_mfma_f32_16x16x32_bf16 v[8:11], v[188:191], v[152:155], v[8:11]
	global_load_lds_dwordx4 v211, s[8:9]
	v_mfma_f32_16x16x32_bf16 v[12:15], v[188:191], v[156:159], v[12:15]
	ds_read_b128 v[140:143], v206 offset:38912
	s_add_u32 s8, s8, 0x80
	s_addc_u32 s9, s9, 0
	ds_read_b128 v[176:179], v204 offset:40960
	s_waitcnt lgkmcnt(7)
	v_mfma_f32_16x16x32_bf16 v[112:115], v[160:163], v[128:131], v[112:115]
	s_add_u32 m0, s98, 0x10000
	s_waitcnt lgkmcnt(5)
	v_mfma_f32_16x16x32_bf16 v[116:119], v[160:163], v[132:135], v[116:119]
	s_waitcnt lgkmcnt(3)
	v_mfma_f32_16x16x32_bf16 v[64:67], v[160:163], v[136:139], v[64:67]
	global_load_lds_dwordx4 v208, s[26:27]
	s_waitcnt lgkmcnt(1)
	v_mfma_f32_16x16x32_bf16 v[68:71], v[160:163], v[140:143], v[68:71]
	ds_read_b128 v[180:183], v204 offset:43008
	v_mfma_f32_16x16x32_bf16 v[120:123], v[164:167], v[128:131], v[120:123]
	s_add_u32 m0, s98, 0x10400
	v_mfma_f32_16x16x32_bf16 v[124:127], v[164:167], v[132:135], v[124:127]
	v_mfma_f32_16x16x32_bf16 v[72:75], v[164:167], v[136:139], v[72:75]
	global_load_lds_dwordx4 v209, s[26:27]
	v_mfma_f32_16x16x32_bf16 v[76:79], v[164:167], v[140:143], v[76:79]
	ds_read_b128 v[184:187], v204 offset:45056
	v_mfma_f32_16x16x32_bf16 v[96:99], v[168:171], v[128:131], v[96:99]
	s_add_u32 m0, s98, 0x10800
	v_mfma_f32_16x16x32_bf16 v[100:103], v[168:171], v[132:135], v[100:103]
	v_mfma_f32_16x16x32_bf16 v[32:35], v[168:171], v[136:139], v[32:35]
	global_load_lds_dwordx4 v210, s[26:27]
	v_mfma_f32_16x16x32_bf16 v[36:39], v[168:171], v[140:143], v[36:39]
	ds_read_b128 v[188:191], v204 offset:47104
	v_mfma_f32_16x16x32_bf16 v[104:107], v[172:175], v[128:131], v[104:107]
	s_add_u32 m0, s98, 0x10c00
	v_mfma_f32_16x16x32_bf16 v[108:111], v[172:175], v[132:135], v[108:111]
	v_mfma_f32_16x16x32_bf16 v[40:43], v[172:175], v[136:139], v[40:43]
	global_load_lds_dwordx4 v211, s[26:27]
	v_mfma_f32_16x16x32_bf16 v[44:47], v[172:175], v[140:143], v[44:47]
	s_add_u32 s26, s26, 0x80
	s_addc_u32 s27, s27, 0
	s_waitcnt lgkmcnt(3)
	v_mfma_f32_16x16x32_bf16 v[80:83], v[176:179], v[128:131], v[80:83]
	v_mfma_f32_16x16x32_bf16 v[84:87], v[176:179], v[132:135], v[84:87]
	ds_read_b128 v[160:163], v205 offset:32768
	v_mfma_f32_16x16x32_bf16 v[16:19], v[176:179], v[136:139], v[16:19]
	v_mfma_f32_16x16x32_bf16 v[20:23], v[176:179], v[140:143], v[20:23]
	ds_read_b128 v[144:147], v207 offset:32768
	s_waitcnt lgkmcnt(4)
	v_mfma_f32_16x16x32_bf16 v[88:91], v[180:183], v[128:131], v[88:91]
	v_mfma_f32_16x16x32_bf16 v[92:95], v[180:183], v[132:135], v[92:95]
	ds_read_b128 v[164:167], v205 offset:34816
	v_mfma_f32_16x16x32_bf16 v[24:27], v[180:183], v[136:139], v[24:27]
	v_mfma_f32_16x16x32_bf16 v[28:31], v[180:183], v[140:143], v[28:31]
	ds_read_b128 v[148:151], v207 offset:34816
	s_waitcnt lgkmcnt(5)
	v_mfma_f32_16x16x32_bf16 v[48:51], v[184:187], v[128:131], v[48:51]
	v_mfma_f32_16x16x32_bf16 v[52:55], v[184:187], v[132:135], v[52:55]
	ds_read_b128 v[168:171], v205 offset:36864
	v_mfma_f32_16x16x32_bf16 v[0:3], v[184:187], v[136:139], v[0:3]
	v_mfma_f32_16x16x32_bf16 v[4:7], v[184:187], v[140:143], v[4:7]
	ds_read_b128 v[152:155], v207 offset:36864
	s_waitcnt lgkmcnt(6)
	v_mfma_f32_16x16x32_bf16 v[56:59], v[188:191], v[128:131], v[56:59]
	v_mfma_f32_16x16x32_bf16 v[60:63], v[188:191], v[132:135], v[60:63]
	ds_read_b128 v[172:175], v205 offset:38912
	v_mfma_f32_16x16x32_bf16 v[8:11], v[188:191], v[136:139], v[8:11]
	v_mfma_f32_16x16x32_bf16 v[12:15], v[188:191], v[140:143], v[12:15]
	ds_read_b128 v[156:159], v207 offset:38912
	ds_read_b128 v[176:179], v205 offset:40960
	ds_read_b128 v[180:183], v205 offset:43008
	ds_read_b128 v[184:187], v205 offset:45056
	ds_read_b128 v[188:191], v205 offset:47104
	s_waitcnt lgkmcnt(10)
	v_mfma_f32_16x16x32_bf16 v[112:115], v[160:163], v[144:147], v[112:115]
	s_waitcnt lgkmcnt(8)
	v_mfma_f32_16x16x32_bf16 v[116:119], v[160:163], v[148:151], v[116:119]
	s_waitcnt lgkmcnt(6)
	v_mfma_f32_16x16x32_bf16 v[64:67], v[160:163], v[152:155], v[64:67]
	s_waitcnt lgkmcnt(4)
	v_mfma_f32_16x16x32_bf16 v[68:71], v[160:163], v[156:159], v[68:71]
	v_mfma_f32_16x16x32_bf16 v[120:123], v[164:167], v[144:147], v[120:123]
	v_mfma_f32_16x16x32_bf16 v[124:127], v[164:167], v[148:151], v[124:127]
	v_mfma_f32_16x16x32_bf16 v[72:75], v[164:167], v[152:155], v[72:75]
	v_mfma_f32_16x16x32_bf16 v[76:79], v[164:167], v[156:159], v[76:79]
	v_mfma_f32_16x16x32_bf16 v[96:99], v[168:171], v[144:147], v[96:99]
	v_mfma_f32_16x16x32_bf16 v[100:103], v[168:171], v[148:151], v[100:103]
	v_mfma_f32_16x16x32_bf16 v[32:35], v[168:171], v[152:155], v[32:35]
	v_mfma_f32_16x16x32_bf16 v[36:39], v[168:171], v[156:159], v[36:39]
	v_mfma_f32_16x16x32_bf16 v[104:107], v[172:175], v[144:147], v[104:107]
	v_mfma_f32_16x16x32_bf16 v[108:111], v[172:175], v[148:151], v[108:111]
	v_mfma_f32_16x16x32_bf16 v[40:43], v[172:175], v[152:155], v[40:43]
	v_mfma_f32_16x16x32_bf16 v[44:47], v[172:175], v[156:159], v[44:47]
	s_waitcnt vmcnt(0) lgkmcnt(0)
	s_barrier
; DI void gemm_wide(const bf16_t* __restrict__ W, int ldw, const bf16_t* __restrict__ X, int ldx, int nkt,
;                   f32x16 (&acc)[4][2], bf16_t* lds) {
;     ...
;   for (int kt = 0; kt < nkt; kt += 2) {
;     __builtin_amdgcn_sched_barrier(0);
;     GW_ST2(1, 0, rw0, rw1)                         GW_KS(kt, 0)
;     GW_ST2(1, 128 * LDT, rw2, rw3)                 GW_KS(kt, 1)
;     GW_ST2(1, WT_E, rx0, rx1)                      GW_KS(kt, 2)
;     GW_ST2(1, WT_E + 128 * LDT, rx2, rx3)          GW_KS(kt, 3)
;     __builtin_amdgcn_sched_barrier(0);
;     GW_GLOAD(kt + 3 < nkt ? kt + 3 : nkt - 1)
;     __syncthreads();
;     __builtin_amdgcn_sched_barrier(0);
;     GW_ST2(0, 0, sw0, sw1)                         GW_KS(kt + 1, 0)
;     GW_ST2(0, 128 * LDT, sw2, sw3)                 GW_KS(kt + 1, 1)
;     GW_ST2(0, WT_E, sx0, sx1)                      GW_KS(kt + 1, 2)
;     GW_ST2(0, WT_E + 128 * LDT, sx2, sx3)          GW_KS(kt + 1, 3)
;     __builtin_amdgcn_sched_barrier(0);
;     GW_GLOAD_B(kt + 4 < nkt ? kt + 4 : nkt - 1)
;     __syncthreads();
;   }
	v_mfma_f32_16x16x32_bf16 v[80:83], v[176:179], v[144:147], v[80:83]
	s_add_u32 m0, s98, 0x8000
	v_mfma_f32_16x16x32_bf16 v[84:87], v[176:179], v[148:151], v[84:87]
	ds_read_b128 v[160:163], v204 offset:0
	v_mfma_f32_16x16x32_bf16 v[16:19], v[176:179], v[152:155], v[16:19]
	global_load_lds_dwordx4 v208, s[8:9]
	v_mfma_f32_16x16x32_bf16 v[20:23], v[176:179], v[156:159], v[20:23]
	ds_read_b128 v[128:131], v206 offset:0
	v_mfma_f32_16x16x32_bf16 v[88:91], v[180:183], v[144:147], v[88:91]
	s_add_u32 m0, s98, 0x8400
	v_mfma_f32_16x16x32_bf16 v[92:95], v[180:183], v[148:151], v[92:95]
	ds_read_b128 v[164:167], v204 offset:2048
	v_mfma_f32_16x16x32_bf16 v[24:27], v[180:183], v[152:155], v[24:27]
	global_load_lds_dwordx4 v209, s[8:9]
	v_mfma_f32_16x16x32_bf16 v[28:31], v[180:183], v[156:159], v[28:31]
	ds_read_b128 v[132:135], v206 offset:2048
	v_mfma_f32_16x16x32_bf16 v[48:51], v[184:187], v[144:147], v[48:51]
	s_add_u32 m0, s98, 0x8800
	v_mfma_f32_16x16x32_bf16 v[52:55], v[184:187], v[148:151], v[52:55]
	ds_read_b128 v[168:171], v204 offset:4096
	v_mfma_f32_16x16x32_bf16 v[0:3], v[184:187], v[152:155], v[0:3]
	global_load_lds_dwordx4 v210, s[8:9]
	v_mfma_f32_16x16x32_bf16 v[4:7], v[184:187], v[156:159], v[4:7]
	ds_read_b128 v[136:139], v206 offset:4096
	v_mfma_f32_16x16x32_bf16 v[56:59], v[188:191], v[144:147], v[56:59]
	s_add_u32 m0, s98, 0x8c00
	v_mfma_f32_16x16x32_bf16 v[60:63], v[188:191], v[148:151], v[60:63]
	ds_read_b128 v[172:175], v204 offset:6144
	v_mfma_f32_16x16x32_bf16 v[8:11], v[188:191], v[152:155], v[8:11]
	global_load_lds_dwordx4 v211, s[8:9]
	v_mfma_f32_16x16x32_bf16 v[12:15], v[188:191], v[156:159], v[12:15]
	ds_read_b128 v[140:143], v206 offset:6144
	s_add_u32 s8, s8, 0x80
	s_addc_u32 s9, s9, 0
	s_sub_u32 s99, s99, 1
	s_cmp_lg_u32 s99, 0
	s_cbranch_scc1 .Lgw_up_loop
	ds_read_b128 v[176:179], v204 offset:8192
	s_waitcnt lgkmcnt(7)
	v_mfma_f32_16x16x32_bf16 v[112:115], v[160:163], v[128:131], v[112:115]
	s_add_u32 m0, s98, 0x18000
	s_waitcnt lgkmcnt(5)
	v_mfma_f32_16x16x32_bf16 v[116:119], v[160:163], v[132:135], v[116:119]
	s_waitcnt lgkmcnt(3)
	v_mfma_f32_16x16x32_bf16 v[64:67], v[160:163], v[136:139], v[64:67]
	global_load_lds_dwordx4 v208, s[26:27]
	s_waitcnt lgkmcnt(1)
	v_mfma_f32_16x16x32_bf16 v[68:71], v[160:163], v[140:143], v[68:71]
	ds_read_b128 v[180:183], v204 offset:10240
	v_mfma_f32_16x16x32_bf16 v[120:123], v[164:167], v[128:131], v[120:123]
	s_add_u32 m0, s98, 0x18400
	v_mfma_f32_16x16x32_bf16 v[124:127], v[164:167], v[132:135], v[124:127]
	v_mfma_f32_16x16x32_bf16 v[72:75], v[164:167], v[136:139], v[72:75]
	global_load_lds_dwordx4 v209, s[26:27]
	v_mfma_f32_16x16x32_bf16 v[76:79], v[164:167], v[140:143], v[76:79]
	ds_read_b128 v[184:187], v204 offset:12288
	v_mfma_f32_16x16x32_bf16 v[96:99], v[168:171], v[128:131], v[96:99]
	s_add_u32 m0, s98, 0x18800
	v_mfma_f32_16x16x32_bf16 v[100:103], v[168:171], v[132:135], v[100:103]
	v_mfma_f32_16x16x32_bf16 v[32:35], v[168:171], v[136:139], v[32:35]
	global_load_lds_dwordx4 v210, s[26:27]
	v_mfma_f32_16x16x32_bf16 v[36:39], v[168:171], v[140:143], v[36:39]
	ds_read_b128 v[188:191], v204 offset:14336
	v_mfma_f32_16x16x32_bf16 v[104:107], v[172:175], v[128:131], v[104:107]
	s_add_u32 m0, s98, 0x18c00
	v_mfma_f32_16x16x32_bf16 v[108:111], v[172:175], v[132:135], v[108:111]
	v_mfma_f32_16x16x32_bf16 v[40:43], v[172:175], v[136:139], v[40:43]
	global_load_lds_dwordx4 v211, s[26:27]
	v_mfma_f32_16x16x32_bf16 v[44:47], v[172:175], v[140:143], v[44:47]
	s_add_u32 s26, s26, 0x80
	s_addc_u32 s27, s27, 0
	s_waitcnt lgkmcnt(3)
	v_mfma_f32_16x16x32_bf16 v[80:83], v[176:179], v[128:131], v[80:83]
	v_mfma_f32_16x16x32_bf16 v[84:87], v[176:179], v[132:135], v[84:87]
	ds_read_b128 v[160:163], v205 offset:0
	v_mfma_f32_16x16x32_bf16 v[16:19], v[176:179], v[136:139], v[16:19]
	v_mfma_f32_16x16x32_bf16 v[20:23], v[176:179], v[140:143], v[20:23]
	ds_read_b128 v[144:147], v207 offset:0
	s_waitcnt lgkmcnt(4)
	v_mfma_f32_16x16x32_bf16 v[88:91], v[180:183], v[128:131], v[88:91]
	v_mfma_f32_16x16x32_bf16 v[92:95], v[180:183], v[132:135], v[92:95]
	ds_read_b128 v[164:167], v205 offset:2048
	v_mfma_f32_16x16x32_bf16 v[24:27], v[180:183], v[136:139], v[24:27]
	v_mfma_f32_16x16x32_bf16 v[28:31], v[180:183], v[140:143], v[28:31]
	ds_read_b128 v[148:151], v207 offset:2048
	s_waitcnt lgkmcnt(5)
	v_mfma_f32_16x16x32_bf16 v[48:51], v[184:187], v[128:131], v[48:51]
	v_mfma_f32_16x16x32_bf16 v[52:55], v[184:187], v[132:135], v[52:55]
	ds_read_b128 v[168:171], v205 offset:4096
	v_mfma_f32_16x16x32_bf16 v[0:3], v[184:187], v[136:139], v[0:3]
	v_mfma_f32_16x16x32_bf16 v[4:7], v[184:187], v[140:143], v[4:7]
	ds_read_b128 v[152:155], v207 offset:4096
	s_waitcnt lgkmcnt(6)
	v_mfma_f32_16x16x32_bf16 v[56:59], v[188:191], v[128:131], v[56:59]
	v_mfma_f32_16x16x32_bf16 v[60:63], v[188:191], v[132:135], v[60:63]
	ds_read_b128 v[172:175], v205 offset:6144
	v_mfma_f32_16x16x32_bf16 v[8:11], v[188:191], v[136:139], v[8:11]
	v_mfma_f32_16x16x32_bf16 v[12:15], v[188:191], v[140:143], v[12:15]
	ds_read_b128 v[156:159], v207 offset:6144
	ds_read_b128 v[176:179], v205 offset:8192
	ds_read_b128 v[180:183], v205 offset:10240
	ds_read_b128 v[184:187], v205 offset:12288
	ds_read_b128 v[188:191], v205 offset:14336
	s_waitcnt lgkmcnt(10)
	v_mfma_f32_16x16x32_bf16 v[112:115], v[160:163], v[144:147], v[112:115]
	s_waitcnt lgkmcnt(8)
	v_mfma_f32_16x16x32_bf16 v[116:119], v[160:163], v[148:151], v[116:119]
	s_waitcnt lgkmcnt(6)
	v_mfma_f32_16x16x32_bf16 v[64:67], v[160:163], v[152:155], v[64:67]
	s_waitcnt lgkmcnt(4)
	v_mfma_f32_16x16x32_bf16 v[68:71], v[160:163], v[156:159], v[68:71]
	v_mfma_f32_16x16x32_bf16 v[120:123], v[164:167], v[144:147], v[120:123]
	v_mfma_f32_16x16x32_bf16 v[124:127], v[164:167], v[148:151], v[124:127]
	v_mfma_f32_16x16x32_bf16 v[72:75], v[164:167], v[152:155], v[72:75]
	v_mfma_f32_16x16x32_bf16 v[76:79], v[164:167], v[156:159], v[76:79]
	v_mfma_f32_16x16x32_bf16 v[96:99], v[168:171], v[144:147], v[96:99]
	v_mfma_f32_16x16x32_bf16 v[100:103], v[168:171], v[148:151], v[100:103]
	v_mfma_f32_16x16x32_bf16 v[32:35], v[168:171], v[152:155], v[32:35]
	v_mfma_f32_16x16x32_bf16 v[36:39], v[168:171], v[156:159], v[36:39]
	v_mfma_f32_16x16x32_bf16 v[104:107], v[172:175], v[144:147], v[104:107]
	v_mfma_f32_16x16x32_bf16 v[108:111], v[172:175], v[148:151], v[108:111]
	v_mfma_f32_16x16x32_bf16 v[40:43], v[172:175], v[152:155], v[40:43]
	v_mfma_f32_16x16x32_bf16 v[44:47], v[172:175], v[156:159], v[44:47]
	s_waitcnt vmcnt(0) lgkmcnt(0)
	s_barrier
; DI void gemm_wide(const bf16_t* __restrict__ W, int ldw, const bf16_t* __restrict__ X, int ldx, int nkt,
;                   f32x16 (&acc)[4][2], bf16_t* lds) {
;     ...
;   __syncthreads();
;   GW_GLOAD(0)
;   GW_LSTORE(0)
;   GW_GLOAD(1)
;   GW_GLOAD_B(nkt > 2 ? 2 : nkt - 1)
;   __syncthreads();
;   for (int kt = 0; kt < nkt; kt += 2) {
;     __builtin_amdgcn_sched_barrier(0);
;     GW_ST2(1, 0, rw0, rw1)                         GW_KS(kt, 0)
;     GW_ST2(1, 128 * LDT, rw2, rw3)                 GW_KS(kt, 1)
;     GW_ST2(1, WT_E, rx0, rx1)                      GW_KS(kt, 2)
;     GW_ST2(1, WT_E + 128 * LDT, rx2, rx3)          GW_KS(kt, 3)
;     __builtin_amdgcn_sched_barrier(0);
;     GW_GLOAD(kt + 3 < nkt ? kt + 3 : nkt - 1)
;     __syncthreads();
;     __builtin_amdgcn_sched_barrier(0);
;     GW_ST2(0, 0, sw0, sw1)                         GW_KS(kt + 1, 0)
;     GW_ST2(0, 128 * LDT, sw2, sw3)                 GW_KS(kt + 1, 1)
;     GW_ST2(0, WT_E, sx0, sx1)                      GW_KS(kt + 1, 2)
;     GW_ST2(0, WT_E + 128 * LDT, sx2, sx3)          GW_KS(kt + 1, 3)
;     __builtin_amdgcn_sched_barrier(0);
;     GW_GLOAD_B(kt + 4 < nkt ? kt + 4 : nkt - 1)
;     __syncthreads();
;   }
	v_mfma_f32_16x16x32_bf16 v[80:83], v[176:179], v[144:147], v[80:83]
	v_mfma_f32_16x16x32_bf16 v[84:87], v[176:179], v[148:151], v[84:87]
	ds_read_b128 v[160:163], v204 offset:32768
	v_mfma_f32_16x16x32_bf16 v[16:19], v[176:179], v[152:155], v[16:19]
	v_mfma_f32_16x16x32_bf16 v[20:23], v[176:179], v[156:159], v[20:23]
	ds_read_b128 v[128:131], v206 offset:32768
	v_mfma_f32_16x16x32_bf16 v[88:91], v[180:183], v[144:147], v[88:91]
	v_mfma_f32_16x16x32_bf16 v[92:95], v[180:183], v[148:151], v[92:95]
	ds_read_b128 v[164:167], v204 offset:34816
	v_mfma_f32_16x16x32_bf16 v[24:27], v[180:183], v[152:155], v[24:27]
	v_mfma_f32_16x16x32_bf16 v[28:31], v[180:183], v[156:159], v[28:31]
	ds_read_b128 v[132:135], v206 offset:34816
	v_mfma_f32_16x16x32_bf16 v[48:51], v[184:187], v[144:147], v[48:51]
	v_mfma_f32_16x16x32_bf16 v[52:55], v[184:187], v[148:151], v[52:55]
	ds_read_b128 v[168:171], v204 offset:36864
	v_mfma_f32_16x16x32_bf16 v[0:3], v[184:187], v[152:155], v[0:3]
	v_mfma_f32_16x16x32_bf16 v[4:7], v[184:187], v[156:159], v[4:7]
	ds_read_b128 v[136:139], v206 offset:36864
	v_mfma_f32_16x16x32_bf16 v[56:59], v[188:191], v[144:147], v[56:59]
	v_mfma_f32_16x16x32_bf16 v[60:63], v[188:191], v[148:151], v[60:63]
	ds_read_b128 v[172:175], v204 offset:38912
	v_mfma_f32_16x16x32_bf16 v[8:11], v[188:191], v[152:155], v[8:11]
	v_mfma_f32_16x16x32_bf16 v[12:15], v[188:191], v[156:159], v[12:15]
	ds_read_b128 v[140:143], v206 offset:38912
	ds_read_b128 v[176:179], v204 offset:40960
	s_waitcnt lgkmcnt(7)
	v_mfma_f32_16x16x32_bf16 v[112:115], v[160:163], v[128:131], v[112:115]
	s_waitcnt lgkmcnt(5)
	v_mfma_f32_16x16x32_bf16 v[116:119], v[160:163], v[132:135], v[116:119]
	s_waitcnt lgkmcnt(3)
	v_mfma_f32_16x16x32_bf16 v[64:67], v[160:163], v[136:139], v[64:67]
	s_waitcnt lgkmcnt(1)
	v_mfma_f32_16x16x32_bf16 v[68:71], v[160:163], v[140:143], v[68:71]
	ds_read_b128 v[180:183], v204 offset:43008
	v_mfma_f32_16x16x32_bf16 v[120:123], v[164:167], v[128:131], v[120:123]
	v_mfma_f32_16x16x32_bf16 v[124:127], v[164:167], v[132:135], v[124:127]
	v_mfma_f32_16x16x32_bf16 v[72:75], v[164:167], v[136:139], v[72:75]
	v_mfma_f32_16x16x32_bf16 v[76:79], v[164:167], v[140:143], v[76:79]
	ds_read_b128 v[184:187], v204 offset:45056
	v_mfma_f32_16x16x32_bf16 v[96:99], v[168:171], v[128:131], v[96:99]
	v_mfma_f32_16x16x32_bf16 v[100:103], v[168:171], v[132:135], v[100:103]
	v_mfma_f32_16x16x32_bf16 v[32:35], v[168:171], v[136:139], v[32:35]
	v_mfma_f32_16x16x32_bf16 v[36:39], v[168:171], v[140:143], v[36:39]
	ds_read_b128 v[188:191], v204 offset:47104
	v_mfma_f32_16x16x32_bf16 v[104:107], v[172:175], v[128:131], v[104:107]
	v_mfma_f32_16x16x32_bf16 v[108:111], v[172:175], v[132:135], v[108:111]
	v_mfma_f32_16x16x32_bf16 v[40:43], v[172:175], v[136:139], v[40:43]
	v_mfma_f32_16x16x32_bf16 v[44:47], v[172:175], v[140:143], v[44:47]
	s_waitcnt lgkmcnt(3)
	v_mfma_f32_16x16x32_bf16 v[80:83], v[176:179], v[128:131], v[80:83]
	v_mfma_f32_16x16x32_bf16 v[84:87], v[176:179], v[132:135], v[84:87]
	ds_read_b128 v[160:163], v205 offset:32768
	v_mfma_f32_16x16x32_bf16 v[16:19], v[176:179], v[136:139], v[16:19]
	v_mfma_f32_16x16x32_bf16 v[20:23], v[176:179], v[140:143], v[20:23]
	ds_read_b128 v[144:147], v207 offset:32768
	s_waitcnt lgkmcnt(4)
	v_mfma_f32_16x16x32_bf16 v[88:91], v[180:183], v[128:131], v[88:91]
	v_mfma_f32_16x16x32_bf16 v[92:95], v[180:183], v[132:135], v[92:95]
	ds_read_b128 v[164:167], v205 offset:34816
	v_mfma_f32_16x16x32_bf16 v[24:27], v[180:183], v[136:139], v[24:27]
	v_mfma_f32_16x16x32_bf16 v[28:31], v[180:183], v[140:143], v[28:31]
	ds_read_b128 v[148:151], v207 offset:34816
	s_waitcnt lgkmcnt(5)
	v_mfma_f32_16x16x32_bf16 v[48:51], v[184:187], v[128:131], v[48:51]
	v_mfma_f32_16x16x32_bf16 v[52:55], v[184:187], v[132:135], v[52:55]
	ds_read_b128 v[168:171], v205 offset:36864
	v_mfma_f32_16x16x32_bf16 v[0:3], v[184:187], v[136:139], v[0:3]
	v_mfma_f32_16x16x32_bf16 v[4:7], v[184:187], v[140:143], v[4:7]
	ds_read_b128 v[152:155], v207 offset:36864
	s_waitcnt lgkmcnt(6)
	v_mfma_f32_16x16x32_bf16 v[56:59], v[188:191], v[128:131], v[56:59]
	v_mfma_f32_16x16x32_bf16 v[60:63], v[188:191], v[132:135], v[60:63]
	ds_read_b128 v[172:175], v205 offset:38912
	v_mfma_f32_16x16x32_bf16 v[8:11], v[188:191], v[136:139], v[8:11]
	v_mfma_f32_16x16x32_bf16 v[12:15], v[188:191], v[140:143], v[12:15]
	ds_read_b128 v[156:159], v207 offset:38912
	ds_read_b128 v[176:179], v205 offset:40960
	ds_read_b128 v[180:183], v205 offset:43008
	ds_read_b128 v[184:187], v205 offset:45056
	ds_read_b128 v[188:191], v205 offset:47104
	s_waitcnt lgkmcnt(10)
	v_mfma_f32_16x16x32_bf16 v[112:115], v[160:163], v[144:147], v[112:115]
	s_waitcnt lgkmcnt(8)
	v_mfma_f32_16x16x32_bf16 v[116:119], v[160:163], v[148:151], v[116:119]
	s_waitcnt lgkmcnt(6)
	v_mfma_f32_16x16x32_bf16 v[64:67], v[160:163], v[152:155], v[64:67]
	s_waitcnt lgkmcnt(4)
	v_mfma_f32_16x16x32_bf16 v[68:71], v[160:163], v[156:159], v[68:71]
	v_mfma_f32_16x16x32_bf16 v[120:123], v[164:167], v[144:147], v[120:123]
	v_mfma_f32_16x16x32_bf16 v[124:127], v[164:167], v[148:151], v[124:127]
	v_mfma_f32_16x16x32_bf16 v[72:75], v[164:167], v[152:155], v[72:75]
	v_mfma_f32_16x16x32_bf16 v[76:79], v[164:167], v[156:159], v[76:79]
	v_mfma_f32_16x16x32_bf16 v[96:99], v[168:171], v[144:147], v[96:99]
	v_mfma_f32_16x16x32_bf16 v[100:103], v[168:171], v[148:151], v[100:103]
	v_mfma_f32_16x16x32_bf16 v[32:35], v[168:171], v[152:155], v[32:35]
	v_mfma_f32_16x16x32_bf16 v[36:39], v[168:171], v[156:159], v[36:39]
	v_mfma_f32_16x16x32_bf16 v[104:107], v[172:175], v[144:147], v[104:107]
	v_mfma_f32_16x16x32_bf16 v[108:111], v[172:175], v[148:151], v[108:111]
	v_mfma_f32_16x16x32_bf16 v[40:43], v[172:175], v[152:155], v[40:43]
	v_mfma_f32_16x16x32_bf16 v[44:47], v[172:175], v[156:159], v[44:47]
	s_waitcnt vmcnt(0) lgkmcnt(0)
	s_barrier
; DI void gemm_wide(const bf16_t* __restrict__ W, int ldw, const bf16_t* __restrict__ X, int ldx, int nkt,
;                   f32x16 (&acc)[4][2], bf16_t* lds) {
;     ...
;   __syncthreads();
;   GW_GLOAD(0)
;   GW_LSTORE(0)
;   GW_GLOAD(1)
;   GW_GLOAD_B(nkt > 2 ? 2 : nkt - 1)
;   __syncthreads();
;   for (int kt = 0; kt < nkt; kt += 2) {
;     __builtin_amdgcn_sched_barrier(0);
;     GW_ST2(1, 0, rw0, rw1)                         GW_KS(kt, 0)
;     GW_ST2(1, 128 * LDT, rw2, rw3)                 GW_KS(kt, 1)
;     GW_ST2(1, WT_E, rx0, rx1)                      GW_KS(kt, 2)
;     GW_ST2(1, WT_E + 128 * LDT, rx2, rx3)          GW_KS(kt, 3)
;     __builtin_amdgcn_sched_barrier(0);
;     GW_GLOAD(kt + 3 < nkt ? kt + 3 : nkt - 1)
;     __syncthreads();
;     __builtin_amdgcn_sched_barrier(0);
;     GW_ST2(0, 0, sw0, sw1)                         GW_KS(kt + 1, 0)
;     GW_ST2(0, 128 * LDT, sw2, sw3)                 GW_KS(kt + 1, 1)
;     GW_ST2(0, WT_E, sx0, sx1)                      GW_KS(kt + 1, 2)
;     GW_ST2(0, WT_E + 128 * LDT, sx2, sx3)          GW_KS(kt + 1, 3)
;     __builtin_amdgcn_sched_barrier(0);
;     GW_GLOAD_B(kt + 4 < nkt ? kt + 4 : nkt - 1)
;     __syncthreads();
;   }
	v_mfma_f32_16x16x32_bf16 v[80:83], v[176:179], v[144:147], v[80:83]
	v_mfma_f32_16x16x32_bf16 v[84:87], v[176:179], v[148:151], v[84:87]
	v_mfma_f32_16x16x32_bf16 v[16:19], v[176:179], v[152:155], v[16:19]
	v_mfma_f32_16x16x32_bf16 v[20:23], v[176:179], v[156:159], v[20:23]
	v_mfma_f32_16x16x32_bf16 v[88:91], v[180:183], v[144:147], v[88:91]
	v_mfma_f32_16x16x32_bf16 v[92:95], v[180:183], v[148:151], v[92:95]
	v_mfma_f32_16x16x32_bf16 v[24:27], v[180:183], v[152:155], v[24:27]
	v_mfma_f32_16x16x32_bf16 v[28:31], v[180:183], v[156:159], v[28:31]
	v_mfma_f32_16x16x32_bf16 v[48:51], v[184:187], v[144:147], v[48:51]
	v_mfma_f32_16x16x32_bf16 v[52:55], v[184:187], v[148:151], v[52:55]
	v_mfma_f32_16x16x32_bf16 v[0:3], v[184:187], v[152:155], v[0:3]
	v_mfma_f32_16x16x32_bf16 v[4:7], v[184:187], v[156:159], v[4:7]
	v_mfma_f32_16x16x32_bf16 v[56:59], v[188:191], v[144:147], v[56:59]
	v_mfma_f32_16x16x32_bf16 v[60:63], v[188:191], v[148:151], v[60:63]
	v_mfma_f32_16x16x32_bf16 v[8:11], v[188:191], v[152:155], v[8:11]
	v_mfma_f32_16x16x32_bf16 v[12:15], v[188:191], v[156:159], v[12:15]
	s_nop 7
	v_permlane16_swap_b32_e32 v112, v116
	v_permlane16_swap_b32_e32 v113, v117
	v_permlane16_swap_b32_e32 v114, v118
	v_permlane16_swap_b32_e32 v115, v119
	v_permlane16_swap_b32_e32 v120, v124
	v_permlane16_swap_b32_e32 v121, v125
	v_permlane16_swap_b32_e32 v122, v126
	v_permlane16_swap_b32_e32 v123, v127
	v_permlane32_swap_b32_e32 v112, v116
	v_permlane32_swap_b32_e32 v113, v117
	v_permlane32_swap_b32_e32 v114, v118
	v_permlane32_swap_b32_e32 v115, v119
	v_permlane32_swap_b32_e32 v120, v124
	v_permlane32_swap_b32_e32 v121, v125
	v_permlane32_swap_b32_e32 v122, v126
	v_permlane32_swap_b32_e32 v123, v127
	v_permlane16_swap_b32_e32 v64, v68
	v_permlane16_swap_b32_e32 v65, v69
	v_permlane16_swap_b32_e32 v66, v70
	v_permlane16_swap_b32_e32 v67, v71
	v_permlane16_swap_b32_e32 v72, v76
	v_permlane16_swap_b32_e32 v73, v77
	v_permlane16_swap_b32_e32 v74, v78
	v_permlane16_swap_b32_e32 v75, v79
	v_permlane32_swap_b32_e32 v64, v68
	v_permlane32_swap_b32_e32 v65, v69
	v_permlane32_swap_b32_e32 v66, v70
	v_permlane32_swap_b32_e32 v67, v71
	v_permlane32_swap_b32_e32 v72, v76
	v_permlane32_swap_b32_e32 v73, v77
	v_permlane32_swap_b32_e32 v74, v78
	v_permlane32_swap_b32_e32 v75, v79
	v_permlane16_swap_b32_e32 v96, v100
	v_permlane16_swap_b32_e32 v97, v101
	v_permlane16_swap_b32_e32 v98, v102
	v_permlane16_swap_b32_e32 v99, v103
	v_permlane16_swap_b32_e32 v104, v108
	v_permlane16_swap_b32_e32 v105, v109
	v_permlane16_swap_b32_e32 v106, v110
	v_permlane16_swap_b32_e32 v107, v111
	v_permlane32_swap_b32_e32 v96, v100
	v_permlane32_swap_b32_e32 v97, v101
	v_permlane32_swap_b32_e32 v98, v102
	v_permlane32_swap_b32_e32 v99, v103
	v_permlane32_swap_b32_e32 v104, v108
	v_permlane32_swap_b32_e32 v105, v109
	v_permlane32_swap_b32_e32 v106, v110
	v_permlane32_swap_b32_e32 v107, v111
	v_permlane16_swap_b32_e32 v32, v36
	v_permlane16_swap_b32_e32 v33, v37
	v_permlane16_swap_b32_e32 v34, v38
	v_permlane16_swap_b32_e32 v35, v39
	v_permlane16_swap_b32_e32 v40, v44
	v_permlane16_swap_b32_e32 v41, v45
	v_permlane16_swap_b32_e32 v42, v46
	v_permlane16_swap_b32_e32 v43, v47
	v_permlane32_swap_b32_e32 v32, v36
	v_permlane32_swap_b32_e32 v33, v37
	v_permlane32_swap_b32_e32 v34, v38
	v_permlane32_swap_b32_e32 v35, v39
	v_permlane32_swap_b32_e32 v40, v44
	v_permlane32_swap_b32_e32 v41, v45
	v_permlane32_swap_b32_e32 v42, v46
	v_permlane32_swap_b32_e32 v43, v47
	v_permlane16_swap_b32_e32 v80, v84
	v_permlane16_swap_b32_e32 v81, v85
	v_permlane16_swap_b32_e32 v82, v86
	v_permlane16_swap_b32_e32 v83, v87
	v_permlane16_swap_b32_e32 v88, v92
	v_permlane16_swap_b32_e32 v89, v93
	v_permlane16_swap_b32_e32 v90, v94
	v_permlane16_swap_b32_e32 v91, v95
	v_permlane32_swap_b32_e32 v80, v84
	v_permlane32_swap_b32_e32 v81, v85
	v_permlane32_swap_b32_e32 v82, v86
	v_permlane32_swap_b32_e32 v83, v87
	v_permlane32_swap_b32_e32 v88, v92
	v_permlane32_swap_b32_e32 v89, v93
	v_permlane32_swap_b32_e32 v90, v94
	v_permlane32_swap_b32_e32 v91, v95
	v_permlane16_swap_b32_e32 v16, v20
	v_permlane16_swap_b32_e32 v17, v21
	v_permlane16_swap_b32_e32 v18, v22
	v_permlane16_swap_b32_e32 v19, v23
	v_permlane16_swap_b32_e32 v24, v28
	v_permlane16_swap_b32_e32 v25, v29
	v_permlane16_swap_b32_e32 v26, v30
	v_permlane16_swap_b32_e32 v27, v31
	v_permlane32_swap_b32_e32 v16, v20
	v_permlane32_swap_b32_e32 v17, v21
	v_permlane32_swap_b32_e32 v18, v22
	v_permlane32_swap_b32_e32 v19, v23
	v_permlane32_swap_b32_e32 v24, v28
	v_permlane32_swap_b32_e32 v25, v29
	v_permlane32_swap_b32_e32 v26, v30
	v_permlane32_swap_b32_e32 v27, v31
	v_permlane16_swap_b32_e32 v48, v52
	v_permlane16_swap_b32_e32 v49, v53
	v_permlane16_swap_b32_e32 v50, v54
	v_permlane16_swap_b32_e32 v51, v55
	v_permlane16_swap_b32_e32 v56, v60
	v_permlane16_swap_b32_e32 v57, v61
	v_permlane16_swap_b32_e32 v58, v62
	v_permlane16_swap_b32_e32 v59, v63
	v_permlane32_swap_b32_e32 v48, v52
	v_permlane32_swap_b32_e32 v49, v53
	v_permlane32_swap_b32_e32 v50, v54
	v_permlane32_swap_b32_e32 v51, v55
	v_permlane32_swap_b32_e32 v56, v60
	v_permlane32_swap_b32_e32 v57, v61
	v_permlane32_swap_b32_e32 v58, v62
	v_permlane32_swap_b32_e32 v59, v63
	v_permlane16_swap_b32_e32 v0, v4
	v_permlane16_swap_b32_e32 v1, v5
	v_permlane16_swap_b32_e32 v2, v6
	v_permlane16_swap_b32_e32 v3, v7
	v_permlane16_swap_b32_e32 v8, v12
	v_permlane16_swap_b32_e32 v9, v13
	v_permlane16_swap_b32_e32 v10, v14
	v_permlane16_swap_b32_e32 v11, v15
	v_permlane32_swap_b32_e32 v0, v4
	v_permlane32_swap_b32_e32 v1, v5
	v_permlane32_swap_b32_e32 v2, v6
	v_permlane32_swap_b32_e32 v3, v7
	v_permlane32_swap_b32_e32 v8, v12
; DI unsigned pack2(float a, float b) { f32x2_t v = {a, b}; bf16x2_t r = __builtin_convertvector(v, bf16x2_t); return __builtin_bit_cast(unsigned, r); }
; DI void phase_up(const P& p, int layer, bf16_t* sm, const Geo& ge) {
;     ...
; #pragma unroll
;     for (int mt = 0; mt < 2; ++mt) {
;       const float rs = mt ? rs1 : rs0;
; #pragma unroll
;       for (int nt = 0; nt < 4; ++nt)
; #pragma unroll
;         for (int qd = 0; qd < 4; ++qd) {
;           const int n = nt_ * 256 + wn * 128 + nt * 32 + 8 * qd + 4 * lh;
;           float a = fmaxf(acc[nt][mt][4 * qd] * rs, 0.f), b = fmaxf(acc[nt][mt][4 * qd + 1] * rs, 0.f);
;           float c = fmaxf(acc[nt][mt][4 * qd + 2] * rs, 0.f), d = fmaxf(acc[nt][mt][4 * qd + 3] * rs, 0.f);
;           *(uint2*)(stg + (mt * 32 + lr) * 136 + nt * 32 + 8 * qd + 4 * lh) = make_uint2(pack2(a * a, b * b), pack2(c * c, d * d));
;         }
;     }
	v_permlane32_swap_b32_e32 v9, v13
	v_permlane32_swap_b32_e32 v10, v14
	v_permlane32_swap_b32_e32 v11, v15
	v_mul_f32_e32 v48, v199, v48
	v_mul_f32_e32 v49, v199, v49
	v_mul_f32_e32 v50, v199, v50
	v_mul_f32_e32 v51, v199, v51
	v_max_f32_e32 v48, 0, v48
	v_max_f32_e32 v49, 0, v49
	v_max_f32_e32 v50, 0, v50
	v_max_f32_e32 v51, 0, v51
	v_pk_mul_f32 v[48:49], v[48:49], v[48:49]
	v_pk_mul_f32 v[50:51], v[50:51], v[50:51]
	v_cvt_pk_bf16_f32 v48, v48, v49
	v_cvt_pk_bf16_f32 v49, v50, v51
	v_mul_f32_e32 v50, v199, v52
	v_mul_f32_e32 v51, v199, v53
	v_mul_f32_e32 v52, v199, v54
	v_mul_f32_e32 v53, v199, v55
	v_max_f32_e32 v50, 0, v50
	v_max_f32_e32 v51, 0, v51
	v_max_f32_e32 v52, 0, v52
	v_max_f32_e32 v53, 0, v53
	v_pk_mul_f32 v[50:51], v[50:51], v[50:51]
	v_pk_mul_f32 v[52:53], v[52:53], v[52:53]
	v_cvt_pk_bf16_f32 v50, v50, v51
	v_cvt_pk_bf16_f32 v51, v52, v53
	ds_write2_b64 v219, v[48:49], v[50:51] offset0:24 offset1:26
	v_mul_f32_e32 v48, v199, v56
	v_mul_f32_e32 v49, v199, v57
	v_mul_f32_e32 v50, v199, v58
	v_mul_f32_e32 v51, v199, v59
	v_max_f32_e32 v48, 0, v48
	v_max_f32_e32 v49, 0, v49
	v_max_f32_e32 v50, 0, v50
	v_max_f32_e32 v51, 0, v51
	v_pk_mul_f32 v[48:49], v[48:49], v[48:49]
	v_pk_mul_f32 v[50:51], v[50:51], v[50:51]
	v_cvt_pk_bf16_f32 v48, v48, v49
	v_cvt_pk_bf16_f32 v49, v50, v51
	v_mul_f32_e32 v50, v199, v60
	v_mul_f32_e32 v51, v199, v61
	v_mul_f32_e32 v52, v199, v62
	v_mul_f32_e32 v53, v199, v63
	v_max_f32_e32 v50, 0, v50
	v_max_f32_e32 v51, 0, v51
	v_max_f32_e32 v52, 0, v52
	v_max_f32_e32 v53, 0, v53
	v_pk_mul_f32 v[50:51], v[50:51], v[50:51]
	v_pk_mul_f32 v[52:53], v[52:53], v[52:53]
	v_cvt_pk_bf16_f32 v50, v50, v51
	v_cvt_pk_bf16_f32 v51, v52, v53
	v_mul_f32_e32 v0, v198, v0
	v_mul_f32_e32 v1, v198, v1
	v_mul_f32_e32 v2, v198, v2
	v_mul_f32_e32 v3, v198, v3
	v_mul_f32_e32 v112, v199, v112
	v_mul_f32_e32 v113, v199, v113
	v_mul_f32_e32 v114, v199, v114
	v_mul_f32_e32 v115, v199, v115
	v_mul_f32_e32 v96, v199, v96
	v_mul_f32_e32 v97, v199, v97
	v_mul_f32_e32 v98, v199, v98
	v_mul_f32_e32 v99, v199, v99
	v_mul_f32_e32 v80, v199, v80
	v_mul_f32_e32 v81, v199, v81
	v_mul_f32_e32 v82, v199, v82
	v_mul_f32_e32 v83, v199, v83
	ds_write2_b64 v219, v[48:49], v[50:51] offset0:28 offset1:30
	v_mul_f32_e32 v48, v198, v64
	v_mul_f32_e32 v49, v198, v65
	v_mul_f32_e32 v50, v198, v66
	v_mul_f32_e32 v51, v198, v67
	v_mul_f32_e32 v32, v198, v32
	v_mul_f32_e32 v33, v198, v33
	v_mul_f32_e32 v34, v198, v34
	v_mul_f32_e32 v35, v198, v35
	v_mul_f32_e32 v16, v198, v16
	v_mul_f32_e32 v17, v198, v17
	v_mul_f32_e32 v18, v198, v18
	v_mul_f32_e32 v19, v198, v19
	v_max_f32_e32 v0, 0, v0
	v_max_f32_e32 v1, 0, v1
	v_max_f32_e32 v2, 0, v2
	v_max_f32_e32 v3, 0, v3
	v_max_f32_e32 v112, 0, v112
	v_max_f32_e32 v113, 0, v113
	v_max_f32_e32 v114, 0, v114
	v_max_f32_e32 v115, 0, v115
	v_max_f32_e32 v96, 0, v96
	v_max_f32_e32 v97, 0, v97
	v_max_f32_e32 v98, 0, v98
	v_max_f32_e32 v99, 0, v99
	v_max_f32_e32 v80, 0, v80
	v_max_f32_e32 v81, 0, v81
	v_max_f32_e32 v82, 0, v82
	v_max_f32_e32 v83, 0, v83
	v_max_f32_e32 v48, 0, v48
	v_max_f32_e32 v49, 0, v49
	v_max_f32_e32 v50, 0, v50
	v_max_f32_e32 v51, 0, v51
	v_max_f32_e32 v32, 0, v32
	v_max_f32_e32 v33, 0, v33
	v_max_f32_e32 v34, 0, v34
	v_max_f32_e32 v35, 0, v35
	v_max_f32_e32 v16, 0, v16
	v_max_f32_e32 v17, 0, v17
	v_max_f32_e32 v18, 0, v18
	v_max_f32_e32 v19, 0, v19
	v_pk_mul_f32 v[0:1], v[0:1], v[0:1]
	v_pk_mul_f32 v[2:3], v[2:3], v[2:3]
	v_pk_mul_f32 v[112:113], v[112:113], v[112:113]
	v_pk_mul_f32 v[114:115], v[114:115], v[114:115]
	v_pk_mul_f32 v[96:97], v[96:97], v[96:97]
	v_pk_mul_f32 v[98:99], v[98:99], v[98:99]
	v_pk_mul_f32 v[80:81], v[80:81], v[80:81]
	v_pk_mul_f32 v[82:83], v[82:83], v[82:83]
	v_pk_mul_f32 v[48:49], v[48:49], v[48:49]
	v_pk_mul_f32 v[50:51], v[50:51], v[50:51]
	v_pk_mul_f32 v[32:33], v[32:33], v[32:33]
	v_pk_mul_f32 v[34:35], v[34:35], v[34:35]
	v_pk_mul_f32 v[16:17], v[16:17], v[16:17]
	v_pk_mul_f32 v[18:19], v[18:19], v[18:19]
	v_cvt_pk_bf16_f32 v0, v0, v1
	v_cvt_pk_bf16_f32 v1, v2, v3
	v_mul_f32_e32 v2, v198, v4
	v_mul_f32_e32 v3, v198, v5
	v_mul_f32_e32 v4, v198, v6
	v_mul_f32_e32 v5, v198, v7
	v_cvt_pk_bf16_f32 v112, v112, v113
	v_cvt_pk_bf16_f32 v113, v114, v115
	v_mul_f32_e32 v114, v199, v116
	v_mul_f32_e32 v115, v199, v117
	v_mul_f32_e32 v116, v199, v118
	v_mul_f32_e32 v117, v199, v119
	v_cvt_pk_bf16_f32 v96, v96, v97
	v_cvt_pk_bf16_f32 v97, v98, v99
	v_mul_f32_e32 v98, v199, v100
	v_mul_f32_e32 v99, v199, v101
	v_mul_f32_e32 v100, v199, v102
	v_mul_f32_e32 v101, v199, v103
	v_cvt_pk_bf16_f32 v80, v80, v81
	v_cvt_pk_bf16_f32 v81, v82, v83
	v_mul_f32_e32 v82, v199, v84
	v_mul_f32_e32 v83, v199, v85
	v_mul_f32_e32 v84, v199, v86
	v_mul_f32_e32 v85, v199, v87
	v_cvt_pk_bf16_f32 v48, v48, v49
	v_cvt_pk_bf16_f32 v49, v50, v51
	v_mul_f32_e32 v50, v198, v68
	v_mul_f32_e32 v51, v198, v69
	v_mul_f32_e32 v52, v198, v70
	v_mul_f32_e32 v53, v198, v71
	v_cvt_pk_bf16_f32 v32, v32, v33
	v_cvt_pk_bf16_f32 v33, v34, v35
	v_mul_f32_e32 v34, v198, v36
	v_mul_f32_e32 v35, v198, v37
	v_mul_f32_e32 v36, v198, v38
	v_mul_f32_e32 v37, v198, v39
	v_cvt_pk_bf16_f32 v16, v16, v17
	v_cvt_pk_bf16_f32 v17, v18, v19
	v_mul_f32_e32 v18, v198, v20
	v_mul_f32_e32 v19, v198, v21
	v_mul_f32_e32 v20, v198, v22
	v_mul_f32_e32 v21, v198, v23
	v_max_f32_e32 v2, 0, v2
	v_max_f32_e32 v3, 0, v3
	v_max_f32_e32 v4, 0, v4
	v_max_f32_e32 v5, 0, v5
	v_max_f32_e32 v114, 0, v114
	v_max_f32_e32 v115, 0, v115
	v_max_f32_e32 v116, 0, v116
	v_max_f32_e32 v117, 0, v117
	v_max_f32_e32 v98, 0, v98
	v_max_f32_e32 v99, 0, v99
	v_max_f32_e32 v100, 0, v100
	v_max_f32_e32 v101, 0, v101
	v_max_f32_e32 v82, 0, v82
	v_max_f32_e32 v83, 0, v83
; DI unsigned pack2(float a, float b) { f32x2_t v = {a, b}; bf16x2_t r = __builtin_convertvector(v, bf16x2_t); return __builtin_bit_cast(unsigned, r); }
; DI void phase_up(const P& p, int layer, bf16_t* sm, const Geo& ge) {
;     ...
; #pragma unroll
;     for (int mt = 0; mt < 2; ++mt) {
;       const float rs = mt ? rs1 : rs0;
; #pragma unroll
;       for (int nt = 0; nt < 4; ++nt)
; #pragma unroll
;         for (int qd = 0; qd < 4; ++qd) {
;           const int n = nt_ * 256 + wn * 128 + nt * 32 + 8 * qd + 4 * lh;
;           float a = fmaxf(acc[nt][mt][4 * qd] * rs, 0.f), b = fmaxf(acc[nt][mt][4 * qd + 1] * rs, 0.f);
;           float c = fmaxf(acc[nt][mt][4 * qd + 2] * rs, 0.f), d = fmaxf(acc[nt][mt][4 * qd + 3] * rs, 0.f);
;           *(uint2*)(stg + (mt * 32 + lr) * 136 + nt * 32 + 8 * qd + 4 * lh) = make_uint2(pack2(a * a, b * b), pack2(c * c, d * d));
;         }
;     }
	v_max_f32_e32 v84, 0, v84
	v_max_f32_e32 v85, 0, v85
	v_max_f32_e32 v50, 0, v50
	v_max_f32_e32 v51, 0, v51
	v_max_f32_e32 v52, 0, v52
	v_max_f32_e32 v53, 0, v53
	v_max_f32_e32 v34, 0, v34
	v_max_f32_e32 v35, 0, v35
	v_max_f32_e32 v36, 0, v36
	v_max_f32_e32 v37, 0, v37
	v_max_f32_e32 v18, 0, v18
	v_max_f32_e32 v19, 0, v19
	v_max_f32_e32 v20, 0, v20
	v_max_f32_e32 v21, 0, v21
	v_pk_mul_f32 v[2:3], v[2:3], v[2:3]
	v_pk_mul_f32 v[4:5], v[4:5], v[4:5]
	v_pk_mul_f32 v[114:115], v[114:115], v[114:115]
	v_pk_mul_f32 v[116:117], v[116:117], v[116:117]
	v_pk_mul_f32 v[98:99], v[98:99], v[98:99]
	v_pk_mul_f32 v[100:101], v[100:101], v[100:101]
	v_pk_mul_f32 v[82:83], v[82:83], v[82:83]
	v_pk_mul_f32 v[84:85], v[84:85], v[84:85]
	v_pk_mul_f32 v[50:51], v[50:51], v[50:51]
	v_pk_mul_f32 v[52:53], v[52:53], v[52:53]
	v_add_u32_e32 v54, 0x2000, v219
	v_pk_mul_f32 v[34:35], v[34:35], v[34:35]
	v_pk_mul_f32 v[36:37], v[36:37], v[36:37]
	v_pk_mul_f32 v[18:19], v[18:19], v[18:19]
	v_pk_mul_f32 v[20:21], v[20:21], v[20:21]
	v_cvt_pk_bf16_f32 v2, v2, v3
	v_cvt_pk_bf16_f32 v3, v4, v5
	v_cvt_pk_bf16_f32 v114, v114, v115
	v_cvt_pk_bf16_f32 v115, v116, v117
	v_cvt_pk_bf16_f32 v98, v98, v99
	v_cvt_pk_bf16_f32 v99, v100, v101
	v_cvt_pk_bf16_f32 v82, v82, v83
	v_cvt_pk_bf16_f32 v83, v84, v85
	v_cvt_pk_bf16_f32 v50, v50, v51
	v_cvt_pk_bf16_f32 v51, v52, v53
	v_cvt_pk_bf16_f32 v34, v34, v35
	v_cvt_pk_bf16_f32 v35, v36, v37
	v_cvt_pk_bf16_f32 v18, v18, v19
	v_cvt_pk_bf16_f32 v19, v20, v21
	ds_write2_b64 v54, v[0:1], v[2:3] offset0:88 offset1:90
	v_mul_f32_e32 v0, v198, v8
	v_mul_f32_e32 v1, v198, v9
	v_mul_f32_e32 v2, v198, v10
	v_mul_f32_e32 v3, v198, v11
	ds_write2_b64 v219, v[112:113], v[114:115] offset1:2
	v_mul_f32_e32 v112, v199, v120
	v_mul_f32_e32 v113, v199, v121
	v_mul_f32_e32 v114, v199, v122
	v_mul_f32_e32 v115, v199, v123
	ds_write2_b64 v219, v[96:97], v[98:99] offset0:8 offset1:10
	v_mul_f32_e32 v96, v199, v104
	v_mul_f32_e32 v97, v199, v105
	v_mul_f32_e32 v98, v199, v106
	v_mul_f32_e32 v99, v199, v107
	ds_write2_b64 v219, v[80:81], v[82:83] offset0:16 offset1:18
	v_mul_f32_e32 v80, v199, v88
	v_mul_f32_e32 v81, v199, v89
	v_mul_f32_e32 v82, v199, v90
	v_mul_f32_e32 v83, v199, v91
	ds_write2_b64 v54, v[48:49], v[50:51] offset0:64 offset1:66
	v_mul_f32_e32 v48, v198, v72
	v_mul_f32_e32 v49, v198, v73
	v_mul_f32_e32 v50, v198, v74
	v_mul_f32_e32 v51, v198, v75
	ds_write2_b64 v54, v[32:33], v[34:35] offset0:72 offset1:74
	v_mul_f32_e32 v32, v198, v40
	v_mul_f32_e32 v33, v198, v41
	v_mul_f32_e32 v34, v198, v42
	v_mul_f32_e32 v35, v198, v43
	ds_write2_b64 v54, v[16:17], v[18:19] offset0:80 offset1:82
	v_mul_f32_e32 v16, v198, v24
	v_mul_f32_e32 v17, v198, v25
	v_mul_f32_e32 v18, v198, v26
	v_mul_f32_e32 v19, v198, v27
	v_max_f32_e32 v0, 0, v0
	v_max_f32_e32 v1, 0, v1
	v_max_f32_e32 v2, 0, v2
	v_max_f32_e32 v3, 0, v3
	v_max_f32_e32 v112, 0, v112
	v_max_f32_e32 v113, 0, v113
	v_max_f32_e32 v114, 0, v114
	v_max_f32_e32 v115, 0, v115
	v_max_f32_e32 v96, 0, v96
	v_max_f32_e32 v97, 0, v97
	v_max_f32_e32 v98, 0, v98
	v_max_f32_e32 v99, 0, v99
	v_max_f32_e32 v80, 0, v80
	v_max_f32_e32 v81, 0, v81
	v_max_f32_e32 v82, 0, v82
	v_max_f32_e32 v83, 0, v83
	v_max_f32_e32 v48, 0, v48
	v_max_f32_e32 v49, 0, v49
	v_max_f32_e32 v50, 0, v50
	v_max_f32_e32 v51, 0, v51
	v_max_f32_e32 v32, 0, v32
	v_max_f32_e32 v33, 0, v33
	v_max_f32_e32 v34, 0, v34
	v_max_f32_e32 v35, 0, v35
	v_max_f32_e32 v16, 0, v16
	v_max_f32_e32 v17, 0, v17
	v_max_f32_e32 v18, 0, v18
	v_max_f32_e32 v19, 0, v19
	v_pk_mul_f32 v[0:1], v[0:1], v[0:1]
	v_pk_mul_f32 v[2:3], v[2:3], v[2:3]
	v_pk_mul_f32 v[112:113], v[112:113], v[112:113]
	v_pk_mul_f32 v[114:115], v[114:115], v[114:115]
	v_pk_mul_f32 v[96:97], v[96:97], v[96:97]
	v_pk_mul_f32 v[98:99], v[98:99], v[98:99]
	v_pk_mul_f32 v[80:81], v[80:81], v[80:81]
	v_pk_mul_f32 v[82:83], v[82:83], v[82:83]
	v_pk_mul_f32 v[48:49], v[48:49], v[48:49]
	v_pk_mul_f32 v[50:51], v[50:51], v[50:51]
	v_pk_mul_f32 v[32:33], v[32:33], v[32:33]
	v_pk_mul_f32 v[34:35], v[34:35], v[34:35]
	v_pk_mul_f32 v[16:17], v[16:17], v[16:17]
	v_pk_mul_f32 v[18:19], v[18:19], v[18:19]
	v_cvt_pk_bf16_f32 v0, v0, v1
	v_cvt_pk_bf16_f32 v1, v2, v3
	v_mul_f32_e32 v2, v198, v12
	v_mul_f32_e32 v3, v198, v13
	v_mul_f32_e32 v4, v198, v14
	v_mul_f32_e32 v5, v198, v15
	v_cvt_pk_bf16_f32 v112, v112, v113
	v_cvt_pk_bf16_f32 v113, v114, v115
	v_mul_f32_e32 v114, v199, v124
	v_mul_f32_e32 v115, v199, v125
	v_mul_f32_e32 v116, v199, v126
	v_mul_f32_e32 v117, v199, v127
	v_cvt_pk_bf16_f32 v96, v96, v97
	v_cvt_pk_bf16_f32 v97, v98, v99
	v_mul_f32_e32 v98, v199, v108
	v_mul_f32_e32 v99, v199, v109
	v_mul_f32_e32 v100, v199, v110
	v_mul_f32_e32 v101, v199, v111
	v_cvt_pk_bf16_f32 v80, v80, v81
	v_cvt_pk_bf16_f32 v81, v82, v83
	v_mul_f32_e32 v82, v199, v92
	v_mul_f32_e32 v83, v199, v93
	v_mul_f32_e32 v84, v199, v94
	v_mul_f32_e32 v85, v199, v95
	v_cvt_pk_bf16_f32 v48, v48, v49
	v_cvt_pk_bf16_f32 v49, v50, v51
	v_mul_f32_e32 v50, v198, v76
	v_mul_f32_e32 v51, v198, v77
	v_mul_f32_e32 v52, v198, v78
	v_mul_f32_e32 v53, v198, v79
	v_cvt_pk_bf16_f32 v32, v32, v33
	v_cvt_pk_bf16_f32 v33, v34, v35
	v_mul_f32_e32 v34, v198, v44
	v_mul_f32_e32 v35, v198, v45
	v_mul_f32_e32 v36, v198, v46
	v_mul_f32_e32 v37, v198, v47
	v_cvt_pk_bf16_f32 v16, v16, v17
	v_cvt_pk_bf16_f32 v17, v18, v19
	v_mul_f32_e32 v18, v198, v28
	v_mul_f32_e32 v19, v198, v29
	v_mul_f32_e32 v20, v198, v30
	v_mul_f32_e32 v21, v198, v31
	v_max_f32_e32 v2, 0, v2
	v_max_f32_e32 v3, 0, v3
	v_max_f32_e32 v4, 0, v4
	v_max_f32_e32 v5, 0, v5
; DI int tidx() { int t = threadIdx.x; asm volatile("" : "+v"(t)); return t; }
; DI unsigned pack2(float a, float b) { f32x2_t v = {a, b}; bf16x2_t r = __builtin_convertvector(v, bf16x2_t); return __builtin_bit_cast(unsigned, r); }
; template <bool NT = false>
; DI void stage_rows_store(const bf16_t* stg, bf16_t* dst, size_t ldd, int m0w) {
;   const int lane = tidx() & 63;
; #pragma unroll
;   for (int it = 0; it < 16; ++it) {
;     const int row = it * 4 + (lane >> 4), c16 = lane & 15;
;     const u32x4 v = *(const u32x4*)(stg + row * 136 + c16 * 8);
;     u32x4* d = (u32x4*)(dst + (size_t)(m0w + row) * ldd + c16 * 8);
;     if (NT) __builtin_nontemporal_store(v, d);
;     else *d = v;
;   }
; DI void phase_up(const P& p, int layer, bf16_t* sm, const Geo& ge) {
;     ...
; #pragma unroll
;     for (int mt = 0; mt < 2; ++mt) {
;       const float rs = mt ? rs1 : rs0;
; #pragma unroll
;       for (int nt = 0; nt < 4; ++nt)
; #pragma unroll
;         for (int qd = 0; qd < 4; ++qd) {
;           const int n = nt_ * 256 + wn * 128 + nt * 32 + 8 * qd + 4 * lh;
;           float a = fmaxf(acc[nt][mt][4 * qd] * rs, 0.f), b = fmaxf(acc[nt][mt][4 * qd + 1] * rs, 0.f);
;           float c = fmaxf(acc[nt][mt][4 * qd + 2] * rs, 0.f), d = fmaxf(acc[nt][mt][4 * qd + 3] * rs, 0.f);
;           *(uint2*)(stg + (mt * 32 + lr) * 136 + nt * 32 + 8 * qd + 4 * lh) = make_uint2(pack2(a * a, b * b), pack2(c * c, d * d));
;         }
;     }
;     stage_rows_store<false>(stg, u + nt_ * 256 + wn * 128, LDK4, mt_ * 256 + wm * 64);
	v_max_f32_e32 v114, 0, v114
	v_max_f32_e32 v115, 0, v115
	v_max_f32_e32 v116, 0, v116
	v_max_f32_e32 v117, 0, v117
	v_max_f32_e32 v98, 0, v98
	v_max_f32_e32 v99, 0, v99
	v_max_f32_e32 v100, 0, v100
	v_max_f32_e32 v101, 0, v101
	v_max_f32_e32 v82, 0, v82
	v_max_f32_e32 v83, 0, v83
	v_max_f32_e32 v84, 0, v84
	v_max_f32_e32 v85, 0, v85
	v_max_f32_e32 v50, 0, v50
	v_max_f32_e32 v51, 0, v51
	v_max_f32_e32 v52, 0, v52
	v_max_f32_e32 v53, 0, v53
	v_max_f32_e32 v34, 0, v34
	v_max_f32_e32 v35, 0, v35
	v_max_f32_e32 v36, 0, v36
	v_max_f32_e32 v37, 0, v37
	v_max_f32_e32 v18, 0, v18
	v_max_f32_e32 v19, 0, v19
	v_max_f32_e32 v20, 0, v20
	v_max_f32_e32 v21, 0, v21
	v_pk_mul_f32 v[2:3], v[2:3], v[2:3]
	v_pk_mul_f32 v[4:5], v[4:5], v[4:5]
	v_pk_mul_f32 v[114:115], v[114:115], v[114:115]
	v_pk_mul_f32 v[116:117], v[116:117], v[116:117]
	v_pk_mul_f32 v[98:99], v[98:99], v[98:99]
	v_pk_mul_f32 v[100:101], v[100:101], v[100:101]
	v_pk_mul_f32 v[82:83], v[82:83], v[82:83]
	v_pk_mul_f32 v[84:85], v[84:85], v[84:85]
	v_pk_mul_f32 v[50:51], v[50:51], v[50:51]
	v_pk_mul_f32 v[52:53], v[52:53], v[52:53]
	v_pk_mul_f32 v[34:35], v[34:35], v[34:35]
	v_pk_mul_f32 v[36:37], v[36:37], v[36:37]
	v_pk_mul_f32 v[18:19], v[18:19], v[18:19]
	v_pk_mul_f32 v[20:21], v[20:21], v[20:21]
	v_cvt_pk_bf16_f32 v2, v2, v3
	v_cvt_pk_bf16_f32 v3, v4, v5
	v_cvt_pk_bf16_f32 v114, v114, v115
	v_cvt_pk_bf16_f32 v115, v116, v117
	v_cvt_pk_bf16_f32 v98, v98, v99
	v_cvt_pk_bf16_f32 v99, v100, v101
	v_cvt_pk_bf16_f32 v82, v82, v83
	v_cvt_pk_bf16_f32 v83, v84, v85
	v_cvt_pk_bf16_f32 v50, v50, v51
	v_cvt_pk_bf16_f32 v51, v52, v53
	v_cvt_pk_bf16_f32 v34, v34, v35
	v_cvt_pk_bf16_f32 v35, v36, v37
	v_cvt_pk_bf16_f32 v18, v18, v19
	v_cvt_pk_bf16_f32 v19, v20, v21
	ds_write2_b64 v54, v[0:1], v[2:3] offset0:92 offset1:94
	v_mov_b32_e32 v2, v195
	ds_write2_b64 v219, v[112:113], v[114:115] offset0:4 offset1:6
	ds_write2_b64 v219, v[96:97], v[98:99] offset0:12 offset1:14
	ds_write2_b64 v219, v[80:81], v[82:83] offset0:20 offset1:22
	ds_write2_b64 v54, v[48:49], v[50:51] offset0:68 offset1:70
	ds_write2_b64 v54, v[32:33], v[34:35] offset0:76 offset1:78
	ds_write2_b64 v54, v[16:17], v[18:19] offset0:84 offset1:86
	s_lshl_b32 s0, s0, 8
	s_ashr_i32 s1, s0, 31
	v_bfe_u32 v5, v2, 4, 2
	v_lshlrev_b32_e32 v2, 4, v2
	v_lshl_add_u64 v[0:1], s[0:1], 1, v[196:197]
	v_and_b32_e32 v192, 0xf0, v2
	v_lshl_add_u64 v[8:9], v[0:1], 0, v[192:193]
	v_mul_u32_u24_e32 v0, 0x110, v5
	v_add3_u32 v12, v218, v192, v0
	ds_read_b128 v[0:3], v12
	v_lshl_add_u32 v4, s6, 8, v216
	v_or_b32_e32 v13, v5, v4
	ds_read_b128 v[4:7], v12 offset:1088
	v_mad_i64_i32 v[10:11], s[0:1], v13, s24, v[8:9]
	s_waitcnt lgkmcnt(1)
	global_store_dwordx4 v[10:11], v[0:3], off
	s_add_i32 s5, s5, s10
	s_nop 0
	v_or_b32_e32 v0, 4, v13
	v_mad_i64_i32 v[0:1], s[0:1], v0, s24, v[8:9]
	s_waitcnt lgkmcnt(0)
	global_store_dwordx4 v[0:1], v[4:7], off
	ds_read_b128 v[0:3], v12 offset:2176
	s_nop 0
	v_or_b32_e32 v4, 8, v13
	v_mad_i64_i32 v[10:11], s[0:1], v4, s24, v[8:9]
	ds_read_b128 v[4:7], v12 offset:3264
	s_waitcnt lgkmcnt(1)
	global_store_dwordx4 v[10:11], v[0:3], off
	s_nop 1
	v_or_b32_e32 v0, 12, v13
	v_mad_i64_i32 v[0:1], s[0:1], v0, s24, v[8:9]
	s_waitcnt lgkmcnt(0)
	global_store_dwordx4 v[0:1], v[4:7], off
	ds_read_b128 v[0:3], v12 offset:4352
	s_nop 0
	v_or_b32_e32 v4, 16, v13
	v_mad_i64_i32 v[10:11], s[0:1], v4, s24, v[8:9]
	ds_read_b128 v[4:7], v12 offset:5440
	s_waitcnt lgkmcnt(1)
	global_store_dwordx4 v[10:11], v[0:3], off
	s_nop 1
	v_or_b32_e32 v0, 20, v13
	v_mad_i64_i32 v[0:1], s[0:1], v0, s24, v[8:9]
	s_waitcnt lgkmcnt(0)
	global_store_dwordx4 v[0:1], v[4:7], off
	ds_read_b128 v[0:3], v12 offset:6528
	s_nop 0
	v_or_b32_e32 v4, 24, v13
	v_mad_i64_i32 v[10:11], s[0:1], v4, s24, v[8:9]
	ds_read_b128 v[4:7], v12 offset:7616
	s_waitcnt lgkmcnt(1)
	global_store_dwordx4 v[10:11], v[0:3], off
	s_nop 1
	v_or_b32_e32 v0, 28, v13
	v_mad_i64_i32 v[0:1], s[0:1], v0, s24, v[8:9]
	s_waitcnt lgkmcnt(0)
	global_store_dwordx4 v[0:1], v[4:7], off
	ds_read_b128 v[0:3], v12 offset:8704
	s_nop 0
	v_or_b32_e32 v4, 32, v13
	v_mad_i64_i32 v[10:11], s[0:1], v4, s24, v[8:9]
	ds_read_b128 v[4:7], v12 offset:9792
	s_waitcnt lgkmcnt(1)
	global_store_dwordx4 v[10:11], v[0:3], off
	s_nop 1
	v_or_b32_e32 v0, 36, v13
	v_mad_i64_i32 v[0:1], s[0:1], v0, s24, v[8:9]
	s_waitcnt lgkmcnt(0)
	global_store_dwordx4 v[0:1], v[4:7], off
	ds_read_b128 v[0:3], v12 offset:10880
	s_nop 0
	v_or_b32_e32 v4, 40, v13
	v_mad_i64_i32 v[10:11], s[0:1], v4, s24, v[8:9]
	ds_read_b128 v[4:7], v12 offset:11968
	s_waitcnt lgkmcnt(1)
	global_store_dwordx4 v[10:11], v[0:3], off
	s_nop 1
	v_or_b32_e32 v0, 44, v13
	v_mad_i64_i32 v[0:1], s[0:1], v0, s24, v[8:9]
	s_waitcnt lgkmcnt(0)
	global_store_dwordx4 v[0:1], v[4:7], off
	ds_read_b128 v[0:3], v12 offset:13056
	s_nop 0
	v_or_b32_e32 v4, 48, v13
	v_mad_i64_i32 v[10:11], s[0:1], v4, s24, v[8:9]
	ds_read_b128 v[4:7], v12 offset:14144
	s_waitcnt lgkmcnt(1)
	global_store_dwordx4 v[10:11], v[0:3], off
	s_nop 1
	v_or_b32_e32 v0, 52, v13
	v_mad_i64_i32 v[0:1], s[0:1], v0, s24, v[8:9]
	s_waitcnt lgkmcnt(0)
	global_store_dwordx4 v[0:1], v[4:7], off
	ds_read_b128 v[0:3], v12 offset:15232
	s_nop 0
	v_or_b32_e32 v4, 56, v13
	v_mad_i64_i32 v[10:11], s[0:1], v4, s24, v[8:9]
	ds_read_b128 v[4:7], v12 offset:16320
	s_waitcnt lgkmcnt(1)
	global_store_dwordx4 v[10:11], v[0:3], off
	s_nop 1
	v_or_b32_e32 v0, 60, v13
	v_mad_i64_i32 v[0:1], s[0:1], v0, s24, v[8:9]
	s_waitcnt lgkmcnt(0)
	global_store_dwordx4 v[0:1], v[4:7], off
	s_branch .LBB0_1140

; DI int tidx() { int t = threadIdx.x; asm volatile("" : "+v"(t)); return t; }
; DI void gemm_wide(const bf16_t* __restrict__ W, int ldw, const bf16_t* __restrict__ X, int ldx, int nkt,
;                   f32x16 (&acc)[4][2], bf16_t* lds) {
;   const int tid = tidx(), lane = tid & 63, wv = tid >> 6, wn = wv & 1, wm = wv >> 1;
;   const int lr = lane & 31, lh = lane >> 5;
;   const int lrow = tid >> 3, lkc = (tid & 7) * 8;
;   const bf16_t* wp = W + (size_t)lrow * ldw + lkc;
;   const bf16_t* xp = X + (size_t)lrow * ldx + lkc;
;   const size_t wst = (size_t)64 * ldw, xst = (size_t)64 * ldx;
;   u32x4 rw0, rw1, rw2, rw3, rx0, rx1, rx2, rx3;
;     ...
;   u32x4 sw0, sw1, sw2, sw3, sx0, sx1, sx2, sx3;
;     ...
;   __syncthreads();
;   GW_GLOAD(0)
;   GW_LSTORE(0)
;   GW_GLOAD(1)
;   GW_GLOAD_B(nkt > 2 ? 2 : nkt - 1)
;   __syncthreads();
; DI void phase_resid(const P& p, const bf16_t* W, const bf16_t* X, int K, bf16_t* sm, const Geo& ge, bool last) {
;     ...
;   while (tw.next(mt_, nt_)) {
;     f32x16 acc[4][2]; zero_acc8(acc);
;     const int ldk = K + 64;
;     gemm_wide(W + (size_t)nt_ * 256 * ldk, ldk, X + (size_t)mt_ * 256 * ldk, ldk, K / 64, acc, sm);
.LBB0_1161:
	s_cmp_gt_i32 s27, 63
	s_cselect_b64 s[6:7], -1, 0
	s_cmp_lt_i32 s27, 64
	s_mov_b64 s[4:5], -1
	s_mov_b32 s8, s54
	s_cbranch_scc0 .LBB0_1181
	s_ashr_i32 s8, s27, 3
	s_cmp_lt_i32 s8, 4
	s_cbranch_scc0 .LBB0_1199
	s_and_b32 s5, s27, 7
	s_or_b32 s4, s5, s55
	s_mul_i32 s28, s8, 0x208000
	s_mul_hi_i32 s9, s8, 0x208000
	s_add_u32 s28, s25, s28
	s_addc_u32 s29, s26, s9
	s_mul_i32 s9, s4, 0x208000
	s_add_u32 s30, s58, s9
	s_addc_u32 s31, s59, 0
	v_and_b32_e32 v128, 63, v195
	v_lshrrev_b32_e32 v129, 6, v195
	v_and_b32_e32 v130, 15, v128
	v_lshrrev_b32_e32 v131, 4, v128
	v_bfe_u32 v132, v130, 1, 3
	v_lshlrev_b32_e32 v133, 7, v130
	v_xor_b32_e32 v134, v131, v132
	v_lshl_add_u32 v135, v134, 4, v133
	v_and_b32_e32 v136, 1, v129
	v_lshlrev_b32_e32 v136, 14, v136
	v_lshrrev_b32_e32 v137, 1, v129
	v_lshlrev_b32_e32 v137, 13, v137
	v_add_u32_e32 v137, 0x10000, v137
	v_readfirstlane_b32 s98, v129
	v_add_u32_e32 v204, v136, v135
	v_xor_b32_e32 v205, 64, v204
	v_add_u32_e32 v206, v137, v135
	v_xor_b32_e32 v207, 64, v206
	s_lshl_b32 s98, s98, 12
	s_movk_i32 s100, 8320
	v_lshrrev_b32_e32 v138, 3, v128
	v_lshl_add_u32 v138, v129, 5, v138
	v_mul_lo_u32 v139, v138, s100
	v_and_b32_e32 v140, 7, v128
	v_lshrrev_b32_e32 v141, 4, v128
	v_xor_b32_e32 v142, v140, v141
	v_xor_b32_e32 v143, 4, v142
	v_lshl_add_u32 v208, v142, 4, v139
	v_lshl_add_u32 v209, v143, 4, v139
	v_add_u32_e32 v209, 0x10400, v209
	v_add_u32_e32 v210, 0x20800, v208
	v_add_u32_e32 v211, 0x20800, v209
	s_barrier
	s_mov_b32 m0, s98
	s_nop 0
	global_load_lds_dwordx4 v208, s[28:29]
	s_add_u32 m0, s98, 0x400
	s_nop 0
	global_load_lds_dwordx4 v209, s[28:29]
	s_add_u32 m0, s98, 0x800
	s_nop 0
	global_load_lds_dwordx4 v210, s[28:29]
	s_add_u32 m0, s98, 0xc00
	s_nop 0
	global_load_lds_dwordx4 v211, s[28:29]
	s_add_u32 s28, s28, 0x80
	s_addc_u32 s29, s29, 0
	s_add_u32 m0, s98, 0x10000
	s_nop 0
	global_load_lds_dwordx4 v208, s[30:31]
	s_add_u32 m0, s98, 0x10400
	s_nop 0
	global_load_lds_dwordx4 v209, s[30:31]
	s_add_u32 m0, s98, 0x10800
	s_nop 0
	global_load_lds_dwordx4 v210, s[30:31]
	s_add_u32 m0, s98, 0x10c00
	s_nop 0
	global_load_lds_dwordx4 v211, s[30:31]
	s_add_u32 s30, s30, 0x80
	s_addc_u32 s31, s31, 0
	s_add_u32 m0, s98, 0x8000
	s_nop 0
	global_load_lds_dwordx4 v208, s[28:29]
	s_add_u32 m0, s98, 0x8400
	s_nop 0
	global_load_lds_dwordx4 v209, s[28:29]
	s_add_u32 m0, s98, 0x8800
	s_nop 0
	global_load_lds_dwordx4 v210, s[28:29]
	s_add_u32 m0, s98, 0x8c00
	s_nop 0
	global_load_lds_dwordx4 v211, s[28:29]
	s_add_u32 s28, s28, 0x80
	s_addc_u32 s29, s29, 0
	v_mov_b64_e32 v[112:113], 0
	v_mov_b64_e32 v[114:115], 0
	v_mov_b64_e32 v[116:117], 0
	v_mov_b64_e32 v[118:119], 0
	v_mov_b64_e32 v[120:121], 0
	v_mov_b64_e32 v[122:123], 0
	v_mov_b64_e32 v[124:125], 0
	v_mov_b64_e32 v[126:127], 0
	v_mov_b64_e32 v[80:81], 0
	v_mov_b64_e32 v[82:83], 0
	v_mov_b64_e32 v[84:85], 0
	v_mov_b64_e32 v[86:87], 0
	v_mov_b64_e32 v[88:89], 0
	v_mov_b64_e32 v[90:91], 0
	v_mov_b64_e32 v[92:93], 0
	v_mov_b64_e32 v[94:95], 0
	v_mov_b64_e32 v[96:97], 0
	v_mov_b64_e32 v[98:99], 0
	v_mov_b64_e32 v[100:101], 0
	v_mov_b64_e32 v[102:103], 0
	v_mov_b64_e32 v[104:105], 0
	v_mov_b64_e32 v[106:107], 0
	v_mov_b64_e32 v[108:109], 0
	v_mov_b64_e32 v[110:111], 0
	v_mov_b64_e32 v[64:65], 0
	v_mov_b64_e32 v[66:67], 0
	v_mov_b64_e32 v[68:69], 0
	v_mov_b64_e32 v[70:71], 0
	v_mov_b64_e32 v[72:73], 0
	v_mov_b64_e32 v[74:75], 0
	v_mov_b64_e32 v[76:77], 0
	v_mov_b64_e32 v[78:79], 0
	v_mov_b64_e32 v[48:49], 0
	v_mov_b64_e32 v[50:51], 0
	v_mov_b64_e32 v[52:53], 0
	v_mov_b64_e32 v[54:55], 0
	v_mov_b64_e32 v[56:57], 0
	v_mov_b64_e32 v[58:59], 0
	v_mov_b64_e32 v[60:61], 0
	v_mov_b64_e32 v[62:63], 0
	v_mov_b64_e32 v[16:17], 0
	v_mov_b64_e32 v[18:19], 0
	v_mov_b64_e32 v[20:21], 0
	v_mov_b64_e32 v[22:23], 0
	v_mov_b64_e32 v[24:25], 0
	v_mov_b64_e32 v[26:27], 0
	v_mov_b64_e32 v[28:29], 0
	v_mov_b64_e32 v[30:31], 0
	v_mov_b64_e32 v[32:33], 0
	v_mov_b64_e32 v[34:35], 0
	v_mov_b64_e32 v[36:37], 0
	v_mov_b64_e32 v[38:39], 0
	v_mov_b64_e32 v[40:41], 0
	v_mov_b64_e32 v[42:43], 0
	v_mov_b64_e32 v[44:45], 0
	v_mov_b64_e32 v[46:47], 0
	v_mov_b64_e32 v[0:1], 0
	v_mov_b64_e32 v[2:3], 0
	v_mov_b64_e32 v[4:5], 0
	v_mov_b64_e32 v[6:7], 0
	v_mov_b64_e32 v[8:9], 0
	v_mov_b64_e32 v[10:11], 0
	v_mov_b64_e32 v[12:13], 0
	v_mov_b64_e32 v[14:15], 0
	s_waitcnt vmcnt(4)
	s_barrier
	ds_read_b128 v[160:163], v204 offset:0
	ds_read_b128 v[128:131], v206 offset:0
	ds_read_b128 v[164:167], v204 offset:2048
	ds_read_b128 v[132:135], v206 offset:2048
	ds_read_b128 v[168:171], v204 offset:4096
	ds_read_b128 v[136:139], v206 offset:4096
	ds_read_b128 v[172:175], v204 offset:6144
	ds_read_b128 v[140:143], v206 offset:6144
	s_movk_i32 s99, 31
; DI void gemm_wide(const bf16_t* __restrict__ W, int ldw, const bf16_t* __restrict__ X, int ldx, int nkt,
;                   f32x16 (&acc)[4][2], bf16_t* lds) {
;     ...
;   for (int kt = 0; kt < nkt; kt += 2) {
;     __builtin_amdgcn_sched_barrier(0);
;     GW_ST2(1, 0, rw0, rw1)                         GW_KS(kt, 0)
;     GW_ST2(1, 128 * LDT, rw2, rw3)                 GW_KS(kt, 1)
;     GW_ST2(1, WT_E, rx0, rx1)                      GW_KS(kt, 2)
;     GW_ST2(1, WT_E + 128 * LDT, rx2, rx3)          GW_KS(kt, 3)
;     __builtin_amdgcn_sched_barrier(0);
;     GW_GLOAD(kt + 3 < nkt ? kt + 3 : nkt - 1)
;     __syncthreads();
;     __builtin_amdgcn_sched_barrier(0);
;     GW_ST2(0, 0, sw0, sw1)                         GW_KS(kt + 1, 0)
;     GW_ST2(0, 128 * LDT, sw2, sw3)                 GW_KS(kt + 1, 1)
;     GW_ST2(0, WT_E, sx0, sx1)                      GW_KS(kt + 1, 2)
;     GW_ST2(0, WT_E + 128 * LDT, sx2, sx3)          GW_KS(kt + 1, 3)
;     __builtin_amdgcn_sched_barrier(0);
;     GW_GLOAD_B(kt + 4 < nkt ? kt + 4 : nkt - 1)
;     __syncthreads();
;   }
.Lgw_down_loop:
	ds_read_b128 v[176:179], v204 offset:8192
	s_waitcnt lgkmcnt(7)
	v_mfma_f32_16x16x32_bf16 v[112:115], v[160:163], v[128:131], v[112:115]
	s_add_u32 m0, s98, 0x18000
	s_waitcnt lgkmcnt(5)
	v_mfma_f32_16x16x32_bf16 v[116:119], v[160:163], v[132:135], v[116:119]
	s_waitcnt lgkmcnt(3)
	v_mfma_f32_16x16x32_bf16 v[80:83], v[160:163], v[136:139], v[80:83]
	global_load_lds_dwordx4 v208, s[30:31]
	s_waitcnt lgkmcnt(1)
	v_mfma_f32_16x16x32_bf16 v[84:87], v[160:163], v[140:143], v[84:87]
	ds_read_b128 v[180:183], v204 offset:10240
	v_mfma_f32_16x16x32_bf16 v[120:123], v[164:167], v[128:131], v[120:123]
	s_add_u32 m0, s98, 0x18400
	v_mfma_f32_16x16x32_bf16 v[124:127], v[164:167], v[132:135], v[124:127]
	v_mfma_f32_16x16x32_bf16 v[88:91], v[164:167], v[136:139], v[88:91]
	global_load_lds_dwordx4 v209, s[30:31]
	v_mfma_f32_16x16x32_bf16 v[92:95], v[164:167], v[140:143], v[92:95]
	ds_read_b128 v[184:187], v204 offset:12288
	v_mfma_f32_16x16x32_bf16 v[96:99], v[168:171], v[128:131], v[96:99]
	s_add_u32 m0, s98, 0x18800
	v_mfma_f32_16x16x32_bf16 v[100:103], v[168:171], v[132:135], v[100:103]
	v_mfma_f32_16x16x32_bf16 v[64:67], v[168:171], v[136:139], v[64:67]
	global_load_lds_dwordx4 v210, s[30:31]
	v_mfma_f32_16x16x32_bf16 v[68:71], v[168:171], v[140:143], v[68:71]
	ds_read_b128 v[188:191], v204 offset:14336
	v_mfma_f32_16x16x32_bf16 v[104:107], v[172:175], v[128:131], v[104:107]
	s_add_u32 m0, s98, 0x18c00
	v_mfma_f32_16x16x32_bf16 v[108:111], v[172:175], v[132:135], v[108:111]
	v_mfma_f32_16x16x32_bf16 v[72:75], v[172:175], v[136:139], v[72:75]
	global_load_lds_dwordx4 v211, s[30:31]
	v_mfma_f32_16x16x32_bf16 v[76:79], v[172:175], v[140:143], v[76:79]
	s_add_u32 s30, s30, 0x80
	s_addc_u32 s31, s31, 0
	s_waitcnt lgkmcnt(3)
	v_mfma_f32_16x16x32_bf16 v[48:51], v[176:179], v[128:131], v[48:51]
	v_mfma_f32_16x16x32_bf16 v[52:55], v[176:179], v[132:135], v[52:55]
	ds_read_b128 v[160:163], v205 offset:0
	v_mfma_f32_16x16x32_bf16 v[16:19], v[176:179], v[136:139], v[16:19]
	v_mfma_f32_16x16x32_bf16 v[20:23], v[176:179], v[140:143], v[20:23]
	ds_read_b128 v[144:147], v207 offset:0
	s_waitcnt lgkmcnt(4)
	v_mfma_f32_16x16x32_bf16 v[56:59], v[180:183], v[128:131], v[56:59]
	v_mfma_f32_16x16x32_bf16 v[60:63], v[180:183], v[132:135], v[60:63]
	ds_read_b128 v[164:167], v205 offset:2048
	v_mfma_f32_16x16x32_bf16 v[24:27], v[180:183], v[136:139], v[24:27]
	v_mfma_f32_16x16x32_bf16 v[28:31], v[180:183], v[140:143], v[28:31]
	ds_read_b128 v[148:151], v207 offset:2048
	s_waitcnt lgkmcnt(5)
	v_mfma_f32_16x16x32_bf16 v[32:35], v[184:187], v[128:131], v[32:35]
	v_mfma_f32_16x16x32_bf16 v[36:39], v[184:187], v[132:135], v[36:39]
	ds_read_b128 v[168:171], v205 offset:4096
	v_mfma_f32_16x16x32_bf16 v[0:3], v[184:187], v[136:139], v[0:3]
	v_mfma_f32_16x16x32_bf16 v[4:7], v[184:187], v[140:143], v[4:7]
	ds_read_b128 v[152:155], v207 offset:4096
	s_waitcnt lgkmcnt(6)
	v_mfma_f32_16x16x32_bf16 v[40:43], v[188:191], v[128:131], v[40:43]
	v_mfma_f32_16x16x32_bf16 v[44:47], v[188:191], v[132:135], v[44:47]
	ds_read_b128 v[172:175], v205 offset:6144
	v_mfma_f32_16x16x32_bf16 v[8:11], v[188:191], v[136:139], v[8:11]
	v_mfma_f32_16x16x32_bf16 v[12:15], v[188:191], v[140:143], v[12:15]
	ds_read_b128 v[156:159], v207 offset:6144
	ds_read_b128 v[176:179], v205 offset:8192
	ds_read_b128 v[180:183], v205 offset:10240
	ds_read_b128 v[184:187], v205 offset:12288
	ds_read_b128 v[188:191], v205 offset:14336
	s_waitcnt lgkmcnt(10)
	v_mfma_f32_16x16x32_bf16 v[112:115], v[160:163], v[144:147], v[112:115]
	s_waitcnt lgkmcnt(8)
	v_mfma_f32_16x16x32_bf16 v[116:119], v[160:163], v[148:151], v[116:119]
	s_waitcnt lgkmcnt(6)
	v_mfma_f32_16x16x32_bf16 v[80:83], v[160:163], v[152:155], v[80:83]
	s_waitcnt lgkmcnt(4)
	v_mfma_f32_16x16x32_bf16 v[84:87], v[160:163], v[156:159], v[84:87]
	v_mfma_f32_16x16x32_bf16 v[120:123], v[164:167], v[144:147], v[120:123]
	v_mfma_f32_16x16x32_bf16 v[124:127], v[164:167], v[148:151], v[124:127]
	v_mfma_f32_16x16x32_bf16 v[88:91], v[164:167], v[152:155], v[88:91]
	v_mfma_f32_16x16x32_bf16 v[92:95], v[164:167], v[156:159], v[92:95]
	v_mfma_f32_16x16x32_bf16 v[96:99], v[168:171], v[144:147], v[96:99]
	v_mfma_f32_16x16x32_bf16 v[100:103], v[168:171], v[148:151], v[100:103]
	v_mfma_f32_16x16x32_bf16 v[64:67], v[168:171], v[152:155], v[64:67]
	v_mfma_f32_16x16x32_bf16 v[68:71], v[168:171], v[156:159], v[68:71]
	v_mfma_f32_16x16x32_bf16 v[104:107], v[172:175], v[144:147], v[104:107]
	v_mfma_f32_16x16x32_bf16 v[108:111], v[172:175], v[148:151], v[108:111]
	v_mfma_f32_16x16x32_bf16 v[72:75], v[172:175], v[152:155], v[72:75]
	v_mfma_f32_16x16x32_bf16 v[76:79], v[172:175], v[156:159], v[76:79]
	s_waitcnt vmcnt(0) lgkmcnt(0)
	s_barrier
; DI void gemm_wide(const bf16_t* __restrict__ W, int ldw, const bf16_t* __restrict__ X, int ldx, int nkt,
;                   f32x16 (&acc)[4][2], bf16_t* lds) {
;     ...
;   for (int kt = 0; kt < nkt; kt += 2) {
;     __builtin_amdgcn_sched_barrier(0);
;     GW_ST2(1, 0, rw0, rw1)                         GW_KS(kt, 0)
;     GW_ST2(1, 128 * LDT, rw2, rw3)                 GW_KS(kt, 1)
;     GW_ST2(1, WT_E, rx0, rx1)                      GW_KS(kt, 2)
;     GW_ST2(1, WT_E + 128 * LDT, rx2, rx3)          GW_KS(kt, 3)
;     __builtin_amdgcn_sched_barrier(0);
;     GW_GLOAD(kt + 3 < nkt ? kt + 3 : nkt - 1)
;     __syncthreads();
;     __builtin_amdgcn_sched_barrier(0);
;     GW_ST2(0, 0, sw0, sw1)                         GW_KS(kt + 1, 0)
;     GW_ST2(0, 128 * LDT, sw2, sw3)                 GW_KS(kt + 1, 1)
;     GW_ST2(0, WT_E, sx0, sx1)                      GW_KS(kt + 1, 2)
;     GW_ST2(0, WT_E + 128 * LDT, sx2, sx3)          GW_KS(kt + 1, 3)
;     __builtin_amdgcn_sched_barrier(0);
;     GW_GLOAD_B(kt + 4 < nkt ? kt + 4 : nkt - 1)
;     __syncthreads();
;   }
	v_mfma_f32_16x16x32_bf16 v[48:51], v[176:179], v[144:147], v[48:51]
	s_mov_b32 m0, s98
	v_mfma_f32_16x16x32_bf16 v[52:55], v[176:179], v[148:151], v[52:55]
	ds_read_b128 v[160:163], v204 offset:32768
	v_mfma_f32_16x16x32_bf16 v[16:19], v[176:179], v[152:155], v[16:19]
	global_load_lds_dwordx4 v208, s[28:29]
	v_mfma_f32_16x16x32_bf16 v[20:23], v[176:179], v[156:159], v[20:23]
	ds_read_b128 v[128:131], v206 offset:32768
	v_mfma_f32_16x16x32_bf16 v[56:59], v[180:183], v[144:147], v[56:59]
	s_add_u32 m0, s98, 0x400
	v_mfma_f32_16x16x32_bf16 v[60:63], v[180:183], v[148:151], v[60:63]
	ds_read_b128 v[164:167], v204 offset:34816
	v_mfma_f32_16x16x32_bf16 v[24:27], v[180:183], v[152:155], v[24:27]
	global_load_lds_dwordx4 v209, s[28:29]
	v_mfma_f32_16x16x32_bf16 v[28:31], v[180:183], v[156:159], v[28:31]
	ds_read_b128 v[132:135], v206 offset:34816
	v_mfma_f32_16x16x32_bf16 v[32:35], v[184:187], v[144:147], v[32:35]
	s_add_u32 m0, s98, 0x800
	v_mfma_f32_16x16x32_bf16 v[36:39], v[184:187], v[148:151], v[36:39]
	ds_read_b128 v[168:171], v204 offset:36864
	v_mfma_f32_16x16x32_bf16 v[0:3], v[184:187], v[152:155], v[0:3]
	global_load_lds_dwordx4 v210, s[28:29]
	v_mfma_f32_16x16x32_bf16 v[4:7], v[184:187], v[156:159], v[4:7]
	ds_read_b128 v[136:139], v206 offset:36864
	v_mfma_f32_16x16x32_bf16 v[40:43], v[188:191], v[144:147], v[40:43]
	s_add_u32 m0, s98, 0xc00
	v_mfma_f32_16x16x32_bf16 v[44:47], v[188:191], v[148:151], v[44:47]
	ds_read_b128 v[172:175], v204 offset:38912
	v_mfma_f32_16x16x32_bf16 v[8:11], v[188:191], v[152:155], v[8:11]
	global_load_lds_dwordx4 v211, s[28:29]
	v_mfma_f32_16x16x32_bf16 v[12:15], v[188:191], v[156:159], v[12:15]
	ds_read_b128 v[140:143], v206 offset:38912
	s_add_u32 s28, s28, 0x80
	s_addc_u32 s29, s29, 0
	ds_read_b128 v[176:179], v204 offset:40960
	s_waitcnt lgkmcnt(7)
	v_mfma_f32_16x16x32_bf16 v[112:115], v[160:163], v[128:131], v[112:115]
	s_add_u32 m0, s98, 0x10000
	s_waitcnt lgkmcnt(5)
	v_mfma_f32_16x16x32_bf16 v[116:119], v[160:163], v[132:135], v[116:119]
	s_waitcnt lgkmcnt(3)
	v_mfma_f32_16x16x32_bf16 v[80:83], v[160:163], v[136:139], v[80:83]
	global_load_lds_dwordx4 v208, s[30:31]
	s_waitcnt lgkmcnt(1)
	v_mfma_f32_16x16x32_bf16 v[84:87], v[160:163], v[140:143], v[84:87]
	ds_read_b128 v[180:183], v204 offset:43008
	v_mfma_f32_16x16x32_bf16 v[120:123], v[164:167], v[128:131], v[120:123]
	s_add_u32 m0, s98, 0x10400
	v_mfma_f32_16x16x32_bf16 v[124:127], v[164:167], v[132:135], v[124:127]
	v_mfma_f32_16x16x32_bf16 v[88:91], v[164:167], v[136:139], v[88:91]
	global_load_lds_dwordx4 v209, s[30:31]
	v_mfma_f32_16x16x32_bf16 v[92:95], v[164:167], v[140:143], v[92:95]
	ds_read_b128 v[184:187], v204 offset:45056
	v_mfma_f32_16x16x32_bf16 v[96:99], v[168:171], v[128:131], v[96:99]
	s_add_u32 m0, s98, 0x10800
	v_mfma_f32_16x16x32_bf16 v[100:103], v[168:171], v[132:135], v[100:103]
	v_mfma_f32_16x16x32_bf16 v[64:67], v[168:171], v[136:139], v[64:67]
	global_load_lds_dwordx4 v210, s[30:31]
	v_mfma_f32_16x16x32_bf16 v[68:71], v[168:171], v[140:143], v[68:71]
	ds_read_b128 v[188:191], v204 offset:47104
	v_mfma_f32_16x16x32_bf16 v[104:107], v[172:175], v[128:131], v[104:107]
	s_add_u32 m0, s98, 0x10c00
	v_mfma_f32_16x16x32_bf16 v[108:111], v[172:175], v[132:135], v[108:111]
	v_mfma_f32_16x16x32_bf16 v[72:75], v[172:175], v[136:139], v[72:75]
	global_load_lds_dwordx4 v211, s[30:31]
	v_mfma_f32_16x16x32_bf16 v[76:79], v[172:175], v[140:143], v[76:79]
	s_add_u32 s30, s30, 0x80
	s_addc_u32 s31, s31, 0
	s_waitcnt lgkmcnt(3)
	v_mfma_f32_16x16x32_bf16 v[48:51], v[176:179], v[128:131], v[48:51]
	v_mfma_f32_16x16x32_bf16 v[52:55], v[176:179], v[132:135], v[52:55]
	ds_read_b128 v[160:163], v205 offset:32768
	v_mfma_f32_16x16x32_bf16 v[16:19], v[176:179], v[136:139], v[16:19]
	v_mfma_f32_16x16x32_bf16 v[20:23], v[176:179], v[140:143], v[20:23]
	ds_read_b128 v[144:147], v207 offset:32768
	s_waitcnt lgkmcnt(4)
	v_mfma_f32_16x16x32_bf16 v[56:59], v[180:183], v[128:131], v[56:59]
	v_mfma_f32_16x16x32_bf16 v[60:63], v[180:183], v[132:135], v[60:63]
	ds_read_b128 v[164:167], v205 offset:34816
	v_mfma_f32_16x16x32_bf16 v[24:27], v[180:183], v[136:139], v[24:27]
	v_mfma_f32_16x16x32_bf16 v[28:31], v[180:183], v[140:143], v[28:31]
	ds_read_b128 v[148:151], v207 offset:34816
	s_waitcnt lgkmcnt(5)
	v_mfma_f32_16x16x32_bf16 v[32:35], v[184:187], v[128:131], v[32:35]
	v_mfma_f32_16x16x32_bf16 v[36:39], v[184:187], v[132:135], v[36:39]
	ds_read_b128 v[168:171], v205 offset:36864
	v_mfma_f32_16x16x32_bf16 v[0:3], v[184:187], v[136:139], v[0:3]
	v_mfma_f32_16x16x32_bf16 v[4:7], v[184:187], v[140:143], v[4:7]
	ds_read_b128 v[152:155], v207 offset:36864
	s_waitcnt lgkmcnt(6)
	v_mfma_f32_16x16x32_bf16 v[40:43], v[188:191], v[128:131], v[40:43]
	v_mfma_f32_16x16x32_bf16 v[44:47], v[188:191], v[132:135], v[44:47]
	ds_read_b128 v[172:175], v205 offset:38912
	v_mfma_f32_16x16x32_bf16 v[8:11], v[188:191], v[136:139], v[8:11]
	v_mfma_f32_16x16x32_bf16 v[12:15], v[188:191], v[140:143], v[12:15]
	ds_read_b128 v[156:159], v207 offset:38912
	ds_read_b128 v[176:179], v205 offset:40960
	ds_read_b128 v[180:183], v205 offset:43008
	ds_read_b128 v[184:187], v205 offset:45056
	ds_read_b128 v[188:191], v205 offset:47104
	s_waitcnt lgkmcnt(10)
	v_mfma_f32_16x16x32_bf16 v[112:115], v[160:163], v[144:147], v[112:115]
	s_waitcnt lgkmcnt(8)
	v_mfma_f32_16x16x32_bf16 v[116:119], v[160:163], v[148:151], v[116:119]
	s_waitcnt lgkmcnt(6)
	v_mfma_f32_16x16x32_bf16 v[80:83], v[160:163], v[152:155], v[80:83]
	s_waitcnt lgkmcnt(4)
	v_mfma_f32_16x16x32_bf16 v[84:87], v[160:163], v[156:159], v[84:87]
	v_mfma_f32_16x16x32_bf16 v[120:123], v[164:167], v[144:147], v[120:123]
	v_mfma_f32_16x16x32_bf16 v[124:127], v[164:167], v[148:151], v[124:127]
	v_mfma_f32_16x16x32_bf16 v[88:91], v[164:167], v[152:155], v[88:91]
	v_mfma_f32_16x16x32_bf16 v[92:95], v[164:167], v[156:159], v[92:95]
	v_mfma_f32_16x16x32_bf16 v[96:99], v[168:171], v[144:147], v[96:99]
	v_mfma_f32_16x16x32_bf16 v[100:103], v[168:171], v[148:151], v[100:103]
	v_mfma_f32_16x16x32_bf16 v[64:67], v[168:171], v[152:155], v[64:67]
	v_mfma_f32_16x16x32_bf16 v[68:71], v[168:171], v[156:159], v[68:71]
	v_mfma_f32_16x16x32_bf16 v[104:107], v[172:175], v[144:147], v[104:107]
	v_mfma_f32_16x16x32_bf16 v[108:111], v[172:175], v[148:151], v[108:111]
	v_mfma_f32_16x16x32_bf16 v[72:75], v[172:175], v[152:155], v[72:75]
	v_mfma_f32_16x16x32_bf16 v[76:79], v[172:175], v[156:159], v[76:79]
	s_waitcnt vmcnt(0) lgkmcnt(0)
	s_barrier
; DI void gemm_wide(const bf16_t* __restrict__ W, int ldw, const bf16_t* __restrict__ X, int ldx, int nkt,
;                   f32x16 (&acc)[4][2], bf16_t* lds) {
;     ...
;   for (int kt = 0; kt < nkt; kt += 2) {
;     __builtin_amdgcn_sched_barrier(0);
;     GW_ST2(1, 0, rw0, rw1)                         GW_KS(kt, 0)
;     GW_ST2(1, 128 * LDT, rw2, rw3)                 GW_KS(kt, 1)
;     GW_ST2(1, WT_E, rx0, rx1)                      GW_KS(kt, 2)
;     GW_ST2(1, WT_E + 128 * LDT, rx2, rx3)          GW_KS(kt, 3)
;     __builtin_amdgcn_sched_barrier(0);
;     GW_GLOAD(kt + 3 < nkt ? kt + 3 : nkt - 1)
;     __syncthreads();
;     __builtin_amdgcn_sched_barrier(0);
;     GW_ST2(0, 0, sw0, sw1)                         GW_KS(kt + 1, 0)
;     GW_ST2(0, 128 * LDT, sw2, sw3)                 GW_KS(kt + 1, 1)
;     GW_ST2(0, WT_E, sx0, sx1)                      GW_KS(kt + 1, 2)
;     GW_ST2(0, WT_E + 128 * LDT, sx2, sx3)          GW_KS(kt + 1, 3)
;     __builtin_amdgcn_sched_barrier(0);
;     GW_GLOAD_B(kt + 4 < nkt ? kt + 4 : nkt - 1)
;     __syncthreads();
;   }
	v_mfma_f32_16x16x32_bf16 v[48:51], v[176:179], v[144:147], v[48:51]
	s_add_u32 m0, s98, 0x8000
	v_mfma_f32_16x16x32_bf16 v[52:55], v[176:179], v[148:151], v[52:55]
	ds_read_b128 v[160:163], v204 offset:0
	v_mfma_f32_16x16x32_bf16 v[16:19], v[176:179], v[152:155], v[16:19]
	global_load_lds_dwordx4 v208, s[28:29]
	v_mfma_f32_16x16x32_bf16 v[20:23], v[176:179], v[156:159], v[20:23]
	ds_read_b128 v[128:131], v206 offset:0
	v_mfma_f32_16x16x32_bf16 v[56:59], v[180:183], v[144:147], v[56:59]
	s_add_u32 m0, s98, 0x8400
	v_mfma_f32_16x16x32_bf16 v[60:63], v[180:183], v[148:151], v[60:63]
	ds_read_b128 v[164:167], v204 offset:2048
	v_mfma_f32_16x16x32_bf16 v[24:27], v[180:183], v[152:155], v[24:27]
	global_load_lds_dwordx4 v209, s[28:29]
	v_mfma_f32_16x16x32_bf16 v[28:31], v[180:183], v[156:159], v[28:31]
	ds_read_b128 v[132:135], v206 offset:2048
	v_mfma_f32_16x16x32_bf16 v[32:35], v[184:187], v[144:147], v[32:35]
	s_add_u32 m0, s98, 0x8800
	v_mfma_f32_16x16x32_bf16 v[36:39], v[184:187], v[148:151], v[36:39]
	ds_read_b128 v[168:171], v204 offset:4096
	v_mfma_f32_16x16x32_bf16 v[0:3], v[184:187], v[152:155], v[0:3]
	global_load_lds_dwordx4 v210, s[28:29]
	v_mfma_f32_16x16x32_bf16 v[4:7], v[184:187], v[156:159], v[4:7]
	ds_read_b128 v[136:139], v206 offset:4096
	v_mfma_f32_16x16x32_bf16 v[40:43], v[188:191], v[144:147], v[40:43]
	s_add_u32 m0, s98, 0x8c00
	v_mfma_f32_16x16x32_bf16 v[44:47], v[188:191], v[148:151], v[44:47]
	ds_read_b128 v[172:175], v204 offset:6144
	v_mfma_f32_16x16x32_bf16 v[8:11], v[188:191], v[152:155], v[8:11]
	global_load_lds_dwordx4 v211, s[28:29]
	v_mfma_f32_16x16x32_bf16 v[12:15], v[188:191], v[156:159], v[12:15]
	ds_read_b128 v[140:143], v206 offset:6144
	s_add_u32 s28, s28, 0x80
	s_addc_u32 s29, s29, 0
	s_sub_u32 s99, s99, 1
	s_cmp_lg_u32 s99, 0
	s_cbranch_scc1 .Lgw_down_loop
	ds_read_b128 v[176:179], v204 offset:8192
	s_waitcnt lgkmcnt(7)
	v_mfma_f32_16x16x32_bf16 v[112:115], v[160:163], v[128:131], v[112:115]
	s_add_u32 m0, s98, 0x18000
	s_waitcnt lgkmcnt(5)
	v_mfma_f32_16x16x32_bf16 v[116:119], v[160:163], v[132:135], v[116:119]
	s_waitcnt lgkmcnt(3)
	v_mfma_f32_16x16x32_bf16 v[80:83], v[160:163], v[136:139], v[80:83]
	global_load_lds_dwordx4 v208, s[30:31]
	s_waitcnt lgkmcnt(1)
	v_mfma_f32_16x16x32_bf16 v[84:87], v[160:163], v[140:143], v[84:87]
	ds_read_b128 v[180:183], v204 offset:10240
	v_mfma_f32_16x16x32_bf16 v[120:123], v[164:167], v[128:131], v[120:123]
	s_add_u32 m0, s98, 0x18400
	v_mfma_f32_16x16x32_bf16 v[124:127], v[164:167], v[132:135], v[124:127]
	v_mfma_f32_16x16x32_bf16 v[88:91], v[164:167], v[136:139], v[88:91]
	global_load_lds_dwordx4 v209, s[30:31]
	v_mfma_f32_16x16x32_bf16 v[92:95], v[164:167], v[140:143], v[92:95]
	ds_read_b128 v[184:187], v204 offset:12288
	v_mfma_f32_16x16x32_bf16 v[96:99], v[168:171], v[128:131], v[96:99]
	s_add_u32 m0, s98, 0x18800
	v_mfma_f32_16x16x32_bf16 v[100:103], v[168:171], v[132:135], v[100:103]
	v_mfma_f32_16x16x32_bf16 v[64:67], v[168:171], v[136:139], v[64:67]
	global_load_lds_dwordx4 v210, s[30:31]
	v_mfma_f32_16x16x32_bf16 v[68:71], v[168:171], v[140:143], v[68:71]
	ds_read_b128 v[188:191], v204 offset:14336
	v_mfma_f32_16x16x32_bf16 v[104:107], v[172:175], v[128:131], v[104:107]
	s_add_u32 m0, s98, 0x18c00
	v_mfma_f32_16x16x32_bf16 v[108:111], v[172:175], v[132:135], v[108:111]
	v_mfma_f32_16x16x32_bf16 v[72:75], v[172:175], v[136:139], v[72:75]
	global_load_lds_dwordx4 v211, s[30:31]
	v_mfma_f32_16x16x32_bf16 v[76:79], v[172:175], v[140:143], v[76:79]
	s_add_u32 s30, s30, 0x80
	s_addc_u32 s31, s31, 0
	s_waitcnt lgkmcnt(3)
	v_mfma_f32_16x16x32_bf16 v[48:51], v[176:179], v[128:131], v[48:51]
	v_mfma_f32_16x16x32_bf16 v[52:55], v[176:179], v[132:135], v[52:55]
	ds_read_b128 v[160:163], v205 offset:0
	v_mfma_f32_16x16x32_bf16 v[16:19], v[176:179], v[136:139], v[16:19]
	v_mfma_f32_16x16x32_bf16 v[20:23], v[176:179], v[140:143], v[20:23]
	ds_read_b128 v[144:147], v207 offset:0
	s_waitcnt lgkmcnt(4)
	v_mfma_f32_16x16x32_bf16 v[56:59], v[180:183], v[128:131], v[56:59]
	v_mfma_f32_16x16x32_bf16 v[60:63], v[180:183], v[132:135], v[60:63]
	ds_read_b128 v[164:167], v205 offset:2048
	v_mfma_f32_16x16x32_bf16 v[24:27], v[180:183], v[136:139], v[24:27]
	v_mfma_f32_16x16x32_bf16 v[28:31], v[180:183], v[140:143], v[28:31]
	ds_read_b128 v[148:151], v207 offset:2048
	s_waitcnt lgkmcnt(5)
	v_mfma_f32_16x16x32_bf16 v[32:35], v[184:187], v[128:131], v[32:35]
	v_mfma_f32_16x16x32_bf16 v[36:39], v[184:187], v[132:135], v[36:39]
	ds_read_b128 v[168:171], v205 offset:4096
	v_mfma_f32_16x16x32_bf16 v[0:3], v[184:187], v[136:139], v[0:3]
	v_mfma_f32_16x16x32_bf16 v[4:7], v[184:187], v[140:143], v[4:7]
	ds_read_b128 v[152:155], v207 offset:4096
	s_waitcnt lgkmcnt(6)
	v_mfma_f32_16x16x32_bf16 v[40:43], v[188:191], v[128:131], v[40:43]
	v_mfma_f32_16x16x32_bf16 v[44:47], v[188:191], v[132:135], v[44:47]
	ds_read_b128 v[172:175], v205 offset:6144
	v_mfma_f32_16x16x32_bf16 v[8:11], v[188:191], v[136:139], v[8:11]
	v_mfma_f32_16x16x32_bf16 v[12:15], v[188:191], v[140:143], v[12:15]
	ds_read_b128 v[156:159], v207 offset:6144
	ds_read_b128 v[176:179], v205 offset:8192
	ds_read_b128 v[180:183], v205 offset:10240
	ds_read_b128 v[184:187], v205 offset:12288
	ds_read_b128 v[188:191], v205 offset:14336
	s_waitcnt lgkmcnt(10)
	v_mfma_f32_16x16x32_bf16 v[112:115], v[160:163], v[144:147], v[112:115]
	s_waitcnt lgkmcnt(8)
	v_mfma_f32_16x16x32_bf16 v[116:119], v[160:163], v[148:151], v[116:119]
	s_waitcnt lgkmcnt(6)
	v_mfma_f32_16x16x32_bf16 v[80:83], v[160:163], v[152:155], v[80:83]
	s_waitcnt lgkmcnt(4)
	v_mfma_f32_16x16x32_bf16 v[84:87], v[160:163], v[156:159], v[84:87]
	v_mfma_f32_16x16x32_bf16 v[120:123], v[164:167], v[144:147], v[120:123]
	v_mfma_f32_16x16x32_bf16 v[124:127], v[164:167], v[148:151], v[124:127]
	v_mfma_f32_16x16x32_bf16 v[88:91], v[164:167], v[152:155], v[88:91]
	v_mfma_f32_16x16x32_bf16 v[92:95], v[164:167], v[156:159], v[92:95]
	v_mfma_f32_16x16x32_bf16 v[96:99], v[168:171], v[144:147], v[96:99]
	v_mfma_f32_16x16x32_bf16 v[100:103], v[168:171], v[148:151], v[100:103]
	v_mfma_f32_16x16x32_bf16 v[64:67], v[168:171], v[152:155], v[64:67]
	v_mfma_f32_16x16x32_bf16 v[68:71], v[168:171], v[156:159], v[68:71]
	v_mfma_f32_16x16x32_bf16 v[104:107], v[172:175], v[144:147], v[104:107]
	v_mfma_f32_16x16x32_bf16 v[108:111], v[172:175], v[148:151], v[108:111]
	v_mfma_f32_16x16x32_bf16 v[72:75], v[172:175], v[152:155], v[72:75]
	v_mfma_f32_16x16x32_bf16 v[76:79], v[172:175], v[156:159], v[76:79]
	s_waitcnt vmcnt(0) lgkmcnt(0)
	s_barrier
; DI void gemm_wide(const bf16_t* __restrict__ W, int ldw, const bf16_t* __restrict__ X, int ldx, int nkt,
;                   f32x16 (&acc)[4][2], bf16_t* lds) {
;     ...
;   for (int kt = 0; kt < nkt; kt += 2) {
;     __builtin_amdgcn_sched_barrier(0);
;     GW_ST2(1, 0, rw0, rw1)                         GW_KS(kt, 0)
;     GW_ST2(1, 128 * LDT, rw2, rw3)                 GW_KS(kt, 1)
;     GW_ST2(1, WT_E, rx0, rx1)                      GW_KS(kt, 2)
;     GW_ST2(1, WT_E + 128 * LDT, rx2, rx3)          GW_KS(kt, 3)
;     __builtin_amdgcn_sched_barrier(0);
;     GW_GLOAD(kt + 3 < nkt ? kt + 3 : nkt - 1)
;     __syncthreads();
;     __builtin_amdgcn_sched_barrier(0);
;     GW_ST2(0, 0, sw0, sw1)                         GW_KS(kt + 1, 0)
;     GW_ST2(0, 128 * LDT, sw2, sw3)                 GW_KS(kt + 1, 1)
;     GW_ST2(0, WT_E, sx0, sx1)                      GW_KS(kt + 1, 2)
;     GW_ST2(0, WT_E + 128 * LDT, sx2, sx3)          GW_KS(kt + 1, 3)
;     __builtin_amdgcn_sched_barrier(0);
;     GW_GLOAD_B(kt + 4 < nkt ? kt + 4 : nkt - 1)
;     __syncthreads();
;   }
	v_mfma_f32_16x16x32_bf16 v[48:51], v[176:179], v[144:147], v[48:51]
	v_mfma_f32_16x16x32_bf16 v[52:55], v[176:179], v[148:151], v[52:55]
	ds_read_b128 v[160:163], v204 offset:32768
	v_mfma_f32_16x16x32_bf16 v[16:19], v[176:179], v[152:155], v[16:19]
	v_mfma_f32_16x16x32_bf16 v[20:23], v[176:179], v[156:159], v[20:23]
	ds_read_b128 v[128:131], v206 offset:32768
	v_mfma_f32_16x16x32_bf16 v[56:59], v[180:183], v[144:147], v[56:59]
	v_mfma_f32_16x16x32_bf16 v[60:63], v[180:183], v[148:151], v[60:63]
	ds_read_b128 v[164:167], v204 offset:34816
	v_mfma_f32_16x16x32_bf16 v[24:27], v[180:183], v[152:155], v[24:27]
	v_mfma_f32_16x16x32_bf16 v[28:31], v[180:183], v[156:159], v[28:31]
	ds_read_b128 v[132:135], v206 offset:34816
	v_mfma_f32_16x16x32_bf16 v[32:35], v[184:187], v[144:147], v[32:35]
	v_mfma_f32_16x16x32_bf16 v[36:39], v[184:187], v[148:151], v[36:39]
	ds_read_b128 v[168:171], v204 offset:36864
	v_mfma_f32_16x16x32_bf16 v[0:3], v[184:187], v[152:155], v[0:3]
	v_mfma_f32_16x16x32_bf16 v[4:7], v[184:187], v[156:159], v[4:7]
	ds_read_b128 v[136:139], v206 offset:36864
	v_mfma_f32_16x16x32_bf16 v[40:43], v[188:191], v[144:147], v[40:43]
	v_mfma_f32_16x16x32_bf16 v[44:47], v[188:191], v[148:151], v[44:47]
	ds_read_b128 v[172:175], v204 offset:38912
	v_mfma_f32_16x16x32_bf16 v[8:11], v[188:191], v[152:155], v[8:11]
	v_mfma_f32_16x16x32_bf16 v[12:15], v[188:191], v[156:159], v[12:15]
	ds_read_b128 v[140:143], v206 offset:38912
	ds_read_b128 v[176:179], v204 offset:40960
	s_waitcnt lgkmcnt(7)
	v_mfma_f32_16x16x32_bf16 v[112:115], v[160:163], v[128:131], v[112:115]
	s_waitcnt lgkmcnt(5)
	v_mfma_f32_16x16x32_bf16 v[116:119], v[160:163], v[132:135], v[116:119]
	s_waitcnt lgkmcnt(3)
	v_mfma_f32_16x16x32_bf16 v[80:83], v[160:163], v[136:139], v[80:83]
	s_waitcnt lgkmcnt(1)
	v_mfma_f32_16x16x32_bf16 v[84:87], v[160:163], v[140:143], v[84:87]
	ds_read_b128 v[180:183], v204 offset:43008
	v_mfma_f32_16x16x32_bf16 v[120:123], v[164:167], v[128:131], v[120:123]
	v_mfma_f32_16x16x32_bf16 v[124:127], v[164:167], v[132:135], v[124:127]
	v_mfma_f32_16x16x32_bf16 v[88:91], v[164:167], v[136:139], v[88:91]
	v_mfma_f32_16x16x32_bf16 v[92:95], v[164:167], v[140:143], v[92:95]
	ds_read_b128 v[184:187], v204 offset:45056
	v_mfma_f32_16x16x32_bf16 v[96:99], v[168:171], v[128:131], v[96:99]
	v_mfma_f32_16x16x32_bf16 v[100:103], v[168:171], v[132:135], v[100:103]
	v_mfma_f32_16x16x32_bf16 v[64:67], v[168:171], v[136:139], v[64:67]
	v_mfma_f32_16x16x32_bf16 v[68:71], v[168:171], v[140:143], v[68:71]
	ds_read_b128 v[188:191], v204 offset:47104
	v_mfma_f32_16x16x32_bf16 v[104:107], v[172:175], v[128:131], v[104:107]
	v_mfma_f32_16x16x32_bf16 v[108:111], v[172:175], v[132:135], v[108:111]
	v_mfma_f32_16x16x32_bf16 v[72:75], v[172:175], v[136:139], v[72:75]
	v_mfma_f32_16x16x32_bf16 v[76:79], v[172:175], v[140:143], v[76:79]
	s_waitcnt lgkmcnt(3)
	v_mfma_f32_16x16x32_bf16 v[48:51], v[176:179], v[128:131], v[48:51]
	v_mfma_f32_16x16x32_bf16 v[52:55], v[176:179], v[132:135], v[52:55]
	ds_read_b128 v[160:163], v205 offset:32768
	v_mfma_f32_16x16x32_bf16 v[16:19], v[176:179], v[136:139], v[16:19]
	v_mfma_f32_16x16x32_bf16 v[20:23], v[176:179], v[140:143], v[20:23]
	ds_read_b128 v[144:147], v207 offset:32768
	s_waitcnt lgkmcnt(4)
	v_mfma_f32_16x16x32_bf16 v[56:59], v[180:183], v[128:131], v[56:59]
	v_mfma_f32_16x16x32_bf16 v[60:63], v[180:183], v[132:135], v[60:63]
	ds_read_b128 v[164:167], v205 offset:34816
	v_mfma_f32_16x16x32_bf16 v[24:27], v[180:183], v[136:139], v[24:27]
	v_mfma_f32_16x16x32_bf16 v[28:31], v[180:183], v[140:143], v[28:31]
	ds_read_b128 v[148:151], v207 offset:34816
	s_waitcnt lgkmcnt(5)
	v_mfma_f32_16x16x32_bf16 v[32:35], v[184:187], v[128:131], v[32:35]
	v_mfma_f32_16x16x32_bf16 v[36:39], v[184:187], v[132:135], v[36:39]
	ds_read_b128 v[168:171], v205 offset:36864
	v_mfma_f32_16x16x32_bf16 v[0:3], v[184:187], v[136:139], v[0:3]
	v_mfma_f32_16x16x32_bf16 v[4:7], v[184:187], v[140:143], v[4:7]
	ds_read_b128 v[152:155], v207 offset:36864
	s_waitcnt lgkmcnt(6)
	v_mfma_f32_16x16x32_bf16 v[40:43], v[188:191], v[128:131], v[40:43]
	v_mfma_f32_16x16x32_bf16 v[44:47], v[188:191], v[132:135], v[44:47]
	ds_read_b128 v[172:175], v205 offset:38912
	v_mfma_f32_16x16x32_bf16 v[8:11], v[188:191], v[136:139], v[8:11]
	v_mfma_f32_16x16x32_bf16 v[12:15], v[188:191], v[140:143], v[12:15]
	ds_read_b128 v[156:159], v207 offset:38912
	ds_read_b128 v[176:179], v205 offset:40960
	ds_read_b128 v[180:183], v205 offset:43008
	ds_read_b128 v[184:187], v205 offset:45056
	ds_read_b128 v[188:191], v205 offset:47104
	s_waitcnt lgkmcnt(10)
	v_mfma_f32_16x16x32_bf16 v[112:115], v[160:163], v[144:147], v[112:115]
	s_waitcnt lgkmcnt(8)
	v_mfma_f32_16x16x32_bf16 v[116:119], v[160:163], v[148:151], v[116:119]
	s_waitcnt lgkmcnt(6)
	v_mfma_f32_16x16x32_bf16 v[80:83], v[160:163], v[152:155], v[80:83]
	s_waitcnt lgkmcnt(4)
	v_mfma_f32_16x16x32_bf16 v[84:87], v[160:163], v[156:159], v[84:87]
	v_mfma_f32_16x16x32_bf16 v[120:123], v[164:167], v[144:147], v[120:123]
	v_mfma_f32_16x16x32_bf16 v[124:127], v[164:167], v[148:151], v[124:127]
	v_mfma_f32_16x16x32_bf16 v[88:91], v[164:167], v[152:155], v[88:91]
	v_mfma_f32_16x16x32_bf16 v[92:95], v[164:167], v[156:159], v[92:95]
	v_mfma_f32_16x16x32_bf16 v[96:99], v[168:171], v[144:147], v[96:99]
	v_mfma_f32_16x16x32_bf16 v[100:103], v[168:171], v[148:151], v[100:103]
	v_mfma_f32_16x16x32_bf16 v[64:67], v[168:171], v[152:155], v[64:67]
	v_mfma_f32_16x16x32_bf16 v[68:71], v[168:171], v[156:159], v[68:71]
	v_mfma_f32_16x16x32_bf16 v[104:107], v[172:175], v[144:147], v[104:107]
	v_mfma_f32_16x16x32_bf16 v[108:111], v[172:175], v[148:151], v[108:111]
	v_mfma_f32_16x16x32_bf16 v[72:75], v[172:175], v[152:155], v[72:75]
	v_mfma_f32_16x16x32_bf16 v[76:79], v[172:175], v[156:159], v[76:79]
	s_waitcnt vmcnt(0) lgkmcnt(0)
	s_barrier
; DI void gemm_wide(const bf16_t* __restrict__ W, int ldw, const bf16_t* __restrict__ X, int ldx, int nkt,
;                   f32x16 (&acc)[4][2], bf16_t* lds) {
;     ...
;   for (int kt = 0; kt < nkt; kt += 2) {
;     __builtin_amdgcn_sched_barrier(0);
;     GW_ST2(1, 0, rw0, rw1)                         GW_KS(kt, 0)
;     GW_ST2(1, 128 * LDT, rw2, rw3)                 GW_KS(kt, 1)
;     GW_ST2(1, WT_E, rx0, rx1)                      GW_KS(kt, 2)
;     GW_ST2(1, WT_E + 128 * LDT, rx2, rx3)          GW_KS(kt, 3)
;     __builtin_amdgcn_sched_barrier(0);
;     GW_GLOAD(kt + 3 < nkt ? kt + 3 : nkt - 1)
;     __syncthreads();
;     __builtin_amdgcn_sched_barrier(0);
;     GW_ST2(0, 0, sw0, sw1)                         GW_KS(kt + 1, 0)
;     GW_ST2(0, 128 * LDT, sw2, sw3)                 GW_KS(kt + 1, 1)
;     GW_ST2(0, WT_E, sx0, sx1)                      GW_KS(kt + 1, 2)
;     GW_ST2(0, WT_E + 128 * LDT, sx2, sx3)          GW_KS(kt + 1, 3)
;     __builtin_amdgcn_sched_barrier(0);
;     GW_GLOAD_B(kt + 4 < nkt ? kt + 4 : nkt - 1)
;     __syncthreads();
;   }
; DI void phase_resid(const P& p, const bf16_t* W, const bf16_t* X, int K, bf16_t* sm, const Geo& ge, bool last) {
;     ...
;     float* stg = (float*)sm + wv * (64 * 68);
;     const int m0w = mt_ * 256 + wm * 64, n0w = nt_ * 256 + wn * 128;
; #pragma unroll
;     for (int cp = 0; cp < 2; ++cp) {
; #pragma unroll 4
;       for (int it = 0; it < 8; ++it) {
;         const int row = it * 8 + (lane >> 3), c8 = (lane & 7) * 8;
;         const u32x4 raw = *(const u32x4*)(xb + (size_t)(m0w + row) * LDK1 + n0w + cp * 64 + c8);
	v_mfma_f32_16x16x32_bf16 v[48:51], v[176:179], v[144:147], v[48:51]
	v_mfma_f32_16x16x32_bf16 v[52:55], v[176:179], v[148:151], v[52:55]
	v_mfma_f32_16x16x32_bf16 v[16:19], v[176:179], v[152:155], v[16:19]
	v_mfma_f32_16x16x32_bf16 v[20:23], v[176:179], v[156:159], v[20:23]
	v_mfma_f32_16x16x32_bf16 v[56:59], v[180:183], v[144:147], v[56:59]
	v_mfma_f32_16x16x32_bf16 v[60:63], v[180:183], v[148:151], v[60:63]
	v_mfma_f32_16x16x32_bf16 v[24:27], v[180:183], v[152:155], v[24:27]
	v_mfma_f32_16x16x32_bf16 v[28:31], v[180:183], v[156:159], v[28:31]
	v_mfma_f32_16x16x32_bf16 v[32:35], v[184:187], v[144:147], v[32:35]
	v_mfma_f32_16x16x32_bf16 v[36:39], v[184:187], v[148:151], v[36:39]
	v_mfma_f32_16x16x32_bf16 v[0:3], v[184:187], v[152:155], v[0:3]
	v_mfma_f32_16x16x32_bf16 v[4:7], v[184:187], v[156:159], v[4:7]
	v_mfma_f32_16x16x32_bf16 v[40:43], v[188:191], v[144:147], v[40:43]
	v_mfma_f32_16x16x32_bf16 v[44:47], v[188:191], v[148:151], v[44:47]
	v_mfma_f32_16x16x32_bf16 v[8:11], v[188:191], v[152:155], v[8:11]
	v_mfma_f32_16x16x32_bf16 v[12:15], v[188:191], v[156:159], v[12:15]
	s_nop 7
	v_permlane16_swap_b32_e32 v112, v116
	v_permlane16_swap_b32_e32 v113, v117
	v_permlane16_swap_b32_e32 v114, v118
	v_permlane16_swap_b32_e32 v115, v119
	v_permlane16_swap_b32_e32 v120, v124
	v_permlane16_swap_b32_e32 v121, v125
	v_permlane16_swap_b32_e32 v122, v126
	v_permlane16_swap_b32_e32 v123, v127
	v_permlane32_swap_b32_e32 v112, v116
	v_permlane32_swap_b32_e32 v113, v117
	v_permlane32_swap_b32_e32 v114, v118
	v_permlane32_swap_b32_e32 v115, v119
	v_permlane32_swap_b32_e32 v120, v124
	v_permlane32_swap_b32_e32 v121, v125
	v_permlane32_swap_b32_e32 v122, v126
	v_permlane32_swap_b32_e32 v123, v127
	v_permlane16_swap_b32_e32 v80, v84
	v_permlane16_swap_b32_e32 v81, v85
	v_permlane16_swap_b32_e32 v82, v86
	v_permlane16_swap_b32_e32 v83, v87
	v_permlane16_swap_b32_e32 v88, v92
	v_permlane16_swap_b32_e32 v89, v93
	v_permlane16_swap_b32_e32 v90, v94
	v_permlane16_swap_b32_e32 v91, v95
	v_permlane32_swap_b32_e32 v80, v84
	v_permlane32_swap_b32_e32 v81, v85
	v_permlane32_swap_b32_e32 v82, v86
	v_permlane32_swap_b32_e32 v83, v87
	v_permlane32_swap_b32_e32 v88, v92
	v_permlane32_swap_b32_e32 v89, v93
	v_permlane32_swap_b32_e32 v90, v94
	v_permlane32_swap_b32_e32 v91, v95
	v_permlane16_swap_b32_e32 v96, v100
	v_permlane16_swap_b32_e32 v97, v101
	v_permlane16_swap_b32_e32 v98, v102
	v_permlane16_swap_b32_e32 v99, v103
	v_permlane16_swap_b32_e32 v104, v108
	v_permlane16_swap_b32_e32 v105, v109
	v_permlane16_swap_b32_e32 v106, v110
	v_permlane16_swap_b32_e32 v107, v111
	v_permlane32_swap_b32_e32 v96, v100
	v_permlane32_swap_b32_e32 v97, v101
	v_permlane32_swap_b32_e32 v98, v102
	v_permlane32_swap_b32_e32 v99, v103
	v_permlane32_swap_b32_e32 v104, v108
	v_permlane32_swap_b32_e32 v105, v109
	v_permlane32_swap_b32_e32 v106, v110
	v_permlane32_swap_b32_e32 v107, v111
	v_permlane16_swap_b32_e32 v64, v68
	v_permlane16_swap_b32_e32 v65, v69
	v_permlane16_swap_b32_e32 v66, v70
	v_permlane16_swap_b32_e32 v67, v71
	v_permlane16_swap_b32_e32 v72, v76
	v_permlane16_swap_b32_e32 v73, v77
	v_permlane16_swap_b32_e32 v74, v78
	v_permlane16_swap_b32_e32 v75, v79
	v_permlane32_swap_b32_e32 v64, v68
	v_permlane32_swap_b32_e32 v65, v69
	v_permlane32_swap_b32_e32 v66, v70
	v_permlane32_swap_b32_e32 v67, v71
	v_permlane32_swap_b32_e32 v72, v76
	v_permlane32_swap_b32_e32 v73, v77
	v_permlane32_swap_b32_e32 v74, v78
	v_permlane32_swap_b32_e32 v75, v79
	v_permlane16_swap_b32_e32 v48, v52
	v_permlane16_swap_b32_e32 v49, v53
	v_permlane16_swap_b32_e32 v50, v54
	v_permlane16_swap_b32_e32 v51, v55
	v_permlane16_swap_b32_e32 v56, v60
	v_permlane16_swap_b32_e32 v57, v61
	v_permlane16_swap_b32_e32 v58, v62
	v_permlane16_swap_b32_e32 v59, v63
	v_permlane32_swap_b32_e32 v48, v52
	v_permlane32_swap_b32_e32 v49, v53
	v_permlane32_swap_b32_e32 v50, v54
	v_permlane32_swap_b32_e32 v51, v55
	v_permlane32_swap_b32_e32 v56, v60
	v_permlane32_swap_b32_e32 v57, v61
	v_permlane32_swap_b32_e32 v58, v62
	v_permlane32_swap_b32_e32 v59, v63
	v_permlane16_swap_b32_e32 v16, v20
	v_permlane16_swap_b32_e32 v17, v21
	v_permlane16_swap_b32_e32 v18, v22
	v_permlane16_swap_b32_e32 v19, v23
	v_permlane16_swap_b32_e32 v24, v28
	v_permlane16_swap_b32_e32 v25, v29
	v_permlane16_swap_b32_e32 v26, v30
	v_permlane16_swap_b32_e32 v27, v31
	v_permlane32_swap_b32_e32 v16, v20
	v_permlane32_swap_b32_e32 v17, v21
	v_permlane32_swap_b32_e32 v18, v22
	v_permlane32_swap_b32_e32 v19, v23
	v_permlane32_swap_b32_e32 v24, v28
	v_permlane32_swap_b32_e32 v25, v29
	v_permlane32_swap_b32_e32 v26, v30
	v_permlane32_swap_b32_e32 v27, v31
	v_permlane16_swap_b32_e32 v32, v36
	v_permlane16_swap_b32_e32 v33, v37
	v_permlane16_swap_b32_e32 v34, v38
	v_permlane16_swap_b32_e32 v35, v39
	v_permlane16_swap_b32_e32 v40, v44
	v_permlane16_swap_b32_e32 v41, v45
	v_permlane16_swap_b32_e32 v42, v46
	v_permlane16_swap_b32_e32 v43, v47
	v_permlane32_swap_b32_e32 v32, v36
	v_permlane32_swap_b32_e32 v33, v37
	v_permlane32_swap_b32_e32 v34, v38
	v_permlane32_swap_b32_e32 v35, v39
	v_permlane32_swap_b32_e32 v40, v44
	v_permlane32_swap_b32_e32 v41, v45
	v_permlane32_swap_b32_e32 v42, v46
	v_permlane32_swap_b32_e32 v43, v47
	v_permlane16_swap_b32_e32 v0, v4
	v_permlane16_swap_b32_e32 v1, v5
	v_permlane16_swap_b32_e32 v2, v6
	v_permlane16_swap_b32_e32 v3, v7
	v_permlane16_swap_b32_e32 v8, v12
	v_permlane16_swap_b32_e32 v9, v13
	v_permlane16_swap_b32_e32 v10, v14
	v_permlane16_swap_b32_e32 v11, v15
	v_permlane32_swap_b32_e32 v0, v4
	v_permlane32_swap_b32_e32 v1, v5
	v_permlane32_swap_b32_e32 v2, v6
	v_permlane32_swap_b32_e32 v3, v7
	v_permlane32_swap_b32_e32 v8, v12
	v_permlane32_swap_b32_e32 v9, v13
	v_permlane32_swap_b32_e32 v10, v14
	v_permlane32_swap_b32_e32 v11, v15
	s_waitcnt vmcnt(9)
	v_lshl_or_b32 v128, s8, 8, v237
	v_ashrrev_i32_e32 v129, 31, v128
	s_lshl_b32 s9, s5, 8
	s_waitcnt vmcnt(1)
	v_lshl_add_u64 v[132:133], v[128:129], 1, v[196:197]
	v_add_u32_e32 v137, s9, v240
	s_mov_b32 s5, 0
	v_mov_b32_e32 v130, v239
